# static s_setprio 1 for trailing GEMM half (toggles removed), scan waves at prio 1, scan y stores write-through
# baseline (speedup 1.0000x reference)
.LBB0_54:
	s_cmp_eq_u32 s35, 1
	s_mov_b64 s[4:5], -1
	s_cbranch_scc0 .LBB0_70
	s_cmpk_gt_i32 s2, 0x2ff
	v_readfirstlane_b32 s5, v241
	s_cbranch_scc1 .LBB0_97
	v_lshlrev_b32_e32 v0, 4, v241
	v_add_u32_e32 v1, 0x2000, v0
	v_ashrrev_i32_e32 v2, 31, v1
	v_lshrrev_b32_e32 v2, 22, v2
	v_add_u32_e32 v2, v1, v2
	v_ashrrev_i32_e32 v10, 10, v2
	v_mul_i32_i24_e32 v2, 0x400, v10
	v_sub_u32_e32 v1, v1, v2
	v_lshrrev_b32_e32 v2, 4, v1
	v_bitop3_b32 v1, v2, v1, 32 bitop3:0x6c
	v_ashrrev_i32_e32 v2, 31, v1
	s_and_b64 s[0:1], s[62:63], exec
	v_lshrrev_b32_e32 v2, 26, v2
	s_cselect_b32 s0, 0x1000000, 0
	v_add_u32_e32 v2, v1, v2
	v_lshlrev_b32_e32 v3, 3, v10
	s_add_u32 s0, s56, s0
	v_ashrrev_i32_e32 v11, 6, v2
	v_and_b32_e32 v3, -16, v3
	s_addc_u32 s3, s57, 0
	v_add_u32_e32 v3, v11, v3
	s_add_u32 s1, s0, 0x1000000
	v_and_b32_e32 v5, 3, v11
	s_mov_b32 s0, 0xfffe0
	v_lshrrev_b32_e32 v6, 2, v3
	v_lshlrev_b32_e32 v7, 1, v3
	v_and_b32_e32 v2, 0xc0, v2
	v_and_or_b32 v5, v3, s0, v5
	v_and_b32_e32 v6, 4, v6
	v_and_b32_e32 v7, 24, v7
	v_sub_u32_e32 v1, v1, v2
	v_or3_b32 v5, v5, v6, v7
	v_lshlrev_b32_e32 v6, 5, v10
	v_ashrrev_i16_sdwa v1, v240, sext(v1) dst_sel:DWORD dst_unused:UNUSED_PAD src0_sel:DWORD src1_sel:BYTE_0
	v_and_b32_e32 v6, 32, v6
	v_bfe_i32 v12, v1, 0, 16
	v_add_lshl_u32 v1, v6, v12, 1
	v_lshl_add_u32 v134, v5, 12, v1
	v_lshl_add_u32 v136, v3, 12, v1
	v_bfe_i32 v1, v241, 27, 1
	v_lshrrev_b32_e32 v1, 22, v1
	v_add_u32_e32 v1, v0, v1
	v_and_b32_e32 v1, 0xfffffc00, v1
	v_sub_u32_e32 v0, v0, v1
	v_lshrrev_b32_e32 v1, 4, v0
	v_ashrrev_i32_e32 v2, 31, v241
	v_bitop3_b32 v0, v1, v0, 32 bitop3:0x6c
	v_lshrrev_b32_e32 v2, 26, v2
	v_ashrrev_i32_e32 v1, 31, v0
	v_add_u32_e32 v2, v241, v2
	v_lshrrev_b32_e32 v1, 26, v1
	v_ashrrev_i32_e32 v18, 6, v2
	v_add_u32_e32 v1, v0, v1
	v_lshlrev_b32_e32 v2, 3, v18
	v_ashrrev_i32_e32 v13, 6, v1
	v_and_b32_e32 v2, -16, v2
	s_addc_u32 s3, s3, 0
	v_add_u32_e32 v2, v13, v2
	v_and_b32_e32 v3, 3, v13
	s_ashr_i32 s18, s2, 31
	v_and_or_b32 v3, v2, s0, v3
	s_lshr_b32 s0, s18, 29
	s_add_i32 s0, s2, s0
	s_ashr_i32 s13, s5, 6
	s_ashr_i32 s4, s0, 3
	s_and_b32 s0, s0, -8
	s_ashr_i32 s12, s5, 8
	s_lshl_b32 s15, s13, 10
	s_sub_i32 s0, s2, s0
	s_cmp_lt_i32 s0, 0
	s_movk_i32 s8, 0x61
	s_cselect_b32 s8, s8, 0x60
	s_mul_i32 s0, s0, s8
	s_add_i32 s0, s0, s4
	s_mul_hi_i32 s4, s0, 0x2aaaaaab
	s_lshr_b32 s8, s4, 31
	s_ashr_i32 s4, s4, 4
	s_add_i32 s4, s4, s8
	s_mul_i32 s8, s4, 6
	s_mulk_i32 s4, 0x60
	s_sub_i32 s0, s0, s4
	s_mul_i32 s4, s0, 43
	s_bfe_u32 s9, s4, 0x1000f
	s_bfe_u32 s4, s4, 0x80008
	s_add_i32 s4, s4, s9
	s_mul_i32 s9, s4, 6
	s_sub_i32 s0, s0, s9
	s_sext_i32_i8 s0, s0
	v_lshrrev_b32_e32 v5, 2, v2
	v_lshlrev_b32_e32 v6, 1, v2
	v_and_b32_e32 v1, 0xc0, v1
	s_add_i32 s70, s8, s0
	v_and_b32_e32 v5, 4, v5
	v_and_b32_e32 v6, 24, v6
	v_sub_u32_e32 v0, v0, v1
	s_ashr_i32 s71, s70, 31
	s_bfe_i64 s[10:11], s[4:5], 0x80000
	v_or3_b32 v3, v3, v5, v6
	v_lshlrev_b32_e32 v5, 5, v18
	v_ashrrev_i16_sdwa v0, v240, sext(v0) dst_sel:DWORD dst_unused:UNUSED_PAD src0_sel:DWORD src1_sel:BYTE_0
	s_lshl_b64 s[8:9], s[70:71], 20
	s_lshl_b64 s[10:11], s[10:11], 20
	v_and_b32_e32 v5, 32, v5
	v_bfe_i32 v19, v0, 0, 16
	s_add_u32 s78, s1, s10
	v_add_lshl_u32 v0, v5, v19, 1
	s_addc_u32 s79, s3, s11
	s_add_i32 s19, s15, 0
	v_lshl_add_u32 v138, v3, 12, v0
	s_add_i32 m0, s19, 0x10000
	v_lshl_add_u32 v140, v2, 12, v0
	global_load_lds_dwordx4 v138, s[78:79]
	s_add_i32 m0, s19, 0x12000
	s_add_u32 s10, s78, 0x80000
	global_load_lds_dwordx4 v134, s[78:79]
	s_addc_u32 s11, s79, 0
	s_add_i32 m0, s19, 0x14000
	v_mov_b32_e32 v139, v4
	global_load_lds_dwordx4 v138, s[10:11]
	s_add_i32 m0, s19, 0x16000
	s_add_u32 s76, s20, s8
	s_addc_u32 s77, s25, s9
	s_add_i32 s0, s19, 0x2000
	global_load_lds_dwordx4 v134, s[10:11]
	s_mov_b32 m0, s19
	s_add_u32 s8, s76, 0x80000
	global_load_lds_dwordx4 v140, s[76:77]
	s_mov_b32 m0, s0
	s_addc_u32 s9, s77, 0
	s_add_i32 s36, s19, 0x4000
	global_load_lds_dwordx4 v136, s[76:77]
	s_mov_b32 m0, s36
	s_add_i32 s37, s19, 0x6000
	global_load_lds_dwordx4 v140, s[8:9]
	s_mov_b32 m0, s37
	v_mov_b32_e32 v135, v4
	global_load_lds_dwordx4 v136, s[8:9]
	v_mov_b32_e32 v141, v4
	v_mov_b32_e32 v137, v4
	s_cmp_eq_u32 s12, 1
	s_mov_b32 s86, s24
	s_mov_b32 s85, s74
	v_lshl_add_u64 v[8:9], s[78:79], 0, v[138:139]
	v_lshl_add_u64 v[6:7], s[78:79], 0, v[134:135]
	v_lshl_add_u64 v[0:1], s[76:77], 0, v[140:141]
	s_cselect_b64 s[8:9], -1, 0
	s_cmp_lg_u32 s12, 1
	v_lshl_add_u64 v[2:3], s[76:77], 0, v[136:137]
	s_cbranch_scc1 .LBB0_58
	s_setprio 1
	s_barrier

.LBB0_64:
	s_add_u32 s44, s76, 0xfff80080
	s_addc_u32 s45, s77, -1
	s_add_i32 s46, 0, 0x10000
	s_cmp_eq_u32 s83, 28
	s_cselect_b32 s81, s64, s45
	s_cselect_b32 s80, s65, s44
	v_add_u32_e32 v149, s46, v146
	s_cselect_b32 s79, s67, s82
	s_cselect_b32 s78, s69, s71
	s_add_i32 s47, 0, 0x14000
	ds_read_b128 v[170:173], v149
	ds_read_b128 v[174:177], v149 offset:1024
	ds_read_b128 v[178:181], v149 offset:2048
	ds_read_b128 v[182:185], v149 offset:3072
	v_add_u32_e32 v149, s47, v146
	ds_read_b128 v[186:189], v149
	ds_read_b128 v[190:193], v149 offset:1024
	ds_read_b128 v[194:197], v149 offset:2048
	ds_read_b128 v[198:201], v149 offset:3072
	v_lshl_add_u64 v[156:157], s[76:77], 0, v[142:143]
	s_add_i32 m0, s19, 0xc000
	ds_read_b128 v[202:205], v148
	ds_read_b128 v[206:209], v148 offset:1024
	ds_read_b128 v[210:213], v148 offset:2048
	ds_read_b128 v[214:217], v148 offset:3072
	ds_read_b128 v[218:221], v148 offset:4096
	ds_read_b128 v[222:225], v148 offset:5120
	ds_read_b128 v[226:229], v148 offset:6144
	ds_read_b128 v[230:233], v148 offset:7168
	global_load_lds_dwordx4 v[156:157], off
	v_lshl_add_u64 v[156:157], s[76:77], 0, v[144:145]
	s_add_i32 m0, s19, 0xe000
	s_nop 0
	global_load_lds_dwordx4 v[156:157], off
	s_waitcnt vmcnt(8)
	s_waitcnt lgkmcnt(0)
	s_barrier
	s_waitcnt lgkmcnt(0)
	v_mfma_f32_16x16x32_bf16 v[130:133], v[170:173], v[202:205], v[130:133]
	v_mfma_f32_16x16x32_bf16 v[126:129], v[178:181], v[202:205], v[126:129]
	v_mfma_f32_16x16x32_bf16 v[122:125], v[170:173], v[210:213], v[122:125]
	v_mfma_f32_16x16x32_bf16 v[118:121], v[178:181], v[210:213], v[118:121]
	v_mfma_f32_16x16x32_bf16 v[106:109], v[170:173], v[218:221], v[106:109]
	v_mfma_f32_16x16x32_bf16 v[102:105], v[178:181], v[218:221], v[102:105]
	v_mfma_f32_16x16x32_bf16 v[90:93], v[170:173], v[226:229], v[90:93]
	v_mfma_f32_16x16x32_bf16 v[86:89], v[178:181], v[226:229], v[86:89]
	v_mfma_f32_16x16x32_bf16 v[130:133], v[174:177], v[206:209], v[130:133]
	v_mfma_f32_16x16x32_bf16 v[126:129], v[182:185], v[206:209], v[126:129]
	v_mfma_f32_16x16x32_bf16 v[122:125], v[174:177], v[214:217], v[122:125]
	v_mfma_f32_16x16x32_bf16 v[118:121], v[182:185], v[214:217], v[118:121]
	v_mfma_f32_16x16x32_bf16 v[106:109], v[174:177], v[222:225], v[106:109]
	v_mfma_f32_16x16x32_bf16 v[102:105], v[182:185], v[222:225], v[102:105]
	v_mfma_f32_16x16x32_bf16 v[90:93], v[174:177], v[230:233], v[90:93]
	v_mfma_f32_16x16x32_bf16 v[86:89], v[182:185], v[230:233], v[86:89]
	v_mfma_f32_16x16x32_bf16 v[114:117], v[186:189], v[202:205], v[114:117]
	v_mfma_f32_16x16x32_bf16 v[110:113], v[194:197], v[202:205], v[110:113]
	v_mfma_f32_16x16x32_bf16 v[98:101], v[186:189], v[210:213], v[98:101]
	v_mfma_f32_16x16x32_bf16 v[94:97], v[194:197], v[210:213], v[94:97]
	v_mfma_f32_16x16x32_bf16 v[82:85], v[186:189], v[218:221], v[82:85]
	v_mfma_f32_16x16x32_bf16 v[78:81], v[194:197], v[218:221], v[78:81]
	v_mfma_f32_16x16x32_bf16 v[74:77], v[186:189], v[226:229], v[74:77]
	v_mfma_f32_16x16x32_bf16 v[70:73], v[194:197], v[226:229], v[70:73]
	v_mfma_f32_16x16x32_bf16 v[114:117], v[190:193], v[206:209], v[114:117]
	v_mfma_f32_16x16x32_bf16 v[110:113], v[198:201], v[206:209], v[110:113]
	v_mfma_f32_16x16x32_bf16 v[98:101], v[190:193], v[214:217], v[98:101]
	v_mfma_f32_16x16x32_bf16 v[94:97], v[198:201], v[214:217], v[94:97]
	v_mfma_f32_16x16x32_bf16 v[82:85], v[190:193], v[222:225], v[82:85]
	v_mfma_f32_16x16x32_bf16 v[78:81], v[198:201], v[222:225], v[78:81]
	v_mfma_f32_16x16x32_bf16 v[74:77], v[190:193], v[230:233], v[74:77]
	v_mfma_f32_16x16x32_bf16 v[70:73], v[198:201], v[230:233], v[70:73]
	s_barrier
	s_add_i32 s44, s46, s15
	v_lshl_add_u64 v[156:157], s[78:79], 0, v[138:139]
	s_mov_b32 m0, s44
	ds_read_b128 v[202:205], v148 offset:16384
	ds_read_b128 v[206:209], v148 offset:17408
	ds_read_b128 v[210:213], v148 offset:18432
	ds_read_b128 v[214:217], v148 offset:19456
	ds_read_b128 v[218:221], v148 offset:20480
	ds_read_b128 v[222:225], v148 offset:21504
	ds_read_b128 v[226:229], v148 offset:22528
	ds_read_b128 v[230:233], v148 offset:23552
	global_load_lds_dwordx4 v[156:157], off
	s_add_i32 m0, s44, 0x2000
	s_add_u32 s44, s78, 0x80000
	v_lshl_add_u64 v[158:159], s[78:79], 0, v[134:135]
	s_addc_u32 s45, s79, 0
	s_add_i32 s46, s47, s15
	global_load_lds_dwordx4 v[158:159], off
	v_lshl_add_u64 v[160:161], s[44:45], 0, v[138:139]
	s_mov_b32 m0, s46
	v_lshl_add_u64 v[162:163], s[80:81], 0, v[136:137]
	global_load_lds_dwordx4 v[160:161], off
	v_lshl_add_u64 v[160:161], s[44:45], 0, v[134:135]
	s_add_i32 m0, s46, 0x2000
	s_nop 0
	global_load_lds_dwordx4 v[160:161], off
	v_lshl_add_u64 v[160:161], s[80:81], 0, v[140:141]
	s_mov_b32 m0, s19
	s_nop 0
	global_load_lds_dwordx4 v[160:161], off
	s_mov_b32 m0, s0
	s_nop 0
	global_load_lds_dwordx4 v[162:163], off
	s_waitcnt vmcnt(8)
	s_waitcnt lgkmcnt(0)
	s_barrier
	s_waitcnt lgkmcnt(0)
	v_mfma_f32_16x16x32_bf16 v[66:69], v[170:173], v[202:205], v[66:69]
	v_mfma_f32_16x16x32_bf16 v[62:65], v[178:181], v[202:205], v[62:65]
	v_mfma_f32_16x16x32_bf16 v[58:61], v[170:173], v[210:213], v[58:61]
	v_mfma_f32_16x16x32_bf16 v[54:57], v[178:181], v[210:213], v[54:57]
	v_mfma_f32_16x16x32_bf16 v[42:45], v[170:173], v[218:221], v[42:45]
	v_mfma_f32_16x16x32_bf16 v[38:41], v[178:181], v[218:221], v[38:41]
	v_mfma_f32_16x16x32_bf16 v[26:29], v[170:173], v[226:229], v[26:29]
	v_mfma_f32_16x16x32_bf16 v[22:25], v[178:181], v[226:229], v[22:25]
	v_mfma_f32_16x16x32_bf16 v[66:69], v[174:177], v[206:209], v[66:69]
	v_mfma_f32_16x16x32_bf16 v[62:65], v[182:185], v[206:209], v[62:65]
	v_mfma_f32_16x16x32_bf16 v[58:61], v[174:177], v[214:217], v[58:61]
	v_mfma_f32_16x16x32_bf16 v[54:57], v[182:185], v[214:217], v[54:57]
	v_mfma_f32_16x16x32_bf16 v[42:45], v[174:177], v[222:225], v[42:45]
	v_mfma_f32_16x16x32_bf16 v[38:41], v[182:185], v[222:225], v[38:41]
	v_mfma_f32_16x16x32_bf16 v[26:29], v[174:177], v[230:233], v[26:29]
	v_mfma_f32_16x16x32_bf16 v[22:25], v[182:185], v[230:233], v[22:25]
	v_mfma_f32_16x16x32_bf16 v[50:53], v[186:189], v[202:205], v[50:53]
	v_mfma_f32_16x16x32_bf16 v[46:49], v[194:197], v[202:205], v[46:49]
	v_mfma_f32_16x16x32_bf16 v[34:37], v[186:189], v[210:213], v[34:37]
	v_mfma_f32_16x16x32_bf16 v[30:33], v[194:197], v[210:213], v[30:33]
	v_mfma_f32_16x16x32_bf16 v[18:21], v[186:189], v[218:221], v[18:21]
	v_mfma_f32_16x16x32_bf16 v[10:13], v[194:197], v[218:221], v[10:13]
	v_mfma_f32_16x16x32_bf16 v[6:9], v[186:189], v[226:229], v[6:9]
	v_mfma_f32_16x16x32_bf16 v[0:3], v[194:197], v[226:229], v[0:3]
	v_mfma_f32_16x16x32_bf16 v[50:53], v[190:193], v[206:209], v[50:53]
	v_mfma_f32_16x16x32_bf16 v[46:49], v[198:201], v[206:209], v[46:49]
	v_mfma_f32_16x16x32_bf16 v[34:37], v[190:193], v[214:217], v[34:37]
	v_mfma_f32_16x16x32_bf16 v[30:33], v[198:201], v[214:217], v[30:33]
	v_mfma_f32_16x16x32_bf16 v[18:21], v[190:193], v[222:225], v[18:21]
	v_mfma_f32_16x16x32_bf16 v[10:13], v[198:201], v[222:225], v[10:13]
	v_mfma_f32_16x16x32_bf16 v[6:9], v[190:193], v[230:233], v[6:9]
	v_mfma_f32_16x16x32_bf16 v[0:3], v[198:201], v[230:233], v[0:3]
	s_barrier
	s_add_i32 s46, 0, 0x18000
	v_add_u32_e32 v149, s46, v146
	s_add_i32 s47, 0, 0x1c000
	ds_read_b128 v[170:173], v149
	ds_read_b128 v[174:177], v149 offset:1024
	ds_read_b128 v[178:181], v149 offset:2048
	ds_read_b128 v[182:185], v149 offset:3072
	v_add_u32_e32 v149, s47, v146
	ds_read_b128 v[186:189], v149
	ds_read_b128 v[190:193], v149 offset:1024
	ds_read_b128 v[194:197], v149 offset:2048
	ds_read_b128 v[198:201], v149 offset:3072
	s_add_u32 s44, s80, 0x80000
	s_addc_u32 s45, s81, 0
	s_mov_b32 m0, s36
	v_lshl_add_u64 v[234:235], s[44:45], 0, v[140:141]
	ds_read_b128 v[202:205], v148 offset:32768
	ds_read_b128 v[206:209], v148 offset:33792
	ds_read_b128 v[210:213], v148 offset:34816
	ds_read_b128 v[214:217], v148 offset:35840
	ds_read_b128 v[218:221], v148 offset:36864
	ds_read_b128 v[222:225], v148 offset:37888
	ds_read_b128 v[226:229], v148 offset:38912
	ds_read_b128 v[230:233], v148 offset:39936
	global_load_lds_dwordx4 v[234:235], off
	v_lshl_add_u64 v[234:235], s[44:45], 0, v[136:137]
	s_mov_b32 m0, s37
	s_nop 0
	global_load_lds_dwordx4 v[234:235], off
	s_waitcnt vmcnt(8)
	s_waitcnt lgkmcnt(0)
	s_barrier
	s_waitcnt lgkmcnt(0)
	v_mfma_f32_16x16x32_bf16 v[130:133], v[170:173], v[202:205], v[130:133]
	v_mfma_f32_16x16x32_bf16 v[126:129], v[178:181], v[202:205], v[126:129]
	v_mfma_f32_16x16x32_bf16 v[122:125], v[170:173], v[210:213], v[122:125]
	v_mfma_f32_16x16x32_bf16 v[118:121], v[178:181], v[210:213], v[118:121]
	v_mfma_f32_16x16x32_bf16 v[106:109], v[170:173], v[218:221], v[106:109]
	v_mfma_f32_16x16x32_bf16 v[102:105], v[178:181], v[218:221], v[102:105]
	v_mfma_f32_16x16x32_bf16 v[90:93], v[170:173], v[226:229], v[90:93]
	v_mfma_f32_16x16x32_bf16 v[86:89], v[178:181], v[226:229], v[86:89]
	v_mfma_f32_16x16x32_bf16 v[130:133], v[174:177], v[206:209], v[130:133]
	v_mfma_f32_16x16x32_bf16 v[126:129], v[182:185], v[206:209], v[126:129]
	v_mfma_f32_16x16x32_bf16 v[122:125], v[174:177], v[214:217], v[122:125]
	v_mfma_f32_16x16x32_bf16 v[118:121], v[182:185], v[214:217], v[118:121]
	v_mfma_f32_16x16x32_bf16 v[106:109], v[174:177], v[222:225], v[106:109]
	v_mfma_f32_16x16x32_bf16 v[102:105], v[182:185], v[222:225], v[102:105]
	v_mfma_f32_16x16x32_bf16 v[90:93], v[174:177], v[230:233], v[90:93]
	v_mfma_f32_16x16x32_bf16 v[86:89], v[182:185], v[230:233], v[86:89]
	v_mfma_f32_16x16x32_bf16 v[114:117], v[186:189], v[202:205], v[114:117]
	v_mfma_f32_16x16x32_bf16 v[110:113], v[194:197], v[202:205], v[110:113]
	v_mfma_f32_16x16x32_bf16 v[98:101], v[186:189], v[210:213], v[98:101]
	v_mfma_f32_16x16x32_bf16 v[94:97], v[194:197], v[210:213], v[94:97]
	v_mfma_f32_16x16x32_bf16 v[82:85], v[186:189], v[218:221], v[82:85]
	v_mfma_f32_16x16x32_bf16 v[78:81], v[194:197], v[218:221], v[78:81]
	v_mfma_f32_16x16x32_bf16 v[74:77], v[186:189], v[226:229], v[74:77]
	v_mfma_f32_16x16x32_bf16 v[70:73], v[194:197], v[226:229], v[70:73]
	v_mfma_f32_16x16x32_bf16 v[114:117], v[190:193], v[206:209], v[114:117]
	v_mfma_f32_16x16x32_bf16 v[110:113], v[198:201], v[206:209], v[110:113]
	v_mfma_f32_16x16x32_bf16 v[98:101], v[190:193], v[214:217], v[98:101]
	v_mfma_f32_16x16x32_bf16 v[94:97], v[198:201], v[214:217], v[94:97]
	v_mfma_f32_16x16x32_bf16 v[82:85], v[190:193], v[222:225], v[82:85]
	v_mfma_f32_16x16x32_bf16 v[78:81], v[198:201], v[222:225], v[78:81]
	v_mfma_f32_16x16x32_bf16 v[74:77], v[190:193], v[230:233], v[74:77]
	v_mfma_f32_16x16x32_bf16 v[70:73], v[198:201], v[230:233], v[70:73]
	s_barrier
	s_add_i32 s44, s46, s15
	v_lshl_add_u64 v[156:157], v[156:157], 0, s[30:31]
	s_mov_b32 m0, s44
	ds_read_b128 v[202:205], v148 offset:49152
	ds_read_b128 v[206:209], v148 offset:50176
	ds_read_b128 v[210:213], v148 offset:51200
	ds_read_b128 v[214:217], v148 offset:52224
	ds_read_b128 v[218:221], v148 offset:53248
	ds_read_b128 v[222:225], v148 offset:54272
	ds_read_b128 v[226:229], v148 offset:55296
	ds_read_b128 v[230:233], v148 offset:56320
	global_load_lds_dwordx4 v[156:157], off
	s_add_i32 m0, s44, 0x2000
	s_add_u32 s44, s78, 0x80080
	v_lshl_add_u64 v[156:157], v[158:159], 0, s[30:31]
	s_addc_u32 s45, s79, 0
	s_add_i32 s46, s47, s15
	global_load_lds_dwordx4 v[156:157], off
	v_lshl_add_u64 v[156:157], s[44:45], 0, v[138:139]
	s_mov_b32 m0, s46
	s_nop 0
	global_load_lds_dwordx4 v[156:157], off
	v_lshl_add_u64 v[156:157], s[44:45], 0, v[134:135]
	s_add_i32 m0, s46, 0x2000
	s_nop 0
	global_load_lds_dwordx4 v[156:157], off
	v_lshl_add_u64 v[156:157], v[160:161], 0, s[30:31]
	s_mov_b32 m0, s38
	s_nop 0
	global_load_lds_dwordx4 v[156:157], off
	v_lshl_add_u64 v[156:157], v[162:163], 0, s[30:31]
	s_mov_b32 m0, s39
	s_nop 0
	global_load_lds_dwordx4 v[156:157], off
	s_waitcnt vmcnt(8)
	s_waitcnt lgkmcnt(0)
	s_barrier
	s_waitcnt lgkmcnt(0)
	v_mfma_f32_16x16x32_bf16 v[66:69], v[170:173], v[202:205], v[66:69]
	v_mfma_f32_16x16x32_bf16 v[62:65], v[178:181], v[202:205], v[62:65]
	v_mfma_f32_16x16x32_bf16 v[58:61], v[170:173], v[210:213], v[58:61]
	v_mfma_f32_16x16x32_bf16 v[54:57], v[178:181], v[210:213], v[54:57]
	v_mfma_f32_16x16x32_bf16 v[42:45], v[170:173], v[218:221], v[42:45]
	v_mfma_f32_16x16x32_bf16 v[38:41], v[178:181], v[218:221], v[38:41]
	v_mfma_f32_16x16x32_bf16 v[26:29], v[170:173], v[226:229], v[26:29]
	v_mfma_f32_16x16x32_bf16 v[22:25], v[178:181], v[226:229], v[22:25]
	v_mfma_f32_16x16x32_bf16 v[66:69], v[174:177], v[206:209], v[66:69]
	v_mfma_f32_16x16x32_bf16 v[62:65], v[182:185], v[206:209], v[62:65]
	v_mfma_f32_16x16x32_bf16 v[58:61], v[174:177], v[214:217], v[58:61]
	v_mfma_f32_16x16x32_bf16 v[54:57], v[182:185], v[214:217], v[54:57]
	v_mfma_f32_16x16x32_bf16 v[42:45], v[174:177], v[222:225], v[42:45]
	v_mfma_f32_16x16x32_bf16 v[38:41], v[182:185], v[222:225], v[38:41]
	v_mfma_f32_16x16x32_bf16 v[26:29], v[174:177], v[230:233], v[26:29]
	v_mfma_f32_16x16x32_bf16 v[22:25], v[182:185], v[230:233], v[22:25]
	v_mfma_f32_16x16x32_bf16 v[50:53], v[186:189], v[202:205], v[50:53]
	v_mfma_f32_16x16x32_bf16 v[46:49], v[194:197], v[202:205], v[46:49]
	v_mfma_f32_16x16x32_bf16 v[34:37], v[186:189], v[210:213], v[34:37]
	v_mfma_f32_16x16x32_bf16 v[30:33], v[194:197], v[210:213], v[30:33]
	v_mfma_f32_16x16x32_bf16 v[18:21], v[186:189], v[218:221], v[18:21]
	v_mfma_f32_16x16x32_bf16 v[10:13], v[194:197], v[218:221], v[10:13]
	v_mfma_f32_16x16x32_bf16 v[6:9], v[186:189], v[226:229], v[6:9]
	v_mfma_f32_16x16x32_bf16 v[0:3], v[194:197], v[226:229], v[0:3]
	v_mfma_f32_16x16x32_bf16 v[50:53], v[190:193], v[206:209], v[50:53]
	v_mfma_f32_16x16x32_bf16 v[46:49], v[198:201], v[206:209], v[46:49]
	v_mfma_f32_16x16x32_bf16 v[34:37], v[190:193], v[214:217], v[34:37]
	v_mfma_f32_16x16x32_bf16 v[30:33], v[198:201], v[214:217], v[30:33]
	v_mfma_f32_16x16x32_bf16 v[18:21], v[190:193], v[222:225], v[18:21]
	v_mfma_f32_16x16x32_bf16 v[10:13], v[198:201], v[222:225], v[10:13]
	v_mfma_f32_16x16x32_bf16 v[6:9], v[190:193], v[230:233], v[6:9]
	v_mfma_f32_16x16x32_bf16 v[0:3], v[198:201], v[230:233], v[0:3]
	s_barrier
	s_add_i32 s83, s83, 2
	s_add_u32 s76, s76, 0x100
	s_addc_u32 s77, s77, 0
	s_add_u32 s71, s71, 0x100
	s_addc_u32 s82, s82, 0
	s_cmp_gt_u32 s83, 29
	s_cbranch_scc0 .LBB0_64
	s_and_b64 vcc, exec, s[12:13]
	s_cbranch_vccz .LBB0_67
	s_barrier

.LBB0_79:
	s_cmp_gt_i32 s35, 6
	s_cbranch_scc0 .LBB0_101
	s_cmp_eq_u32 s35, 7
	s_mov_b64 s[4:5], -1
	s_cbranch_scc0 .LBB0_100
	s_cmpk_gt_i32 s2, 0x83f
	v_readfirstlane_b32 s5, v241
	s_cbranch_scc1 .LBB0_99
	v_lshlrev_b32_e32 v0, 4, v241
	v_add_u32_e32 v1, 0x2000, v0
	v_ashrrev_i32_e32 v2, 31, v1
	v_lshrrev_b32_e32 v2, 22, v2
	v_add_u32_e32 v2, v1, v2
	v_ashrrev_i32_e32 v10, 10, v2
	v_mul_i32_i24_e32 v2, 0x400, v10
	v_sub_u32_e32 v1, v1, v2
	v_lshrrev_b32_e32 v2, 4, v1
	v_bitop3_b32 v1, v2, v1, 32 bitop3:0x6c
	v_ashrrev_i32_e32 v2, 31, v1
	s_and_b64 s[0:1], s[62:63], exec
	v_lshrrev_b32_e32 v2, 26, v2
	s_cselect_b32 s0, 0x2c00000, 0
	v_add_u32_e32 v2, v1, v2
	v_lshlrev_b32_e32 v3, 3, v10
	s_add_u32 s0, s56, s0
	v_ashrrev_i32_e32 v11, 6, v2
	v_and_b32_e32 v3, -16, v3
	s_addc_u32 s1, s57, 0
	v_add_u32_e32 v3, v11, v3
	s_add_u32 s15, s0, 0x4400000
	v_and_b32_e32 v5, 3, v11
	s_mov_b32 s0, 0xfffe0
	v_lshrrev_b32_e32 v6, 2, v3
	v_lshlrev_b32_e32 v7, 1, v3
	v_and_b32_e32 v2, 0xc0, v2
	v_and_or_b32 v5, v3, s0, v5
	v_and_b32_e32 v6, 4, v6
	v_and_b32_e32 v7, 24, v7
	v_sub_u32_e32 v1, v1, v2
	v_or3_b32 v5, v5, v6, v7
	v_lshlrev_b32_e32 v6, 5, v10
	v_ashrrev_i16_sdwa v1, v240, sext(v1) dst_sel:DWORD dst_unused:UNUSED_PAD src0_sel:DWORD src1_sel:BYTE_0
	v_and_b32_e32 v6, 32, v6
	v_bfe_i32 v12, v1, 0, 16
	v_add_lshl_u32 v1, v6, v12, 1
	v_lshl_add_u32 v134, v5, 12, v1
	v_lshl_add_u32 v136, v3, 12, v1
	v_bfe_i32 v1, v241, 27, 1
	v_lshrrev_b32_e32 v1, 22, v1
	v_add_u32_e32 v1, v0, v1
	v_and_b32_e32 v1, 0xfffffc00, v1
	v_sub_u32_e32 v0, v0, v1
	v_lshrrev_b32_e32 v1, 4, v0
	v_ashrrev_i32_e32 v2, 31, v241
	v_bitop3_b32 v0, v1, v0, 32 bitop3:0x6c
	v_lshrrev_b32_e32 v2, 26, v2
	v_ashrrev_i32_e32 v1, 31, v0
	v_add_u32_e32 v2, v241, v2
	v_lshrrev_b32_e32 v1, 26, v1
	v_ashrrev_i32_e32 v18, 6, v2
	v_add_u32_e32 v1, v0, v1
	v_lshlrev_b32_e32 v2, 3, v18
	v_ashrrev_i32_e32 v13, 6, v1
	v_and_b32_e32 v2, -16, v2
	s_addc_u32 s18, s1, 0
	v_add_u32_e32 v2, v13, v2
	v_and_b32_e32 v3, 3, v13
	s_ashr_i32 s1, s2, 31
	v_and_or_b32 v3, v2, s0, v3
	s_lshr_b32 s0, s1, 29
	s_add_i32 s0, s2, s0
	s_ashr_i32 s39, s5, 6
	s_ashr_i32 s3, s0, 3
	s_and_b32 s0, s0, -8
	s_ashr_i32 s40, s5, 8
	s_lshl_b32 s19, s39, 10
	s_sub_i32 s0, s2, s0
	s_cmp_lt_i32 s0, 0
	s_movk_i32 s4, 0x109
	s_cselect_b32 s4, s4, 0x108
	s_mul_i32 s0, s0, s4
	s_add_i32 s0, s0, s3
	s_mul_hi_i32 s3, s0, 0x3e0f83e1
	s_lshr_b32 s4, s3, 31
	s_ashr_i32 s3, s3, 6
	s_add_i32 s3, s3, s4
	s_mul_i32 s10, s3, 6
	s_mulk_i32 s3, 0x108
	s_sub_i32 s0, s0, s3
	s_mul_i32 s3, s0, 0x2aab
	s_lshr_b32 s4, s3, 31
	s_lshr_b32 s3, s3, 16
	s_add_i32 s4, s3, s4
	s_mul_i32 s3, s4, 6
	s_sub_i32 s0, s0, s3
	s_sext_i32_i16 s0, s0
	v_lshrrev_b32_e32 v5, 2, v2
	v_lshlrev_b32_e32 v6, 1, v2
	v_and_b32_e32 v1, 0xc0, v1
	s_add_i32 s76, s10, s0
	v_and_b32_e32 v5, 4, v5
	v_and_b32_e32 v6, 24, v6
	v_sub_u32_e32 v0, v0, v1
	s_ashr_i32 s77, s76, 31
	s_bfe_i64 s[12:13], s[4:5], 0x100000
	v_or3_b32 v3, v3, v5, v6
	v_lshlrev_b32_e32 v5, 5, v18
	v_ashrrev_i16_sdwa v0, v240, sext(v0) dst_sel:DWORD dst_unused:UNUSED_PAD src0_sel:DWORD src1_sel:BYTE_0
	s_lshl_b64 s[10:11], s[76:77], 20
	s_lshl_b64 s[12:13], s[12:13], 20
	v_and_b32_e32 v5, 32, v5
	v_bfe_i32 v19, v0, 0, 16
	s_add_u32 s80, s15, s12
	v_add_lshl_u32 v0, v5, v19, 1
	s_addc_u32 s81, s18, s13
	s_add_i32 s3, s19, 0
	v_lshl_add_u32 v138, v3, 12, v0
	s_add_i32 m0, s3, 0x10000
	v_lshl_add_u32 v140, v2, 12, v0
	global_load_lds_dwordx4 v138, s[80:81]
	s_add_i32 m0, s3, 0x12000
	s_add_u32 s12, s80, 0x80000
	global_load_lds_dwordx4 v134, s[80:81]
	s_addc_u32 s13, s81, 0
	s_add_i32 m0, s3, 0x14000
	v_mov_b32_e32 v139, v4
	global_load_lds_dwordx4 v138, s[12:13]
	s_add_i32 m0, s3, 0x16000
	s_add_u32 s78, s20, s10
	s_addc_u32 s79, s25, s11
	s_add_i32 s36, s3, 0x2000
	global_load_lds_dwordx4 v134, s[12:13]
	s_mov_b32 m0, s3
	s_add_u32 s10, s78, 0x80000
	global_load_lds_dwordx4 v140, s[78:79]
	s_mov_b32 m0, s36
	s_addc_u32 s11, s79, 0
	s_add_i32 s37, s3, 0x4000
	global_load_lds_dwordx4 v136, s[78:79]
	s_mov_b32 m0, s37
	s_add_i32 s38, s3, 0x6000
	global_load_lds_dwordx4 v140, s[10:11]
	s_mov_b32 m0, s38
	v_mov_b32_e32 v135, v4
	global_load_lds_dwordx4 v136, s[10:11]
	v_mov_b32_e32 v141, v4
	v_mov_b32_e32 v137, v4
	s_cmp_eq_u32 s40, 1
	s_mov_b32 s87, s74
	v_lshl_add_u64 v[8:9], s[80:81], 0, v[138:139]
	v_lshl_add_u64 v[6:7], s[80:81], 0, v[134:135]
	v_lshl_add_u64 v[0:1], s[78:79], 0, v[140:141]
	s_cselect_b64 s[10:11], -1, 0
	s_cmp_lg_u32 s40, 1
	v_lshl_add_u64 v[2:3], s[78:79], 0, v[136:137]
	s_cbranch_scc1 .LBB0_84
	s_setprio 1
	s_barrier

.LBB0_90:
	s_add_u32 s44, s78, 0xfff80080
	s_addc_u32 s45, s79, -1
	s_add_i32 s46, 0, 0x10000
	s_cmp_eq_u32 s86, 28
	s_cselect_b32 s83, s64, s45
	s_cselect_b32 s82, s65, s44
	v_add_u32_e32 v149, s46, v146
	s_cselect_b32 s81, s69, s85
	s_cselect_b32 s80, s71, s77
	s_add_i32 s47, 0, 0x14000
	ds_read_b128 v[156:159], v149
	ds_read_b128 v[160:163], v149 offset:1024
	ds_read_b128 v[170:173], v149 offset:2048
	ds_read_b128 v[174:177], v149 offset:3072
	v_add_u32_e32 v149, s47, v146
	ds_read_b128 v[178:181], v149
	ds_read_b128 v[182:185], v149 offset:1024
	ds_read_b128 v[186:189], v149 offset:2048
	ds_read_b128 v[190:193], v149 offset:3072
	v_lshl_add_u64 v[226:227], s[78:79], 0, v[142:143]
	s_add_i32 m0, s3, 0xc000
	ds_read_b128 v[194:197], v148
	ds_read_b128 v[198:201], v148 offset:1024
	ds_read_b128 v[202:205], v148 offset:2048
	ds_read_b128 v[206:209], v148 offset:3072
	ds_read_b128 v[210:213], v148 offset:4096
	ds_read_b128 v[214:217], v148 offset:5120
	ds_read_b128 v[218:221], v148 offset:6144
	ds_read_b128 v[222:225], v148 offset:7168
	global_load_lds_dwordx4 v[226:227], off
	v_lshl_add_u64 v[226:227], s[78:79], 0, v[144:145]
	s_add_i32 m0, s3, 0xe000
	s_nop 0
	global_load_lds_dwordx4 v[226:227], off
	s_waitcnt vmcnt(8)
	s_waitcnt lgkmcnt(0)
	s_barrier
	s_waitcnt lgkmcnt(0)
	v_mfma_f32_16x16x32_bf16 v[130:133], v[156:159], v[194:197], v[130:133]
	v_mfma_f32_16x16x32_bf16 v[122:125], v[170:173], v[194:197], v[122:125]
	v_mfma_f32_16x16x32_bf16 v[114:117], v[156:159], v[202:205], v[114:117]
	v_mfma_f32_16x16x32_bf16 v[106:109], v[170:173], v[202:205], v[106:109]
	v_mfma_f32_16x16x32_bf16 v[98:101], v[156:159], v[210:213], v[98:101]
	v_mfma_f32_16x16x32_bf16 v[90:93], v[170:173], v[210:213], v[90:93]
	v_mfma_f32_16x16x32_bf16 v[82:85], v[156:159], v[218:221], v[82:85]
	v_mfma_f32_16x16x32_bf16 v[74:77], v[170:173], v[218:221], v[74:77]
	v_mfma_f32_16x16x32_bf16 v[130:133], v[160:163], v[198:201], v[130:133]
	v_mfma_f32_16x16x32_bf16 v[122:125], v[174:177], v[198:201], v[122:125]
	v_mfma_f32_16x16x32_bf16 v[114:117], v[160:163], v[206:209], v[114:117]
	v_mfma_f32_16x16x32_bf16 v[106:109], v[174:177], v[206:209], v[106:109]
	v_mfma_f32_16x16x32_bf16 v[98:101], v[160:163], v[214:217], v[98:101]
	v_mfma_f32_16x16x32_bf16 v[90:93], v[174:177], v[214:217], v[90:93]
	v_mfma_f32_16x16x32_bf16 v[82:85], v[160:163], v[222:225], v[82:85]
	v_mfma_f32_16x16x32_bf16 v[74:77], v[174:177], v[222:225], v[74:77]
	v_mfma_f32_16x16x32_bf16 v[126:129], v[178:181], v[194:197], v[126:129]
	v_mfma_f32_16x16x32_bf16 v[118:121], v[186:189], v[194:197], v[118:121]
	v_mfma_f32_16x16x32_bf16 v[110:113], v[178:181], v[202:205], v[110:113]
	v_mfma_f32_16x16x32_bf16 v[102:105], v[186:189], v[202:205], v[102:105]
	v_mfma_f32_16x16x32_bf16 v[94:97], v[178:181], v[210:213], v[94:97]
	v_mfma_f32_16x16x32_bf16 v[86:89], v[186:189], v[210:213], v[86:89]
	v_mfma_f32_16x16x32_bf16 v[78:81], v[178:181], v[218:221], v[78:81]
	v_mfma_f32_16x16x32_bf16 v[70:73], v[186:189], v[218:221], v[70:73]
	v_mfma_f32_16x16x32_bf16 v[126:129], v[182:185], v[198:201], v[126:129]
	v_mfma_f32_16x16x32_bf16 v[118:121], v[190:193], v[198:201], v[118:121]
	v_mfma_f32_16x16x32_bf16 v[110:113], v[182:185], v[206:209], v[110:113]
	v_mfma_f32_16x16x32_bf16 v[102:105], v[190:193], v[206:209], v[102:105]
	v_mfma_f32_16x16x32_bf16 v[94:97], v[182:185], v[214:217], v[94:97]
	v_mfma_f32_16x16x32_bf16 v[86:89], v[190:193], v[214:217], v[86:89]
	v_mfma_f32_16x16x32_bf16 v[78:81], v[182:185], v[222:225], v[78:81]
	v_mfma_f32_16x16x32_bf16 v[70:73], v[190:193], v[222:225], v[70:73]
	s_barrier
	s_add_i32 s44, s46, s19
	v_lshl_add_u64 v[226:227], s[80:81], 0, v[138:139]
	s_mov_b32 m0, s44
	ds_read_b128 v[194:197], v148 offset:16384
	ds_read_b128 v[198:201], v148 offset:17408
	ds_read_b128 v[202:205], v148 offset:18432
	ds_read_b128 v[206:209], v148 offset:19456
	ds_read_b128 v[210:213], v148 offset:20480
	ds_read_b128 v[214:217], v148 offset:21504
	ds_read_b128 v[218:221], v148 offset:22528
	ds_read_b128 v[222:225], v148 offset:23552
	global_load_lds_dwordx4 v[226:227], off
	s_add_i32 m0, s44, 0x2000
	s_add_u32 s44, s80, 0x80000
	v_lshl_add_u64 v[228:229], s[80:81], 0, v[134:135]
	s_addc_u32 s45, s81, 0
	s_add_i32 s46, s47, s19
	global_load_lds_dwordx4 v[228:229], off
	v_lshl_add_u64 v[230:231], s[44:45], 0, v[138:139]
	s_mov_b32 m0, s46
	v_lshl_add_u64 v[232:233], s[82:83], 0, v[136:137]
	global_load_lds_dwordx4 v[230:231], off
	v_lshl_add_u64 v[230:231], s[44:45], 0, v[134:135]
	s_add_i32 m0, s46, 0x2000
	s_nop 0
	global_load_lds_dwordx4 v[230:231], off
	v_lshl_add_u64 v[230:231], s[82:83], 0, v[140:141]
	s_mov_b32 m0, s3
	s_nop 0
	global_load_lds_dwordx4 v[230:231], off
	s_mov_b32 m0, s36
	s_nop 0
	global_load_lds_dwordx4 v[232:233], off
	s_waitcnt vmcnt(8)
	s_waitcnt lgkmcnt(0)
	s_barrier
	s_waitcnt lgkmcnt(0)
	v_mfma_f32_16x16x32_bf16 v[66:69], v[156:159], v[194:197], v[66:69]
	v_mfma_f32_16x16x32_bf16 v[58:61], v[170:173], v[194:197], v[58:61]
	v_mfma_f32_16x16x32_bf16 v[50:53], v[156:159], v[202:205], v[50:53]
	v_mfma_f32_16x16x32_bf16 v[42:45], v[170:173], v[202:205], v[42:45]
	v_mfma_f32_16x16x32_bf16 v[34:37], v[156:159], v[210:213], v[34:37]
	v_mfma_f32_16x16x32_bf16 v[26:29], v[170:173], v[210:213], v[26:29]
	v_mfma_f32_16x16x32_bf16 v[18:21], v[156:159], v[218:221], v[18:21]
	v_mfma_f32_16x16x32_bf16 v[6:9], v[170:173], v[218:221], v[6:9]
	v_mfma_f32_16x16x32_bf16 v[66:69], v[160:163], v[198:201], v[66:69]
	v_mfma_f32_16x16x32_bf16 v[58:61], v[174:177], v[198:201], v[58:61]
	v_mfma_f32_16x16x32_bf16 v[50:53], v[160:163], v[206:209], v[50:53]
	v_mfma_f32_16x16x32_bf16 v[42:45], v[174:177], v[206:209], v[42:45]
	v_mfma_f32_16x16x32_bf16 v[34:37], v[160:163], v[214:217], v[34:37]
	v_mfma_f32_16x16x32_bf16 v[26:29], v[174:177], v[214:217], v[26:29]
	v_mfma_f32_16x16x32_bf16 v[18:21], v[160:163], v[222:225], v[18:21]
	v_mfma_f32_16x16x32_bf16 v[6:9], v[174:177], v[222:225], v[6:9]
	v_mfma_f32_16x16x32_bf16 v[62:65], v[178:181], v[194:197], v[62:65]
	v_mfma_f32_16x16x32_bf16 v[54:57], v[186:189], v[194:197], v[54:57]
	v_mfma_f32_16x16x32_bf16 v[46:49], v[178:181], v[202:205], v[46:49]
	v_mfma_f32_16x16x32_bf16 v[38:41], v[186:189], v[202:205], v[38:41]
	v_mfma_f32_16x16x32_bf16 v[30:33], v[178:181], v[210:213], v[30:33]
	v_mfma_f32_16x16x32_bf16 v[22:25], v[186:189], v[210:213], v[22:25]
	v_mfma_f32_16x16x32_bf16 v[10:13], v[178:181], v[218:221], v[10:13]
	v_mfma_f32_16x16x32_bf16 v[0:3], v[186:189], v[218:221], v[0:3]
	v_mfma_f32_16x16x32_bf16 v[62:65], v[182:185], v[198:201], v[62:65]
	v_mfma_f32_16x16x32_bf16 v[54:57], v[190:193], v[198:201], v[54:57]
	v_mfma_f32_16x16x32_bf16 v[46:49], v[182:185], v[206:209], v[46:49]
	v_mfma_f32_16x16x32_bf16 v[38:41], v[190:193], v[206:209], v[38:41]
	v_mfma_f32_16x16x32_bf16 v[30:33], v[182:185], v[214:217], v[30:33]
	v_mfma_f32_16x16x32_bf16 v[22:25], v[190:193], v[214:217], v[22:25]
	v_mfma_f32_16x16x32_bf16 v[10:13], v[182:185], v[222:225], v[10:13]
	v_mfma_f32_16x16x32_bf16 v[0:3], v[190:193], v[222:225], v[0:3]
	s_barrier
	s_add_i32 s46, 0, 0x18000
	v_add_u32_e32 v149, s46, v146
	s_add_i32 s47, 0, 0x1c000
	ds_read_b128 v[156:159], v149
	ds_read_b128 v[160:163], v149 offset:1024
	ds_read_b128 v[170:173], v149 offset:2048
	ds_read_b128 v[174:177], v149 offset:3072
	v_add_u32_e32 v149, s47, v146
	ds_read_b128 v[178:181], v149
	ds_read_b128 v[182:185], v149 offset:1024
	ds_read_b128 v[186:189], v149 offset:2048
	ds_read_b128 v[190:193], v149 offset:3072
	s_add_u32 s44, s82, 0x80000
	s_addc_u32 s45, s83, 0
	s_mov_b32 m0, s37
	v_lshl_add_u64 v[234:235], s[44:45], 0, v[140:141]
	ds_read_b128 v[194:197], v148 offset:32768
	ds_read_b128 v[198:201], v148 offset:33792
	ds_read_b128 v[202:205], v148 offset:34816
	ds_read_b128 v[206:209], v148 offset:35840
	ds_read_b128 v[210:213], v148 offset:36864
	ds_read_b128 v[214:217], v148 offset:37888
	ds_read_b128 v[218:221], v148 offset:38912
	ds_read_b128 v[222:225], v148 offset:39936
	global_load_lds_dwordx4 v[234:235], off
	v_lshl_add_u64 v[234:235], s[44:45], 0, v[136:137]
	s_mov_b32 m0, s38
	s_nop 0
	global_load_lds_dwordx4 v[234:235], off
	s_waitcnt vmcnt(8)
	s_waitcnt lgkmcnt(0)
	s_barrier
	s_waitcnt lgkmcnt(0)
	v_mfma_f32_16x16x32_bf16 v[130:133], v[156:159], v[194:197], v[130:133]
	v_mfma_f32_16x16x32_bf16 v[122:125], v[170:173], v[194:197], v[122:125]
	v_mfma_f32_16x16x32_bf16 v[114:117], v[156:159], v[202:205], v[114:117]
	v_mfma_f32_16x16x32_bf16 v[106:109], v[170:173], v[202:205], v[106:109]
	v_mfma_f32_16x16x32_bf16 v[98:101], v[156:159], v[210:213], v[98:101]
	v_mfma_f32_16x16x32_bf16 v[90:93], v[170:173], v[210:213], v[90:93]
	v_mfma_f32_16x16x32_bf16 v[82:85], v[156:159], v[218:221], v[82:85]
	v_mfma_f32_16x16x32_bf16 v[74:77], v[170:173], v[218:221], v[74:77]
	v_mfma_f32_16x16x32_bf16 v[130:133], v[160:163], v[198:201], v[130:133]
	v_mfma_f32_16x16x32_bf16 v[122:125], v[174:177], v[198:201], v[122:125]
	v_mfma_f32_16x16x32_bf16 v[114:117], v[160:163], v[206:209], v[114:117]
	v_mfma_f32_16x16x32_bf16 v[106:109], v[174:177], v[206:209], v[106:109]
	v_mfma_f32_16x16x32_bf16 v[98:101], v[160:163], v[214:217], v[98:101]
	v_mfma_f32_16x16x32_bf16 v[90:93], v[174:177], v[214:217], v[90:93]
	v_mfma_f32_16x16x32_bf16 v[82:85], v[160:163], v[222:225], v[82:85]
	v_mfma_f32_16x16x32_bf16 v[74:77], v[174:177], v[222:225], v[74:77]
	v_mfma_f32_16x16x32_bf16 v[126:129], v[178:181], v[194:197], v[126:129]
	v_mfma_f32_16x16x32_bf16 v[118:121], v[186:189], v[194:197], v[118:121]
	v_mfma_f32_16x16x32_bf16 v[110:113], v[178:181], v[202:205], v[110:113]
	v_mfma_f32_16x16x32_bf16 v[102:105], v[186:189], v[202:205], v[102:105]
	v_mfma_f32_16x16x32_bf16 v[94:97], v[178:181], v[210:213], v[94:97]
	v_mfma_f32_16x16x32_bf16 v[86:89], v[186:189], v[210:213], v[86:89]
	v_mfma_f32_16x16x32_bf16 v[78:81], v[178:181], v[218:221], v[78:81]
	v_mfma_f32_16x16x32_bf16 v[70:73], v[186:189], v[218:221], v[70:73]
	v_mfma_f32_16x16x32_bf16 v[126:129], v[182:185], v[198:201], v[126:129]
	v_mfma_f32_16x16x32_bf16 v[118:121], v[190:193], v[198:201], v[118:121]
	v_mfma_f32_16x16x32_bf16 v[110:113], v[182:185], v[206:209], v[110:113]
	v_mfma_f32_16x16x32_bf16 v[102:105], v[190:193], v[206:209], v[102:105]
	v_mfma_f32_16x16x32_bf16 v[94:97], v[182:185], v[214:217], v[94:97]
	v_mfma_f32_16x16x32_bf16 v[86:89], v[190:193], v[214:217], v[86:89]
	v_mfma_f32_16x16x32_bf16 v[78:81], v[182:185], v[222:225], v[78:81]
	v_mfma_f32_16x16x32_bf16 v[70:73], v[190:193], v[222:225], v[70:73]
	s_barrier
	s_add_i32 s44, s46, s19
	v_lshl_add_u64 v[226:227], v[226:227], 0, s[30:31]
	s_mov_b32 m0, s44
	ds_read_b128 v[194:197], v148 offset:49152
	ds_read_b128 v[198:201], v148 offset:50176
	ds_read_b128 v[202:205], v148 offset:51200
	ds_read_b128 v[206:209], v148 offset:52224
	ds_read_b128 v[210:213], v148 offset:53248
	ds_read_b128 v[214:217], v148 offset:54272
	ds_read_b128 v[218:221], v148 offset:55296
	ds_read_b128 v[222:225], v148 offset:56320
	global_load_lds_dwordx4 v[226:227], off
	s_add_i32 m0, s44, 0x2000
	s_add_u32 s44, s80, 0x80080
	v_lshl_add_u64 v[226:227], v[228:229], 0, s[30:31]
	s_addc_u32 s45, s81, 0
	s_add_i32 s46, s47, s19
	global_load_lds_dwordx4 v[226:227], off
	v_lshl_add_u64 v[226:227], s[44:45], 0, v[138:139]
	s_mov_b32 m0, s46
	s_nop 0
	global_load_lds_dwordx4 v[226:227], off
	v_lshl_add_u64 v[226:227], s[44:45], 0, v[134:135]
	s_add_i32 m0, s46, 0x2000
	s_nop 0
	global_load_lds_dwordx4 v[226:227], off
	v_lshl_add_u64 v[226:227], v[230:231], 0, s[30:31]
	s_mov_b32 m0, s39
	s_nop 0
	global_load_lds_dwordx4 v[226:227], off
	v_lshl_add_u64 v[226:227], v[232:233], 0, s[30:31]
	s_mov_b32 m0, s40
	s_nop 0
	global_load_lds_dwordx4 v[226:227], off
	s_waitcnt vmcnt(8)
	s_waitcnt lgkmcnt(0)
	s_barrier
	s_waitcnt lgkmcnt(0)
	v_mfma_f32_16x16x32_bf16 v[66:69], v[156:159], v[194:197], v[66:69]
	v_mfma_f32_16x16x32_bf16 v[58:61], v[170:173], v[194:197], v[58:61]
	v_mfma_f32_16x16x32_bf16 v[50:53], v[156:159], v[202:205], v[50:53]
	v_mfma_f32_16x16x32_bf16 v[42:45], v[170:173], v[202:205], v[42:45]
	v_mfma_f32_16x16x32_bf16 v[34:37], v[156:159], v[210:213], v[34:37]
	v_mfma_f32_16x16x32_bf16 v[26:29], v[170:173], v[210:213], v[26:29]
	v_mfma_f32_16x16x32_bf16 v[18:21], v[156:159], v[218:221], v[18:21]
	v_mfma_f32_16x16x32_bf16 v[6:9], v[170:173], v[218:221], v[6:9]
	v_mfma_f32_16x16x32_bf16 v[66:69], v[160:163], v[198:201], v[66:69]
	v_mfma_f32_16x16x32_bf16 v[58:61], v[174:177], v[198:201], v[58:61]
	v_mfma_f32_16x16x32_bf16 v[50:53], v[160:163], v[206:209], v[50:53]
	v_mfma_f32_16x16x32_bf16 v[42:45], v[174:177], v[206:209], v[42:45]
	v_mfma_f32_16x16x32_bf16 v[34:37], v[160:163], v[214:217], v[34:37]
	v_mfma_f32_16x16x32_bf16 v[26:29], v[174:177], v[214:217], v[26:29]
	v_mfma_f32_16x16x32_bf16 v[18:21], v[160:163], v[222:225], v[18:21]
	v_mfma_f32_16x16x32_bf16 v[6:9], v[174:177], v[222:225], v[6:9]
	v_mfma_f32_16x16x32_bf16 v[62:65], v[178:181], v[194:197], v[62:65]
	v_mfma_f32_16x16x32_bf16 v[54:57], v[186:189], v[194:197], v[54:57]
	v_mfma_f32_16x16x32_bf16 v[46:49], v[178:181], v[202:205], v[46:49]
	v_mfma_f32_16x16x32_bf16 v[38:41], v[186:189], v[202:205], v[38:41]
	v_mfma_f32_16x16x32_bf16 v[30:33], v[178:181], v[210:213], v[30:33]
	v_mfma_f32_16x16x32_bf16 v[22:25], v[186:189], v[210:213], v[22:25]
	v_mfma_f32_16x16x32_bf16 v[10:13], v[178:181], v[218:221], v[10:13]
	v_mfma_f32_16x16x32_bf16 v[0:3], v[186:189], v[218:221], v[0:3]
	v_mfma_f32_16x16x32_bf16 v[62:65], v[182:185], v[198:201], v[62:65]
	v_mfma_f32_16x16x32_bf16 v[54:57], v[190:193], v[198:201], v[54:57]
	v_mfma_f32_16x16x32_bf16 v[46:49], v[182:185], v[206:209], v[46:49]
	v_mfma_f32_16x16x32_bf16 v[38:41], v[190:193], v[206:209], v[38:41]
	v_mfma_f32_16x16x32_bf16 v[30:33], v[182:185], v[214:217], v[30:33]
	v_mfma_f32_16x16x32_bf16 v[22:25], v[190:193], v[214:217], v[22:25]
	v_mfma_f32_16x16x32_bf16 v[10:13], v[182:185], v[222:225], v[10:13]
	v_mfma_f32_16x16x32_bf16 v[0:3], v[190:193], v[222:225], v[0:3]
	s_barrier
	s_add_i32 s86, s86, 2
	s_add_u32 s78, s78, 0x100
	s_addc_u32 s79, s79, 0
	s_add_u32 s77, s77, 0x100
	s_addc_u32 s85, s85, 0
	s_cmp_gt_u32 s86, 29
	s_cbranch_scc0 .LBB0_90
	s_and_b64 vcc, exec, s[66:67]
	s_cbranch_vccz .LBB0_93
	s_barrier

.LBB0_96:
	s_waitcnt vmcnt(0)
	v_readlane_b32 s72, v247, 5
	v_readlane_b32 s68, v247, 7
	v_readlane_b32 s79, v247, 4
	v_readlane_b32 s73, v247, 6
	v_readlane_b32 s69, v247, 8
	s_mov_b32 s46, 0xc800000
	s_mov_b64 s[70:71], 0x20000000
	s_mov_b32 s74, s85
	s_mov_b32 s24, s86
	s_setprio 0
	s_barrier

.LBB0_98:
	s_waitcnt vmcnt(0)
	v_readlane_b32 s72, v247, 5
	v_readlane_b32 s68, v247, 7
	v_readlane_b32 s79, v247, 4
	v_readlane_b32 s73, v247, 6
	v_readlane_b32 s69, v247, 8
	s_mov_b64 s[70:71], 0x20000000
	s_mov_b32 s74, s87
	s_setprio 0
	s_barrier
	s_cmpk_lt_i32 s2, 0x40
	s_cbranch_scc1 .LBB0_99
	s_sub_i32 s4, s2, 0x40
	s_lshl_b32 s4, s4, 3
	s_add_i32 s4, s4, s43
	s_movk_i32 s1, 0x600
	s_and_b64 s[10:11], s[62:63], exec
	s_mov_b32 s25, 17920
	s_mov_b32 s39, 32208
	s_cbranch_scc0 .Lconv_entry
	s_mov_b32 s25, 41472
	s_mov_b32 s39, 47104
	s_branch .Lconv_entry

.LBB0_101:
	s_and_b64 vcc, exec, s[10:11]
	s_cbranch_vccz .LBB0_141
	s_cmp_eq_u32 s35, 4
	s_mov_b64 s[4:5], -1
	s_cbranch_scc0 .LBB0_141
	s_add_u32 s65, s56, 0x3000000
	s_addc_u32 s66, s57, 0
	s_cmpk_gt_i32 s2, 0xbf
	v_readfirstlane_b32 s1, v241
	s_cbranch_scc1 .LBB0_119
	v_lshlrev_b32_e32 v0, 4, v241
	v_add_u32_e32 v1, 0x2000, v0
	v_ashrrev_i32_e32 v2, 31, v1
	v_lshrrev_b32_e32 v2, 22, v2
	v_add_u32_e32 v2, v1, v2
	v_ashrrev_i32_e32 v10, 10, v2
	v_mul_i32_i24_e32 v2, 0x400, v10
	v_sub_u32_e32 v1, v1, v2
	v_lshrrev_b32_e32 v2, 4, v1
	v_bitop3_b32 v1, v2, v1, 32 bitop3:0x6c
	v_ashrrev_i32_e32 v2, 31, v1
	v_lshrrev_b32_e32 v2, 26, v2
	v_add_u32_e32 v2, v1, v2
	v_lshlrev_b32_e32 v3, 3, v10
	s_and_b64 s[4:5], s[62:63], exec
	v_ashrrev_i32_e32 v11, 6, v2
	v_and_b32_e32 v3, -16, v3
	s_cselect_b32 s0, 0x200000, 0
	v_add_u32_e32 v3, v11, v3
	s_add_u32 s20, s65, s0
	v_and_b32_e32 v5, 3, v11
	s_mov_b32 s0, 0x1fffe0
	v_lshrrev_b32_e32 v6, 2, v3
	v_lshlrev_b32_e32 v7, 1, v3
	v_and_b32_e32 v2, 0xc0, v2
	v_and_or_b32 v5, v3, s0, v5
	v_and_b32_e32 v6, 4, v6
	v_and_b32_e32 v7, 24, v7
	v_sub_u32_e32 v1, v1, v2
	v_or3_b32 v5, v5, v6, v7
	v_lshlrev_b32_e32 v6, 5, v10
	v_ashrrev_i16_sdwa v1, v240, sext(v1) dst_sel:DWORD dst_unused:UNUSED_PAD src0_sel:DWORD src1_sel:BYTE_0
	v_and_b32_e32 v6, 32, v6
	v_bfe_i32 v12, v1, 0, 16
	v_add_lshl_u32 v1, v6, v12, 1
	v_lshl_add_u32 v134, v5, 11, v1
	v_lshl_add_u32 v136, v3, 11, v1
	v_bfe_i32 v1, v241, 27, 1
	v_lshrrev_b32_e32 v1, 22, v1
	v_add_u32_e32 v1, v0, v1
	v_and_b32_e32 v1, 0xfffffc00, v1
	v_sub_u32_e32 v0, v0, v1
	v_lshrrev_b32_e32 v1, 4, v0
	v_ashrrev_i32_e32 v2, 31, v241
	v_bitop3_b32 v0, v1, v0, 32 bitop3:0x6c
	v_lshrrev_b32_e32 v2, 26, v2
	v_ashrrev_i32_e32 v1, 31, v0
	v_add_u32_e32 v2, v241, v2
	s_addc_u32 s87, s66, 0
	s_ashr_i32 s3, s1, 6
	v_lshrrev_b32_e32 v1, 26, v1
	v_ashrrev_i32_e32 v18, 6, v2
	s_ashr_i32 s5, s1, 8
	s_lshl_b32 s88, s3, 10
	v_add_u32_e32 v1, v0, v1
	v_lshlrev_b32_e32 v2, 3, v18
	s_add_u32 s10, s56, 0x18800000
	v_ashrrev_i32_e32 v13, 6, v1
	v_and_b32_e32 v2, -16, v2
	s_addc_u32 s11, s57, 0
	v_add_u32_e32 v2, v13, v2
	v_and_b32_e32 v3, 3, v13
	s_ashr_i32 s89, s2, 31
	v_and_or_b32 v3, v2, s0, v3
	s_lshr_b32 s0, s89, 29
	s_add_i32 s0, s2, s0
	s_ashr_i32 s4, s0, 3
	s_and_b32 s0, s0, -8
	s_sub_i32 s0, s2, s0
	s_cmp_lt_i32 s0, 0
	s_cselect_b32 s12, 25, 24
	s_mul_i32 s0, s0, s12
	s_add_i32 s0, s0, s4
	s_mul_hi_i32 s4, s0, 0x2aaaaaab
	s_lshr_b32 s12, s4, 31
	s_ashr_i32 s4, s4, 2
	s_add_i32 s4, s4, s12
	s_mul_i32 s12, s4, 6
	s_mul_i32 s4, s4, 24
	s_sub_i32 s0, s0, s4
	s_mul_i32 s4, s0, 43
	s_bfe_u32 s13, s4, 0x1000f
	s_bfe_u32 s4, s4, 0x80008
	s_add_i32 s4, s4, s13
	s_mul_i32 s13, s4, 6
	s_sub_i32 s0, s0, s13
	s_sext_i32_i8 s0, s0
	v_lshrrev_b32_e32 v5, 2, v2
	v_lshlrev_b32_e32 v6, 1, v2
	v_and_b32_e32 v1, 0xc0, v1
	s_add_i32 s76, s12, s0
	v_and_b32_e32 v5, 4, v5
	v_and_b32_e32 v6, 24, v6
	v_sub_u32_e32 v0, v0, v1
	s_ashr_i32 s77, s76, 31
	s_bfe_i64 s[18:19], s[4:5], 0x80000
	v_or3_b32 v3, v3, v5, v6
	v_lshlrev_b32_e32 v5, 5, v18
	v_ashrrev_i16_sdwa v0, v240, sext(v0) dst_sel:DWORD dst_unused:UNUSED_PAD src0_sel:DWORD src1_sel:BYTE_0
	s_lshl_b64 s[12:13], s[76:77], 19
	s_lshl_b64 s[18:19], s[18:19], 19
	v_and_b32_e32 v5, 32, v5
	v_bfe_i32 v19, v0, 0, 16
	s_add_u32 s80, s20, s18
	v_add_lshl_u32 v0, v5, v19, 1
	s_addc_u32 s81, s87, s19
	s_add_i32 s85, s88, 0
	v_lshl_add_u32 v138, v3, 11, v0
	s_add_i32 m0, s85, 0x10000
	v_lshl_add_u32 v140, v2, 11, v0
	global_load_lds_dwordx4 v138, s[80:81]
	s_add_i32 m0, s85, 0x12000
	s_add_u32 s18, s80, 0x40000
	global_load_lds_dwordx4 v134, s[80:81]
	s_addc_u32 s19, s81, 0
	s_add_i32 m0, s85, 0x14000
	s_mov_b32 s47, s65
	global_load_lds_dwordx4 v138, s[18:19]
	s_add_i32 m0, s85, 0x16000
	s_add_u32 s78, s10, s12
	s_addc_u32 s79, s11, s13
	s_add_i32 s86, s85, 0x2000
	global_load_lds_dwordx4 v134, s[18:19]
	s_mov_b32 m0, s85
	s_add_u32 s12, s78, 0x40000
	global_load_lds_dwordx4 v140, s[78:79]
	s_mov_b32 m0, s86
	s_addc_u32 s13, s79, 0
	s_add_i32 s64, s85, 0x4000
	global_load_lds_dwordx4 v136, s[78:79]
	s_mov_b32 m0, s64
	s_add_i32 s65, s85, 0x6000
	global_load_lds_dwordx4 v140, s[12:13]
	s_mov_b32 m0, s65
	v_mov_b32_e32 v139, v4
	global_load_lds_dwordx4 v136, s[12:13]
	v_mov_b32_e32 v135, v4
	v_mov_b32_e32 v141, v4
	v_mov_b32_e32 v137, v4
	s_cmp_eq_u32 s5, 1
	s_mov_b32 s24, s74
	s_mov_b32 s46, s66
	v_lshl_add_u64 v[8:9], s[80:81], 0, v[138:139]
	v_lshl_add_u64 v[6:7], s[80:81], 0, v[134:135]
	v_lshl_add_u64 v[0:1], s[78:79], 0, v[140:141]
	s_cselect_b64 s[12:13], -1, 0
	s_cmp_lg_u32 s5, 1
	v_lshl_add_u64 v[2:3], s[78:79], 0, v[136:137]
	s_cbranch_scc1 .LBB0_106
	s_setprio 1
	s_barrier

.LBB0_112:
	s_add_u32 s41, s78, 0xfffc0080
	s_addc_u32 s42, s79, -1
	s_add_i32 s44, 0, 0x10000
	s_cmp_eq_u32 s40, 12
	s_cselect_b32 s83, s1, s42
	s_cselect_b32 s82, s3, s41
	v_add_u32_e32 v171, s44, v150
	s_cselect_b32 s81, s15, s25
	s_cselect_b32 s80, s18, s19
	s_add_i32 s41, 0, 0x14000
	ds_read_b128 v[146:149], v171
	ds_read_b128 v[156:159], v171 offset:1024
	ds_read_b128 v[160:163], v171 offset:2048
	ds_read_b128 v[172:175], v171 offset:3072
	v_add_u32_e32 v171, s41, v150
	ds_read_b128 v[176:179], v171
	ds_read_b128 v[180:183], v171 offset:1024
	ds_read_b128 v[184:187], v171 offset:2048
	ds_read_b128 v[188:191], v171 offset:3072
	v_lshl_add_u64 v[224:225], s[78:79], 0, v[142:143]
	s_add_i32 m0, s85, 0xc000
	ds_read_b128 v[192:195], v170
	ds_read_b128 v[196:199], v170 offset:1024
	ds_read_b128 v[200:203], v170 offset:2048
	ds_read_b128 v[204:207], v170 offset:3072
	ds_read_b128 v[208:211], v170 offset:4096
	ds_read_b128 v[212:215], v170 offset:5120
	ds_read_b128 v[216:219], v170 offset:6144
	ds_read_b128 v[220:223], v170 offset:7168
	global_load_lds_dwordx4 v[224:225], off
	v_lshl_add_u64 v[224:225], s[78:79], 0, v[144:145]
	s_add_i32 m0, s85, 0xe000
	s_nop 0
	global_load_lds_dwordx4 v[224:225], off
	s_waitcnt vmcnt(8)
	s_waitcnt lgkmcnt(0)
	s_barrier
	s_waitcnt lgkmcnt(0)
	v_mfma_f32_16x16x32_bf16 v[130:133], v[146:149], v[192:195], v[130:133]
	v_mfma_f32_16x16x32_bf16 v[126:129], v[160:163], v[192:195], v[126:129]
	v_mfma_f32_16x16x32_bf16 v[114:117], v[146:149], v[200:203], v[114:117]
	v_mfma_f32_16x16x32_bf16 v[110:113], v[160:163], v[200:203], v[110:113]
	v_mfma_f32_16x16x32_bf16 v[98:101], v[146:149], v[208:211], v[98:101]
	v_mfma_f32_16x16x32_bf16 v[94:97], v[160:163], v[208:211], v[94:97]
	v_mfma_f32_16x16x32_bf16 v[82:85], v[146:149], v[216:219], v[82:85]
	v_mfma_f32_16x16x32_bf16 v[78:81], v[160:163], v[216:219], v[78:81]
	v_mfma_f32_16x16x32_bf16 v[130:133], v[156:159], v[196:199], v[130:133]
	v_mfma_f32_16x16x32_bf16 v[126:129], v[172:175], v[196:199], v[126:129]
	v_mfma_f32_16x16x32_bf16 v[114:117], v[156:159], v[204:207], v[114:117]
	v_mfma_f32_16x16x32_bf16 v[110:113], v[172:175], v[204:207], v[110:113]
	v_mfma_f32_16x16x32_bf16 v[98:101], v[156:159], v[212:215], v[98:101]
	v_mfma_f32_16x16x32_bf16 v[94:97], v[172:175], v[212:215], v[94:97]
	v_mfma_f32_16x16x32_bf16 v[82:85], v[156:159], v[220:223], v[82:85]
	v_mfma_f32_16x16x32_bf16 v[78:81], v[172:175], v[220:223], v[78:81]
	v_mfma_f32_16x16x32_bf16 v[122:125], v[176:179], v[192:195], v[122:125]
	v_mfma_f32_16x16x32_bf16 v[118:121], v[184:187], v[192:195], v[118:121]
	v_mfma_f32_16x16x32_bf16 v[106:109], v[176:179], v[200:203], v[106:109]
	v_mfma_f32_16x16x32_bf16 v[102:105], v[184:187], v[200:203], v[102:105]
	v_mfma_f32_16x16x32_bf16 v[90:93], v[176:179], v[208:211], v[90:93]
	v_mfma_f32_16x16x32_bf16 v[86:89], v[184:187], v[208:211], v[86:89]
	v_mfma_f32_16x16x32_bf16 v[74:77], v[176:179], v[216:219], v[74:77]
	v_mfma_f32_16x16x32_bf16 v[70:73], v[184:187], v[216:219], v[70:73]
	v_mfma_f32_16x16x32_bf16 v[122:125], v[180:183], v[196:199], v[122:125]
	v_mfma_f32_16x16x32_bf16 v[118:121], v[188:191], v[196:199], v[118:121]
	v_mfma_f32_16x16x32_bf16 v[106:109], v[180:183], v[204:207], v[106:109]
	v_mfma_f32_16x16x32_bf16 v[102:105], v[188:191], v[204:207], v[102:105]
	v_mfma_f32_16x16x32_bf16 v[90:93], v[180:183], v[212:215], v[90:93]
	v_mfma_f32_16x16x32_bf16 v[86:89], v[188:191], v[212:215], v[86:89]
	v_mfma_f32_16x16x32_bf16 v[74:77], v[180:183], v[220:223], v[74:77]
	v_mfma_f32_16x16x32_bf16 v[70:73], v[188:191], v[220:223], v[70:73]
	s_barrier
	s_add_i32 s42, s44, s88
	v_lshl_add_u64 v[224:225], s[80:81], 0, v[138:139]
	s_mov_b32 m0, s42
	ds_read_b128 v[192:195], v170 offset:16384
	ds_read_b128 v[196:199], v170 offset:17408
	ds_read_b128 v[200:203], v170 offset:18432
	ds_read_b128 v[204:207], v170 offset:19456
	ds_read_b128 v[208:211], v170 offset:20480
	ds_read_b128 v[212:215], v170 offset:21504
	ds_read_b128 v[216:219], v170 offset:22528
	ds_read_b128 v[220:223], v170 offset:23552
	global_load_lds_dwordx4 v[224:225], off
	s_add_i32 m0, s42, 0x2000
	s_add_u32 s44, s80, 0x40000
	v_lshl_add_u64 v[226:227], s[80:81], 0, v[134:135]
	s_addc_u32 s45, s81, 0
	s_add_i32 s41, s41, s88
	global_load_lds_dwordx4 v[226:227], off
	v_lshl_add_u64 v[228:229], s[44:45], 0, v[138:139]
	s_mov_b32 m0, s41
	v_lshl_add_u64 v[230:231], s[82:83], 0, v[136:137]
	global_load_lds_dwordx4 v[228:229], off
	v_lshl_add_u64 v[228:229], s[44:45], 0, v[134:135]
	s_add_i32 m0, s41, 0x2000
	s_nop 0
	global_load_lds_dwordx4 v[228:229], off
	v_lshl_add_u64 v[228:229], s[82:83], 0, v[140:141]
	s_mov_b32 m0, s85
	s_nop 0
	global_load_lds_dwordx4 v[228:229], off
	s_mov_b32 m0, s86
	s_nop 0
	global_load_lds_dwordx4 v[230:231], off
	s_waitcnt vmcnt(8)
	s_waitcnt lgkmcnt(0)
	s_barrier
	s_waitcnt lgkmcnt(0)
	v_mfma_f32_16x16x32_bf16 v[66:69], v[146:149], v[192:195], v[66:69]
	v_mfma_f32_16x16x32_bf16 v[62:65], v[160:163], v[192:195], v[62:65]
	v_mfma_f32_16x16x32_bf16 v[50:53], v[146:149], v[200:203], v[50:53]
	v_mfma_f32_16x16x32_bf16 v[46:49], v[160:163], v[200:203], v[46:49]
	v_mfma_f32_16x16x32_bf16 v[34:37], v[146:149], v[208:211], v[34:37]
	v_mfma_f32_16x16x32_bf16 v[30:33], v[160:163], v[208:211], v[30:33]
	v_mfma_f32_16x16x32_bf16 v[18:21], v[146:149], v[216:219], v[18:21]
	v_mfma_f32_16x16x32_bf16 v[10:13], v[160:163], v[216:219], v[10:13]
	v_mfma_f32_16x16x32_bf16 v[66:69], v[156:159], v[196:199], v[66:69]
	v_mfma_f32_16x16x32_bf16 v[62:65], v[172:175], v[196:199], v[62:65]
	v_mfma_f32_16x16x32_bf16 v[50:53], v[156:159], v[204:207], v[50:53]
	v_mfma_f32_16x16x32_bf16 v[46:49], v[172:175], v[204:207], v[46:49]
	v_mfma_f32_16x16x32_bf16 v[34:37], v[156:159], v[212:215], v[34:37]
	v_mfma_f32_16x16x32_bf16 v[30:33], v[172:175], v[212:215], v[30:33]
	v_mfma_f32_16x16x32_bf16 v[18:21], v[156:159], v[220:223], v[18:21]
	v_mfma_f32_16x16x32_bf16 v[10:13], v[172:175], v[220:223], v[10:13]
	v_mfma_f32_16x16x32_bf16 v[58:61], v[176:179], v[192:195], v[58:61]
	v_mfma_f32_16x16x32_bf16 v[54:57], v[184:187], v[192:195], v[54:57]
	v_mfma_f32_16x16x32_bf16 v[42:45], v[176:179], v[200:203], v[42:45]
	v_mfma_f32_16x16x32_bf16 v[38:41], v[184:187], v[200:203], v[38:41]
	v_mfma_f32_16x16x32_bf16 v[26:29], v[176:179], v[208:211], v[26:29]
	v_mfma_f32_16x16x32_bf16 v[22:25], v[184:187], v[208:211], v[22:25]
	v_mfma_f32_16x16x32_bf16 v[6:9], v[176:179], v[216:219], v[6:9]
	v_mfma_f32_16x16x32_bf16 v[0:3], v[184:187], v[216:219], v[0:3]
	v_mfma_f32_16x16x32_bf16 v[58:61], v[180:183], v[196:199], v[58:61]
	v_mfma_f32_16x16x32_bf16 v[54:57], v[188:191], v[196:199], v[54:57]
	v_mfma_f32_16x16x32_bf16 v[42:45], v[180:183], v[204:207], v[42:45]
	v_mfma_f32_16x16x32_bf16 v[38:41], v[188:191], v[204:207], v[38:41]
	v_mfma_f32_16x16x32_bf16 v[26:29], v[180:183], v[212:215], v[26:29]
	v_mfma_f32_16x16x32_bf16 v[22:25], v[188:191], v[212:215], v[22:25]
	v_mfma_f32_16x16x32_bf16 v[6:9], v[180:183], v[220:223], v[6:9]
	v_mfma_f32_16x16x32_bf16 v[0:3], v[188:191], v[220:223], v[0:3]
	s_barrier
	s_add_i32 s41, 0, 0x18000
	v_add_u32_e32 v171, s41, v150
	s_add_i32 s42, 0, 0x1c000
	ds_read_b128 v[146:149], v171
	ds_read_b128 v[156:159], v171 offset:1024
	ds_read_b128 v[160:163], v171 offset:2048
	ds_read_b128 v[172:175], v171 offset:3072
	v_add_u32_e32 v171, s42, v150
	ds_read_b128 v[176:179], v171
	ds_read_b128 v[180:183], v171 offset:1024
	ds_read_b128 v[184:187], v171 offset:2048
	ds_read_b128 v[188:191], v171 offset:3072
	s_add_u32 s44, s82, 0x40000
	s_addc_u32 s45, s83, 0
	s_mov_b32 m0, s64
	v_lshl_add_u64 v[232:233], s[44:45], 0, v[140:141]
	ds_read_b128 v[192:195], v170 offset:32768
	ds_read_b128 v[196:199], v170 offset:33792
	ds_read_b128 v[200:203], v170 offset:34816
	ds_read_b128 v[204:207], v170 offset:35840
	ds_read_b128 v[208:211], v170 offset:36864
	ds_read_b128 v[212:215], v170 offset:37888
	ds_read_b128 v[216:219], v170 offset:38912
	ds_read_b128 v[220:223], v170 offset:39936
	global_load_lds_dwordx4 v[232:233], off
	v_lshl_add_u64 v[232:233], s[44:45], 0, v[136:137]
	s_mov_b32 m0, s65
	s_nop 0
	global_load_lds_dwordx4 v[232:233], off
	s_waitcnt vmcnt(8)
	s_waitcnt lgkmcnt(0)
	s_barrier
	s_waitcnt lgkmcnt(0)
	v_mfma_f32_16x16x32_bf16 v[130:133], v[146:149], v[192:195], v[130:133]
	v_mfma_f32_16x16x32_bf16 v[126:129], v[160:163], v[192:195], v[126:129]
	v_mfma_f32_16x16x32_bf16 v[114:117], v[146:149], v[200:203], v[114:117]
	v_mfma_f32_16x16x32_bf16 v[110:113], v[160:163], v[200:203], v[110:113]
	v_mfma_f32_16x16x32_bf16 v[98:101], v[146:149], v[208:211], v[98:101]
	v_mfma_f32_16x16x32_bf16 v[94:97], v[160:163], v[208:211], v[94:97]
	v_mfma_f32_16x16x32_bf16 v[82:85], v[146:149], v[216:219], v[82:85]
	v_mfma_f32_16x16x32_bf16 v[78:81], v[160:163], v[216:219], v[78:81]
	v_mfma_f32_16x16x32_bf16 v[130:133], v[156:159], v[196:199], v[130:133]
	v_mfma_f32_16x16x32_bf16 v[126:129], v[172:175], v[196:199], v[126:129]
	v_mfma_f32_16x16x32_bf16 v[114:117], v[156:159], v[204:207], v[114:117]
	v_mfma_f32_16x16x32_bf16 v[110:113], v[172:175], v[204:207], v[110:113]
	v_mfma_f32_16x16x32_bf16 v[98:101], v[156:159], v[212:215], v[98:101]
	v_mfma_f32_16x16x32_bf16 v[94:97], v[172:175], v[212:215], v[94:97]
	v_mfma_f32_16x16x32_bf16 v[82:85], v[156:159], v[220:223], v[82:85]
	v_mfma_f32_16x16x32_bf16 v[78:81], v[172:175], v[220:223], v[78:81]
	v_mfma_f32_16x16x32_bf16 v[122:125], v[176:179], v[192:195], v[122:125]
	v_mfma_f32_16x16x32_bf16 v[118:121], v[184:187], v[192:195], v[118:121]
	v_mfma_f32_16x16x32_bf16 v[106:109], v[176:179], v[200:203], v[106:109]
	v_mfma_f32_16x16x32_bf16 v[102:105], v[184:187], v[200:203], v[102:105]
	v_mfma_f32_16x16x32_bf16 v[90:93], v[176:179], v[208:211], v[90:93]
	v_mfma_f32_16x16x32_bf16 v[86:89], v[184:187], v[208:211], v[86:89]
	v_mfma_f32_16x16x32_bf16 v[74:77], v[176:179], v[216:219], v[74:77]
	v_mfma_f32_16x16x32_bf16 v[70:73], v[184:187], v[216:219], v[70:73]
	v_mfma_f32_16x16x32_bf16 v[122:125], v[180:183], v[196:199], v[122:125]
	v_mfma_f32_16x16x32_bf16 v[118:121], v[188:191], v[196:199], v[118:121]
	v_mfma_f32_16x16x32_bf16 v[106:109], v[180:183], v[204:207], v[106:109]
	v_mfma_f32_16x16x32_bf16 v[102:105], v[188:191], v[204:207], v[102:105]
	v_mfma_f32_16x16x32_bf16 v[90:93], v[180:183], v[212:215], v[90:93]
	v_mfma_f32_16x16x32_bf16 v[86:89], v[188:191], v[212:215], v[86:89]
	v_mfma_f32_16x16x32_bf16 v[74:77], v[180:183], v[220:223], v[74:77]
	v_mfma_f32_16x16x32_bf16 v[70:73], v[188:191], v[220:223], v[70:73]
	s_barrier
	s_add_i32 s41, s41, s88
	v_lshl_add_u64 v[224:225], v[224:225], 0, s[30:31]
	s_mov_b32 m0, s41
	ds_read_b128 v[192:195], v170 offset:49152
	ds_read_b128 v[196:199], v170 offset:50176
	ds_read_b128 v[200:203], v170 offset:51200
	ds_read_b128 v[204:207], v170 offset:52224
	ds_read_b128 v[208:211], v170 offset:53248
	ds_read_b128 v[212:215], v170 offset:54272
	ds_read_b128 v[216:219], v170 offset:55296
	ds_read_b128 v[220:223], v170 offset:56320
	global_load_lds_dwordx4 v[224:225], off
	s_add_i32 m0, s41, 0x2000
	s_add_u32 s44, s80, 0x40080
	v_lshl_add_u64 v[224:225], v[226:227], 0, s[30:31]
	s_addc_u32 s45, s81, 0
	s_add_i32 s41, s42, s88
	global_load_lds_dwordx4 v[224:225], off
	v_lshl_add_u64 v[224:225], s[44:45], 0, v[138:139]
	s_mov_b32 m0, s41
	s_nop 0
	global_load_lds_dwordx4 v[224:225], off
	v_lshl_add_u64 v[224:225], s[44:45], 0, v[134:135]
	s_add_i32 m0, s41, 0x2000
	s_nop 0
	global_load_lds_dwordx4 v[224:225], off
	v_lshl_add_u64 v[224:225], v[228:229], 0, s[30:31]
	s_mov_b32 m0, s36
	s_nop 0
	global_load_lds_dwordx4 v[224:225], off
	v_lshl_add_u64 v[224:225], v[230:231], 0, s[30:31]
	s_mov_b32 m0, s37
	s_nop 0
	global_load_lds_dwordx4 v[224:225], off
	s_waitcnt vmcnt(8)
	s_waitcnt lgkmcnt(0)
	s_barrier
	s_waitcnt lgkmcnt(0)
	v_mfma_f32_16x16x32_bf16 v[66:69], v[146:149], v[192:195], v[66:69]
	v_mfma_f32_16x16x32_bf16 v[62:65], v[160:163], v[192:195], v[62:65]
	v_mfma_f32_16x16x32_bf16 v[50:53], v[146:149], v[200:203], v[50:53]
	v_mfma_f32_16x16x32_bf16 v[46:49], v[160:163], v[200:203], v[46:49]
	v_mfma_f32_16x16x32_bf16 v[34:37], v[146:149], v[208:211], v[34:37]
	v_mfma_f32_16x16x32_bf16 v[30:33], v[160:163], v[208:211], v[30:33]
	v_mfma_f32_16x16x32_bf16 v[18:21], v[146:149], v[216:219], v[18:21]
	v_mfma_f32_16x16x32_bf16 v[10:13], v[160:163], v[216:219], v[10:13]
	v_mfma_f32_16x16x32_bf16 v[66:69], v[156:159], v[196:199], v[66:69]
	v_mfma_f32_16x16x32_bf16 v[62:65], v[172:175], v[196:199], v[62:65]
	v_mfma_f32_16x16x32_bf16 v[50:53], v[156:159], v[204:207], v[50:53]
	v_mfma_f32_16x16x32_bf16 v[46:49], v[172:175], v[204:207], v[46:49]
	v_mfma_f32_16x16x32_bf16 v[34:37], v[156:159], v[212:215], v[34:37]
	v_mfma_f32_16x16x32_bf16 v[30:33], v[172:175], v[212:215], v[30:33]
	v_mfma_f32_16x16x32_bf16 v[18:21], v[156:159], v[220:223], v[18:21]
	v_mfma_f32_16x16x32_bf16 v[10:13], v[172:175], v[220:223], v[10:13]
	v_mfma_f32_16x16x32_bf16 v[58:61], v[176:179], v[192:195], v[58:61]
	v_mfma_f32_16x16x32_bf16 v[54:57], v[184:187], v[192:195], v[54:57]
	v_mfma_f32_16x16x32_bf16 v[42:45], v[176:179], v[200:203], v[42:45]
	v_mfma_f32_16x16x32_bf16 v[38:41], v[184:187], v[200:203], v[38:41]
	v_mfma_f32_16x16x32_bf16 v[26:29], v[176:179], v[208:211], v[26:29]
	v_mfma_f32_16x16x32_bf16 v[22:25], v[184:187], v[208:211], v[22:25]
	v_mfma_f32_16x16x32_bf16 v[6:9], v[176:179], v[216:219], v[6:9]
	v_mfma_f32_16x16x32_bf16 v[0:3], v[184:187], v[216:219], v[0:3]
	v_mfma_f32_16x16x32_bf16 v[58:61], v[180:183], v[196:199], v[58:61]
	v_mfma_f32_16x16x32_bf16 v[54:57], v[188:191], v[196:199], v[54:57]
	v_mfma_f32_16x16x32_bf16 v[42:45], v[180:183], v[204:207], v[42:45]
	v_mfma_f32_16x16x32_bf16 v[38:41], v[188:191], v[204:207], v[38:41]
	v_mfma_f32_16x16x32_bf16 v[26:29], v[180:183], v[212:215], v[26:29]
	v_mfma_f32_16x16x32_bf16 v[22:25], v[188:191], v[212:215], v[22:25]
	v_mfma_f32_16x16x32_bf16 v[6:9], v[180:183], v[220:223], v[6:9]
	v_mfma_f32_16x16x32_bf16 v[0:3], v[188:191], v[220:223], v[0:3]
	s_barrier
	s_add_i32 s40, s40, 2
	s_add_u32 s78, s78, 0x100
	s_addc_u32 s79, s79, 0
	s_add_u32 s19, s19, 0x100
	s_addc_u32 s25, s25, 0
	s_cmp_gt_u32 s40, 13
	s_cbranch_scc0 .LBB0_112
	s_and_b64 vcc, exec, s[66:67]
	s_cbranch_vccz .LBB0_115
	s_barrier

.LBB0_118:
	s_waitcnt vmcnt(0)
	v_readlane_b32 s72, v247, 5
	v_readlane_b32 s68, v247, 7
	v_readlane_b32 s79, v247, 4
	v_readlane_b32 s73, v247, 6
	v_readlane_b32 s69, v247, 8
	s_mov_b64 s[70:71], 0x20000000
	s_mov_b32 s74, s24
	s_mov_b32 s65, s47
	s_mov_b32 s66, s46
	s_setprio 0
	s_barrier
	v_readlane_b32 s24, v247, 11

.LBB0_143:
	s_cmp_eq_u32 s35, 5
	s_cselect_b64 s[8:9], -1, 0
	s_cmpk_lg_i32 s14, 0x100
	s_cselect_b64 s[0:1], -1, 0
	s_or_b64 s[0:1], s[8:9], s[0:1]
	s_andn2_b64 vcc, exec, s[0:1]
	s_mov_b64 s[4:5], -1
	s_cbranch_vccz .LBB0_171
	v_ashrrev_i32_e32 v1, 31, v241
	v_lshrrev_b32_e32 v1, 26, v1
	v_add_u32_e32 v1, v241, v1
	v_ashrrev_i32_e32 v10, 6, v1
	v_bfe_i32 v1, v241, 27, 1
	v_lshlrev_b32_e32 v0, 4, v241
	v_lshrrev_b32_e32 v1, 22, v1
	v_add_u32_e32 v1, v0, v1
	v_and_b32_e32 v1, 0xfffffc00, v1
	v_sub_u32_e32 v1, v0, v1
	s_add_u32 s15, s56, 0x1a000000
	v_lshrrev_b32_e32 v2, 4, v1
	s_addc_u32 s20, s57, 0
	v_bitop3_b32 v1, v2, v1, 32 bitop3:0x6c
	s_and_b64 s[0:1], s[62:63], exec
	v_ashrrev_i32_e32 v3, 31, v1
	s_cselect_b32 s0, 0x1600000, 0
	v_lshrrev_b32_e32 v3, 26, v3
	s_add_u32 s0, s56, s0
	v_lshlrev_b32_e32 v2, 3, v10
	v_add_u32_e32 v3, v1, v3
	s_addc_u32 s1, s57, 0
	v_and_b32_e32 v2, -16, v2
	v_ashrrev_i32_e32 v12, 6, v3
	v_and_b32_e32 v3, 0xc0, v3
	s_add_u32 s25, s0, 0x9c00000
	v_add_u32_e32 v2, v12, v2
	v_lshlrev_b32_e32 v5, 5, v10
	v_sub_u32_e32 v1, v1, v3
	s_addc_u32 s36, s1, 0
	v_and_b32_e32 v11, 32, v5
	v_ashrrev_i16_sdwa v1, v240, sext(v1) dst_sel:DWORD dst_unused:UNUSED_PAD src0_sel:DWORD src1_sel:BYTE_0
	v_lshlrev_b32_e32 v3, 1, v2
	v_lshrrev_b32_e32 v5, 2, v2
	v_and_b32_e32 v6, 3, v12
	s_mov_b32 s1, 0x7fffe0
	v_bfe_i32 v13, v1, 0, 16
	v_and_b32_e32 v3, 24, v3
	v_and_b32_e32 v5, 4, v5
	v_and_or_b32 v6, v2, s1, v6
	s_movk_i32 s4, 0x1600
	v_add_u32_e32 v1, v11, v13
	v_or3_b32 v3, v6, v5, v3
	v_mul_lo_u32 v2, v2, s4
	v_add_lshl_u32 v170, v1, v2, 1
	v_mul_u32_u24_e32 v2, 0x1600, v3
	v_add_u32_e32 v0, 0x2000, v0
	v_add_lshl_u32 v172, v2, v1, 1
	v_ashrrev_i32_e32 v1, 31, v0
	v_lshrrev_b32_e32 v1, 22, v1
	v_add_u32_e32 v1, v0, v1
	v_ashrrev_i32_e32 v18, 10, v1
	v_mul_i32_i24_e32 v1, 0x400, v18
	v_sub_u32_e32 v0, v0, v1
	v_lshrrev_b32_e32 v1, 4, v0
	v_bitop3_b32 v0, v1, v0, 32 bitop3:0x6c
	v_ashrrev_i32_e32 v2, 31, v0
	v_lshrrev_b32_e32 v2, 26, v2
	v_lshlrev_b32_e32 v1, 3, v18
	v_add_u32_e32 v2, v0, v2
	v_and_b32_e32 v1, -16, v1
	v_ashrrev_i32_e32 v20, 6, v2
	v_add_u32_e32 v1, v20, v1
	v_lshlrev_b32_e32 v3, 5, v18
	v_and_b32_e32 v2, 0xc0, v2
	v_and_b32_e32 v5, 3, v20
	v_readfirstlane_b32 s3, v241
	v_and_b32_e32 v19, 32, v3
	v_sub_u32_e32 v0, v0, v2
	v_lshlrev_b32_e32 v2, 1, v1
	v_lshrrev_b32_e32 v3, 2, v1
	v_and_or_b32 v5, v1, s1, v5
	v_mul_lo_u32 v1, v1, s4
	s_and_b32 s4, s2, 7
	s_ashr_i32 s5, s3, 6
	s_lshl_b32 s37, s4, 2
	s_ashr_i32 s1, s2, 6
	s_bfe_u32 s39, s2, 0x30003
	s_ashr_i32 s0, s3, 8
	s_add_i32 s37, s37, s1
	s_lshl_b32 s38, s5, 10
	s_mul_i32 s10, s39, 0x2c0000
	v_ashrrev_i16_sdwa v0, v240, sext(v0) dst_sel:DWORD dst_unused:UNUSED_PAD src0_sel:DWORD src1_sel:BYTE_0
	s_add_u32 s72, s25, s10
	v_bfe_i32 v21, v0, 0, 16
	v_and_b32_e32 v2, 24, v2
	v_and_b32_e32 v3, 4, v3
	s_addc_u32 s73, s36, 0
	s_add_i32 s40, s38, 0
	v_add_u32_e32 v0, v19, v21
	v_or3_b32 v2, v5, v3, v2
	s_add_i32 m0, s40, 0x10000
	v_add_lshl_u32 v174, v0, v1, 1
	v_mul_u32_u24_e32 v1, 0x1600, v2
	global_load_lds_dwordx4 v172, s[72:73]
	s_add_i32 m0, s40, 0x12000
	v_add_lshl_u32 v176, v1, v0, 1
	s_add_u32 s10, s72, 0x160000
	global_load_lds_dwordx4 v176, s[72:73]
	s_addc_u32 s11, s73, 0
	s_add_i32 m0, s40, 0x14000
	s_mul_i32 s12, s37, 0x2c0000
	global_load_lds_dwordx4 v172, s[10:11]
	s_add_i32 m0, s40, 0x16000
	s_mul_hi_i32 s1, s37, 0x2c0000
	s_add_u32 s68, s15, s12
	s_addc_u32 s69, s20, s1
	s_add_i32 s41, s40, 0x2000
	global_load_lds_dwordx4 v176, s[10:11]
	s_mov_b32 m0, s40
	s_add_u32 s10, s68, 0x160000
	global_load_lds_dwordx4 v170, s[68:69]
	s_mov_b32 m0, s41
	s_addc_u32 s11, s69, 0
	s_add_i32 s64, s40, 0x4000
	global_load_lds_dwordx4 v174, s[68:69]
	s_mov_b32 m0, s64
	s_add_i32 s65, s40, 0x6000
	global_load_lds_dwordx4 v170, s[10:11]
	s_mov_b32 m0, s65
	v_mov_b32_e32 v173, v4
	global_load_lds_dwordx4 v174, s[10:11]
	v_mov_b32_e32 v177, v4
	v_mov_b32_e32 v171, v4
	v_mov_b32_e32 v175, v4
	s_cmp_eq_u32 s0, 1
	v_lshl_add_u64 v[8:9], s[72:73], 0, v[172:173]
	v_lshl_add_u64 v[6:7], s[72:73], 0, v[176:177]
	v_lshl_add_u64 v[0:1], s[68:69], 0, v[170:171]
	s_cselect_b64 s[10:11], -1, 0
	s_cmp_lg_u32 s0, 1
	v_lshl_add_u64 v[2:3], s[68:69], 0, v[174:175]
	v_writelane_b32 v247, s74, 12
	s_cbranch_scc1 .LBB0_146
	s_setprio 1
	s_barrier

.LBB0_157:
	s_add_u32 s72, s68, 0x100
	s_addc_u32 s73, s69, 0
	s_add_i32 s45, 0, 0x10000
	s_cmp_eq_u32 s44, 40
	s_cselect_b32 s77, s67, s73
	s_cselect_b32 s76, s66, s72
	s_cselect_b32 s75, s5, vcc_hi
	s_cselect_b32 s74, s4, vcc_lo
	s_add_i32 s24, 0, 0x14000
	v_add_u32_e32 v146, s45, v150
	v_add_u32_e32 v186, s24, v150
	ds_read_b128 v[134:137], v146
	ds_read_b128 v[138:141], v146 offset:1024
	ds_read_b128 v[142:145], v146 offset:2048
	ds_read_b128 v[146:149], v146 offset:3072
	ds_read_b128 v[156:159], v186
	ds_read_b128 v[160:163], v186 offset:1024
	ds_read_b128 v[182:185], v186 offset:2048
	ds_read_b128 v[186:189], v186 offset:3072
	v_lshl_add_u64 v[224:225], s[68:69], 0, v[178:179]
	s_add_i32 m0, s40, 0xc000
	ds_read_b128 v[190:193], v198
	ds_read_b128 v[194:197], v198 offset:1024
	ds_read_b128 v[200:203], v198 offset:2048
	ds_read_b128 v[204:207], v198 offset:3072
	ds_read_b128 v[208:211], v198 offset:4096
	ds_read_b128 v[212:215], v198 offset:5120
	ds_read_b128 v[216:219], v198 offset:6144
	ds_read_b128 v[220:223], v198 offset:7168
	global_load_lds_dwordx4 v[224:225], off
	v_lshl_add_u64 v[224:225], s[68:69], 0, v[180:181]
	s_add_i32 m0, s40, 0xe000
	s_nop 0
	global_load_lds_dwordx4 v[224:225], off
	s_waitcnt vmcnt(8)
	s_waitcnt lgkmcnt(0)
	s_barrier
	s_waitcnt lgkmcnt(0)
	v_mfma_f32_16x16x32_bf16 v[130:133], v[134:137], v[190:193], v[130:133]
	v_mfma_f32_16x16x32_bf16 v[126:129], v[142:145], v[190:193], v[126:129]
	v_mfma_f32_16x16x32_bf16 v[122:125], v[134:137], v[200:203], v[122:125]
	v_mfma_f32_16x16x32_bf16 v[118:121], v[142:145], v[200:203], v[118:121]
	v_mfma_f32_16x16x32_bf16 v[114:117], v[134:137], v[208:211], v[114:117]
	v_mfma_f32_16x16x32_bf16 v[110:113], v[142:145], v[208:211], v[110:113]
	v_mfma_f32_16x16x32_bf16 v[106:109], v[134:137], v[216:219], v[106:109]
	v_mfma_f32_16x16x32_bf16 v[102:105], v[142:145], v[216:219], v[102:105]
	v_mfma_f32_16x16x32_bf16 v[130:133], v[138:141], v[194:197], v[130:133]
	v_mfma_f32_16x16x32_bf16 v[126:129], v[146:149], v[194:197], v[126:129]
	v_mfma_f32_16x16x32_bf16 v[122:125], v[138:141], v[204:207], v[122:125]
	v_mfma_f32_16x16x32_bf16 v[118:121], v[146:149], v[204:207], v[118:121]
	v_mfma_f32_16x16x32_bf16 v[114:117], v[138:141], v[212:215], v[114:117]
	v_mfma_f32_16x16x32_bf16 v[110:113], v[146:149], v[212:215], v[110:113]
	v_mfma_f32_16x16x32_bf16 v[106:109], v[138:141], v[220:223], v[106:109]
	v_mfma_f32_16x16x32_bf16 v[102:105], v[146:149], v[220:223], v[102:105]
	v_mfma_f32_16x16x32_bf16 v[98:101], v[156:159], v[190:193], v[98:101]
	v_mfma_f32_16x16x32_bf16 v[94:97], v[182:185], v[190:193], v[94:97]
	v_mfma_f32_16x16x32_bf16 v[90:93], v[156:159], v[200:203], v[90:93]
	v_mfma_f32_16x16x32_bf16 v[86:89], v[182:185], v[200:203], v[86:89]
	v_mfma_f32_16x16x32_bf16 v[82:85], v[156:159], v[208:211], v[82:85]
	v_mfma_f32_16x16x32_bf16 v[78:81], v[182:185], v[208:211], v[78:81]
	v_mfma_f32_16x16x32_bf16 v[74:77], v[156:159], v[216:219], v[74:77]
	v_mfma_f32_16x16x32_bf16 v[70:73], v[182:185], v[216:219], v[70:73]
	v_mfma_f32_16x16x32_bf16 v[98:101], v[160:163], v[194:197], v[98:101]
	v_mfma_f32_16x16x32_bf16 v[94:97], v[186:189], v[194:197], v[94:97]
	v_mfma_f32_16x16x32_bf16 v[90:93], v[160:163], v[204:207], v[90:93]
	v_mfma_f32_16x16x32_bf16 v[86:89], v[186:189], v[204:207], v[86:89]
	v_mfma_f32_16x16x32_bf16 v[82:85], v[160:163], v[212:215], v[82:85]
	v_mfma_f32_16x16x32_bf16 v[78:81], v[186:189], v[212:215], v[78:81]
	v_mfma_f32_16x16x32_bf16 v[74:77], v[160:163], v[220:223], v[74:77]
	v_mfma_f32_16x16x32_bf16 v[70:73], v[186:189], v[220:223], v[70:73]
	s_barrier
	s_add_i32 s45, s45, s38
	v_lshl_add_u64 v[224:225], s[74:75], 0, v[172:173]
	s_mov_b32 m0, s45
	ds_read_b128 v[190:193], v198 offset:16384
	ds_read_b128 v[194:197], v198 offset:17408
	ds_read_b128 v[200:203], v198 offset:18432
	ds_read_b128 v[204:207], v198 offset:19456
	ds_read_b128 v[208:211], v198 offset:20480
	ds_read_b128 v[212:215], v198 offset:21504
	ds_read_b128 v[216:219], v198 offset:22528
	ds_read_b128 v[220:223], v198 offset:23552
	global_load_lds_dwordx4 v[224:225], off
	s_add_i32 m0, s45, 0x2000
	s_add_u32 s46, s74, 0x160000
	v_lshl_add_u64 v[226:227], s[74:75], 0, v[176:177]
	s_addc_u32 s47, s75, 0
	s_add_i32 s24, s24, s38
	global_load_lds_dwordx4 v[226:227], off
	v_lshl_add_u64 v[228:229], s[46:47], 0, v[172:173]
	s_mov_b32 m0, s24
	v_lshl_add_u64 v[230:231], s[76:77], 0, v[174:175]
	global_load_lds_dwordx4 v[228:229], off
	v_lshl_add_u64 v[228:229], s[46:47], 0, v[176:177]
	s_add_i32 m0, s24, 0x2000
	s_nop 0
	global_load_lds_dwordx4 v[228:229], off
	v_lshl_add_u64 v[228:229], s[76:77], 0, v[170:171]
	s_mov_b32 m0, s40
	s_nop 0
	global_load_lds_dwordx4 v[228:229], off
	s_mov_b32 m0, s41
	s_nop 0
	global_load_lds_dwordx4 v[230:231], off
	s_waitcnt vmcnt(8)
	s_waitcnt lgkmcnt(0)
	s_barrier
	s_waitcnt lgkmcnt(0)
	v_mfma_f32_16x16x32_bf16 v[66:69], v[134:137], v[190:193], v[66:69]
	v_mfma_f32_16x16x32_bf16 v[62:65], v[142:145], v[190:193], v[62:65]
	v_mfma_f32_16x16x32_bf16 v[58:61], v[134:137], v[200:203], v[58:61]
	v_mfma_f32_16x16x32_bf16 v[54:57], v[142:145], v[200:203], v[54:57]
	v_mfma_f32_16x16x32_bf16 v[50:53], v[134:137], v[208:211], v[50:53]
	v_mfma_f32_16x16x32_bf16 v[46:49], v[142:145], v[208:211], v[46:49]
	v_mfma_f32_16x16x32_bf16 v[42:45], v[134:137], v[216:219], v[42:45]
	v_mfma_f32_16x16x32_bf16 v[38:41], v[142:145], v[216:219], v[38:41]
	v_mfma_f32_16x16x32_bf16 v[66:69], v[138:141], v[194:197], v[66:69]
	v_mfma_f32_16x16x32_bf16 v[62:65], v[146:149], v[194:197], v[62:65]
	v_mfma_f32_16x16x32_bf16 v[58:61], v[138:141], v[204:207], v[58:61]
	v_mfma_f32_16x16x32_bf16 v[54:57], v[146:149], v[204:207], v[54:57]
	v_mfma_f32_16x16x32_bf16 v[50:53], v[138:141], v[212:215], v[50:53]
	v_mfma_f32_16x16x32_bf16 v[46:49], v[146:149], v[212:215], v[46:49]
	v_mfma_f32_16x16x32_bf16 v[42:45], v[138:141], v[220:223], v[42:45]
	v_mfma_f32_16x16x32_bf16 v[38:41], v[146:149], v[220:223], v[38:41]
	v_mfma_f32_16x16x32_bf16 v[34:37], v[156:159], v[190:193], v[34:37]
	v_mfma_f32_16x16x32_bf16 v[30:33], v[182:185], v[190:193], v[30:33]
	v_mfma_f32_16x16x32_bf16 v[26:29], v[156:159], v[200:203], v[26:29]
	v_mfma_f32_16x16x32_bf16 v[22:25], v[182:185], v[200:203], v[22:25]
	v_mfma_f32_16x16x32_bf16 v[18:21], v[156:159], v[208:211], v[18:21]
	v_mfma_f32_16x16x32_bf16 v[10:13], v[182:185], v[208:211], v[10:13]
	v_mfma_f32_16x16x32_bf16 v[6:9], v[156:159], v[216:219], v[6:9]
	v_mfma_f32_16x16x32_bf16 v[0:3], v[182:185], v[216:219], v[0:3]
	v_mfma_f32_16x16x32_bf16 v[34:37], v[160:163], v[194:197], v[34:37]
	v_mfma_f32_16x16x32_bf16 v[30:33], v[186:189], v[194:197], v[30:33]
	v_mfma_f32_16x16x32_bf16 v[26:29], v[160:163], v[204:207], v[26:29]
	v_mfma_f32_16x16x32_bf16 v[22:25], v[186:189], v[204:207], v[22:25]
	v_mfma_f32_16x16x32_bf16 v[18:21], v[160:163], v[212:215], v[18:21]
	v_mfma_f32_16x16x32_bf16 v[10:13], v[186:189], v[212:215], v[10:13]
	v_mfma_f32_16x16x32_bf16 v[6:9], v[160:163], v[220:223], v[6:9]
	v_mfma_f32_16x16x32_bf16 v[0:3], v[186:189], v[220:223], v[0:3]
	s_barrier
	s_add_i32 s24, 0, 0x18000
	s_add_i32 s45, 0, 0x1c000
	v_add_u32_e32 v146, s24, v150
	v_add_u32_e32 v186, s45, v150
	ds_read_b128 v[134:137], v146
	ds_read_b128 v[138:141], v146 offset:1024
	ds_read_b128 v[142:145], v146 offset:2048
	ds_read_b128 v[146:149], v146 offset:3072
	ds_read_b128 v[156:159], v186
	ds_read_b128 v[160:163], v186 offset:1024
	ds_read_b128 v[182:185], v186 offset:2048
	ds_read_b128 v[186:189], v186 offset:3072
	s_add_u32 s46, s76, 0x160000
	s_addc_u32 s47, s77, 0
	s_mov_b32 m0, s64
	v_lshl_add_u64 v[232:233], s[46:47], 0, v[170:171]
	ds_read_b128 v[190:193], v198 offset:32768
	ds_read_b128 v[194:197], v198 offset:33792
	ds_read_b128 v[200:203], v198 offset:34816
	ds_read_b128 v[204:207], v198 offset:35840
	ds_read_b128 v[208:211], v198 offset:36864
	ds_read_b128 v[212:215], v198 offset:37888
	ds_read_b128 v[216:219], v198 offset:38912
	ds_read_b128 v[220:223], v198 offset:39936
	global_load_lds_dwordx4 v[232:233], off
	v_lshl_add_u64 v[232:233], s[46:47], 0, v[174:175]
	s_mov_b32 m0, s65
	s_nop 0
	global_load_lds_dwordx4 v[232:233], off
	s_waitcnt vmcnt(8)
	s_waitcnt lgkmcnt(0)
	s_barrier
	s_waitcnt lgkmcnt(0)
	v_mfma_f32_16x16x32_bf16 v[130:133], v[134:137], v[190:193], v[130:133]
	v_mfma_f32_16x16x32_bf16 v[126:129], v[142:145], v[190:193], v[126:129]
	v_mfma_f32_16x16x32_bf16 v[122:125], v[134:137], v[200:203], v[122:125]
	v_mfma_f32_16x16x32_bf16 v[118:121], v[142:145], v[200:203], v[118:121]
	v_mfma_f32_16x16x32_bf16 v[114:117], v[134:137], v[208:211], v[114:117]
	v_mfma_f32_16x16x32_bf16 v[110:113], v[142:145], v[208:211], v[110:113]
	v_mfma_f32_16x16x32_bf16 v[106:109], v[134:137], v[216:219], v[106:109]
	v_mfma_f32_16x16x32_bf16 v[102:105], v[142:145], v[216:219], v[102:105]
	v_mfma_f32_16x16x32_bf16 v[130:133], v[138:141], v[194:197], v[130:133]
	v_mfma_f32_16x16x32_bf16 v[126:129], v[146:149], v[194:197], v[126:129]
	v_mfma_f32_16x16x32_bf16 v[122:125], v[138:141], v[204:207], v[122:125]
	v_mfma_f32_16x16x32_bf16 v[118:121], v[146:149], v[204:207], v[118:121]
	v_mfma_f32_16x16x32_bf16 v[114:117], v[138:141], v[212:215], v[114:117]
	v_mfma_f32_16x16x32_bf16 v[110:113], v[146:149], v[212:215], v[110:113]
	v_mfma_f32_16x16x32_bf16 v[106:109], v[138:141], v[220:223], v[106:109]
	v_mfma_f32_16x16x32_bf16 v[102:105], v[146:149], v[220:223], v[102:105]
	v_mfma_f32_16x16x32_bf16 v[98:101], v[156:159], v[190:193], v[98:101]
	v_mfma_f32_16x16x32_bf16 v[94:97], v[182:185], v[190:193], v[94:97]
	v_mfma_f32_16x16x32_bf16 v[90:93], v[156:159], v[200:203], v[90:93]
	v_mfma_f32_16x16x32_bf16 v[86:89], v[182:185], v[200:203], v[86:89]
	v_mfma_f32_16x16x32_bf16 v[82:85], v[156:159], v[208:211], v[82:85]
	v_mfma_f32_16x16x32_bf16 v[78:81], v[182:185], v[208:211], v[78:81]
	v_mfma_f32_16x16x32_bf16 v[74:77], v[156:159], v[216:219], v[74:77]
	v_mfma_f32_16x16x32_bf16 v[70:73], v[182:185], v[216:219], v[70:73]
	v_mfma_f32_16x16x32_bf16 v[98:101], v[160:163], v[194:197], v[98:101]
	v_mfma_f32_16x16x32_bf16 v[94:97], v[186:189], v[194:197], v[94:97]
	v_mfma_f32_16x16x32_bf16 v[90:93], v[160:163], v[204:207], v[90:93]
	v_mfma_f32_16x16x32_bf16 v[86:89], v[186:189], v[204:207], v[86:89]
	v_mfma_f32_16x16x32_bf16 v[82:85], v[160:163], v[212:215], v[82:85]
	v_mfma_f32_16x16x32_bf16 v[78:81], v[186:189], v[212:215], v[78:81]
	v_mfma_f32_16x16x32_bf16 v[74:77], v[160:163], v[220:223], v[74:77]
	v_mfma_f32_16x16x32_bf16 v[70:73], v[186:189], v[220:223], v[70:73]
	s_barrier
	s_add_i32 s24, s24, s38
	v_lshl_add_u64 v[224:225], v[224:225], 0, s[30:31]
	s_mov_b32 m0, s24
	ds_read_b128 v[190:193], v198 offset:49152
	ds_read_b128 v[194:197], v198 offset:50176
	ds_read_b128 v[200:203], v198 offset:51200
	ds_read_b128 v[204:207], v198 offset:52224
	ds_read_b128 v[208:211], v198 offset:53248
	ds_read_b128 v[212:215], v198 offset:54272
	ds_read_b128 v[216:219], v198 offset:55296
	ds_read_b128 v[220:223], v198 offset:56320
	global_load_lds_dwordx4 v[224:225], off
	s_add_i32 m0, s24, 0x2000
	s_add_u32 s46, s74, 0x160080
	v_lshl_add_u64 v[224:225], v[226:227], 0, s[30:31]
	s_addc_u32 s47, s75, 0
	s_add_i32 s24, s45, s38
	global_load_lds_dwordx4 v[224:225], off
	v_lshl_add_u64 v[224:225], s[46:47], 0, v[172:173]
	s_mov_b32 m0, s24
	s_nop 0
	global_load_lds_dwordx4 v[224:225], off
	v_lshl_add_u64 v[224:225], s[46:47], 0, v[176:177]
	s_add_i32 m0, s24, 0x2000
	s_nop 0
	global_load_lds_dwordx4 v[224:225], off
	v_lshl_add_u64 v[224:225], v[228:229], 0, s[30:31]
	s_mov_b32 m0, s80
	s_nop 0
	global_load_lds_dwordx4 v[224:225], off
	v_lshl_add_u64 v[224:225], v[230:231], 0, s[30:31]
	s_mov_b32 m0, s81
	s_nop 0
	global_load_lds_dwordx4 v[224:225], off
	s_waitcnt vmcnt(8)
	s_waitcnt lgkmcnt(0)
	s_barrier
	s_waitcnt lgkmcnt(0)
	v_mfma_f32_16x16x32_bf16 v[66:69], v[134:137], v[190:193], v[66:69]
	v_mfma_f32_16x16x32_bf16 v[62:65], v[142:145], v[190:193], v[62:65]
	v_mfma_f32_16x16x32_bf16 v[58:61], v[134:137], v[200:203], v[58:61]
	v_mfma_f32_16x16x32_bf16 v[54:57], v[142:145], v[200:203], v[54:57]
	v_mfma_f32_16x16x32_bf16 v[50:53], v[134:137], v[208:211], v[50:53]
	v_mfma_f32_16x16x32_bf16 v[46:49], v[142:145], v[208:211], v[46:49]
	v_mfma_f32_16x16x32_bf16 v[42:45], v[134:137], v[216:219], v[42:45]
	v_mfma_f32_16x16x32_bf16 v[38:41], v[142:145], v[216:219], v[38:41]
	v_mfma_f32_16x16x32_bf16 v[66:69], v[138:141], v[194:197], v[66:69]
	v_mfma_f32_16x16x32_bf16 v[62:65], v[146:149], v[194:197], v[62:65]
	v_mfma_f32_16x16x32_bf16 v[58:61], v[138:141], v[204:207], v[58:61]
	v_mfma_f32_16x16x32_bf16 v[54:57], v[146:149], v[204:207], v[54:57]
	v_mfma_f32_16x16x32_bf16 v[50:53], v[138:141], v[212:215], v[50:53]
	v_mfma_f32_16x16x32_bf16 v[46:49], v[146:149], v[212:215], v[46:49]
	v_mfma_f32_16x16x32_bf16 v[42:45], v[138:141], v[220:223], v[42:45]
	v_mfma_f32_16x16x32_bf16 v[38:41], v[146:149], v[220:223], v[38:41]
	v_mfma_f32_16x16x32_bf16 v[34:37], v[156:159], v[190:193], v[34:37]
	v_mfma_f32_16x16x32_bf16 v[30:33], v[182:185], v[190:193], v[30:33]
	v_mfma_f32_16x16x32_bf16 v[26:29], v[156:159], v[200:203], v[26:29]
	v_mfma_f32_16x16x32_bf16 v[22:25], v[182:185], v[200:203], v[22:25]
	v_mfma_f32_16x16x32_bf16 v[18:21], v[156:159], v[208:211], v[18:21]
	v_mfma_f32_16x16x32_bf16 v[10:13], v[182:185], v[208:211], v[10:13]
	v_mfma_f32_16x16x32_bf16 v[6:9], v[156:159], v[216:219], v[6:9]
	v_mfma_f32_16x16x32_bf16 v[0:3], v[182:185], v[216:219], v[0:3]
	v_mfma_f32_16x16x32_bf16 v[34:37], v[160:163], v[194:197], v[34:37]
	v_mfma_f32_16x16x32_bf16 v[30:33], v[186:189], v[194:197], v[30:33]
	v_mfma_f32_16x16x32_bf16 v[26:29], v[160:163], v[204:207], v[26:29]
	v_mfma_f32_16x16x32_bf16 v[22:25], v[186:189], v[204:207], v[22:25]
	v_mfma_f32_16x16x32_bf16 v[18:21], v[160:163], v[212:215], v[18:21]
	v_mfma_f32_16x16x32_bf16 v[10:13], v[186:189], v[212:215], v[10:13]
	v_mfma_f32_16x16x32_bf16 v[6:9], v[160:163], v[220:223], v[6:9]
	v_mfma_f32_16x16x32_bf16 v[0:3], v[186:189], v[220:223], v[0:3]
	s_barrier
	s_add_i32 s44, s44, 2
	s_add_u32 vcc_lo, vcc_lo, 0x100
	s_addc_u32 vcc_hi, vcc_hi, 0
	s_cmp_gt_u32 s44, 41
	s_mov_b64 s[68:69], s[72:73]
	s_cbranch_scc0 .LBB0_157
	s_and_b64 vcc, exec, s[12:13]
	s_cbranch_vccz .LBB0_160
	s_barrier

.LBB0_170:
	s_waitcnt vmcnt(0)
	v_readlane_b32 s72, v247, 5
	v_readlane_b32 s68, v247, 7
	s_mov_b64 s[4:5], 0
	v_readlane_b32 s79, v247, 4
	v_readlane_b32 s73, v247, 6
	v_readlane_b32 s69, v247, 8
	s_mov_b64 s[70:71], 0x20000000
	v_readlane_b32 s74, v247, 12
	s_setprio 0
	s_barrier
	v_readlane_b32 s24, v247, 11

.LBB0_176:
	s_cmpk_gt_i32 s2, 0x17f
	v_readfirstlane_b32 s44, v241
	s_cbranch_scc1 .LBB0_196
	s_and_b64 s[0:1], s[8:9], exec
	s_movk_i32 s0, 0x800
	v_lshlrev_b32_e32 v0, 4, v241
	s_cselect_b32 s65, s0, 0x1600
	s_ashr_i32 s45, s44, 6
	v_add_u32_e32 v1, 0x2000, v0
	s_ashr_i32 s68, s44, 8
	s_lshl_b32 s20, s65, 8
	s_lshl_b32 s1, s65, 9
	s_lshl_b32 s3, s45, 10
	v_ashrrev_i32_e32 v2, 31, v1
	s_add_u32 s0, s56, 0x1a000000
	v_lshrrev_b32_e32 v2, 22, v2
	s_addc_u32 s15, s57, 0
	v_add_u32_e32 v2, v1, v2
	s_and_b64 s[18:19], s[8:9], exec
	v_ashrrev_i32_e32 v2, 10, v2
	s_cselect_b32 s18, s6, s0
	s_mov_b32 s0, 0x3400000
	v_mul_i32_i24_e32 v3, 0x400, v2
	s_cselect_b32 s0, s0, 0x9c00000
	v_sub_u32_e32 v1, v1, v3
	s_cselect_b32 s15, s7, s15
	s_add_u32 s0, s56, s0
	v_lshrrev_b32_e32 v3, 4, v1
	s_addc_u32 s25, s57, 0
	v_bitop3_b32 v1, v3, v1, 32 bitop3:0x6c
	s_and_b64 s[6:7], s[8:9], exec
	v_ashrrev_i32_e32 v3, 31, v1
	s_mov_b32 s6, 0x400000
	v_lshrrev_b32_e32 v3, 26, v3
	s_cselect_b32 s19, s6, 0xb00000
	s_and_b64 s[6:7], s[62:63], exec
	v_add_u32_e32 v3, v1, v3
	v_lshlrev_b32_e32 v6, 3, v2
	s_cselect_b32 s6, s19, 0
	v_ashrrev_i32_e32 v5, 6, v3
	v_and_b32_e32 v6, -16, v6
	v_lshlrev_b32_e32 v2, 5, v2
	s_lshl_b32 s6, s6, 1
	v_add_u32_e32 v6, v5, v6
	v_and_b32_e32 v18, 32, v2
	v_and_b32_e32 v2, 0xc0, v3
	s_add_u32 s19, s0, s6
	v_and_b32_e32 v5, 3, v5
	s_mov_b32 s0, 0x7fffffe0
	v_lshrrev_b32_e32 v7, 2, v6
	v_lshlrev_b32_e32 v8, 1, v6
	v_sub_u32_e32 v1, v1, v2
	v_and_or_b32 v5, v6, s0, v5
	v_and_b32_e32 v7, 4, v7
	v_and_b32_e32 v8, 24, v8
	v_ashrrev_i16_sdwa v1, v240, sext(v1) dst_sel:DWORD dst_unused:UNUSED_PAD src0_sel:DWORD src1_sel:BYTE_0
	v_or3_b32 v5, v5, v7, v8
	v_bfe_i32 v19, v1, 0, 16
	v_mul_lo_u32 v5, s65, v5
	v_add_u32_e32 v1, v18, v19
	v_mul_lo_u32 v20, s65, v6
	v_add_lshl_u32 v170, v5, v1, 1
	v_add_lshl_u32 v172, v20, v1, 1
	v_bfe_i32 v1, v241, 27, 1
	v_lshrrev_b32_e32 v1, 22, v1
	v_add_u32_e32 v1, v0, v1
	v_and_b32_e32 v1, 0xfffffc00, v1
	v_sub_u32_e32 v0, v0, v1
	v_lshrrev_b32_e32 v1, 4, v0
	v_ashrrev_i32_e32 v3, 31, v241
	v_bitop3_b32 v0, v1, v0, 32 bitop3:0x6c
	v_lshrrev_b32_e32 v3, 26, v3
	v_ashrrev_i32_e32 v1, 31, v0
	v_add_u32_e32 v3, v241, v3
	v_lshrrev_b32_e32 v1, 26, v1
	v_ashrrev_i32_e32 v3, 6, v3
	v_add_u32_e32 v1, v0, v1
	v_lshlrev_b32_e32 v5, 3, v3
	v_ashrrev_i32_e32 v2, 6, v1
	v_and_b32_e32 v5, -16, v5
	s_addc_u32 s25, s25, 0
	v_add_u32_e32 v5, v2, v5
	v_and_b32_e32 v2, 3, v2
	s_ashr_i32 s36, s2, 31
	v_and_or_b32 v2, v5, s0, v2
	s_lshr_b32 s0, s36, 29
	s_add_i32 s0, s2, s0
	s_ashr_i32 s6, s0, 3
	s_and_b32 s0, s0, -8
	s_sub_i32 s0, s2, s0
	s_cmp_lt_i32 s0, 0
	s_cselect_b32 s7, 49, 48
	s_mul_i32 s0, s0, s7
	s_add_i32 s0, s0, s6
	s_mul_hi_i32 s6, s0, 0x2aaaaaab
	s_lshr_b32 s7, s6, 31
	s_ashr_i32 s6, s6, 3
	s_add_i32 s6, s6, s7
	s_mul_i32 s7, s6, 6
	s_mul_i32 s6, s6, 48
	s_sub_i32 s0, s0, s6
	s_mul_i32 s6, s0, 43
	s_bfe_u32 s37, s6, 0x1000f
	s_bfe_u32 s6, s6, 0x80008
	s_add_i32 s6, s6, s37
	s_mul_i32 s37, s6, 6
	s_sub_i32 s0, s0, s37
	s_sext_i32_i8 s0, s0
	s_add_i32 s0, s7, s0
	v_and_b32_e32 v1, 0xc0, v1
	s_mul_hi_i32 s7, s1, s0
	v_lshrrev_b32_e32 v6, 2, v5
	v_lshlrev_b32_e32 v7, 1, v5
	v_sub_u32_e32 v0, v0, v1
	s_bfe_i64 s[38:39], s[6:7], 0x80000
	v_and_b32_e32 v6, 4, v6
	v_and_b32_e32 v7, 24, v7
	v_lshlrev_b32_e32 v3, 5, v3
	v_ashrrev_i16_sdwa v0, v240, sext(v0) dst_sel:DWORD dst_unused:UNUSED_PAD src0_sel:DWORD src1_sel:BYTE_0
	s_mul_hi_i32 s37, s1, s38
	s_mul_i32 s38, s1, s38
	s_mov_b32 s24, s74
	v_or3_b32 v2, v2, v6, v7
	v_and_b32_e32 v21, 32, v3
	v_bfe_i32 v22, v0, 0, 16
	s_add_u32 s74, s19, s38
	v_mul_lo_u32 v2, s65, v2
	v_add_u32_e32 v0, v21, v22
	s_addc_u32 s75, s25, s37
	s_add_i32 s37, s3, 0
	v_add_lshl_u32 v174, v2, v0, 1
	s_add_i32 m0, s37, 0x10000
	s_mul_i32 s40, s1, s0
	global_load_lds_dwordx4 v174, s[74:75]
	s_add_i32 m0, s37, 0x12000
	s_add_u32 s38, s74, s20
	global_load_lds_dwordx4 v170, s[74:75]
	s_addc_u32 s39, s75, 0
	s_add_i32 m0, s37, 0x14000
	v_mov_b32_e32 v175, v4
	global_load_lds_dwordx4 v174, s[38:39]
	s_add_i32 m0, s37, 0x16000
	v_mov_b32_e32 v171, v4
	s_add_u32 s72, s18, s40
	v_mul_lo_u32 v23, s65, v5
	v_lshl_add_u64 v[6:7], s[38:39], 0, v[174:175]
	v_lshl_add_u64 v[8:9], s[38:39], 0, v[170:171]
	global_load_lds_dwordx4 v170, s[38:39]
	s_addc_u32 s73, s15, s7
	s_add_i32 s38, s37, 0x2000
	v_add_lshl_u32 v176, v23, v0, 1
	s_mov_b32 m0, s37
	s_add_u32 s46, s72, s20
	global_load_lds_dwordx4 v176, s[72:73]
	s_mov_b32 m0, s38
	s_addc_u32 s47, s73, 0
	s_add_i32 s39, s37, 0x4000
	global_load_lds_dwordx4 v172, s[72:73]
	s_mov_b32 m0, s39
	s_add_i32 s40, s37, 0x6000
	global_load_lds_dwordx4 v176, s[46:47]
	s_mov_b32 m0, s40
	v_mov_b32_e32 v177, v4
	global_load_lds_dwordx4 v172, s[46:47]
	v_mov_b32_e32 v173, v4
	s_cmp_eq_u32 s68, 1
	v_lshl_add_u64 v[0:1], s[74:75], 0, v[174:175]
	v_lshl_add_u64 v[2:3], s[74:75], 0, v[170:171]
	v_lshl_add_u64 v[10:11], s[72:73], 0, v[176:177]
	v_lshl_add_u64 v[12:13], s[72:73], 0, v[172:173]
	s_cselect_b64 s[66:67], -1, 0
	s_cmp_lg_u32 s68, 1
	s_cbranch_scc1 .LBB0_179
	s_setprio 1
	s_barrier

.LBB0_189:
	s_add_i32 s45, s44, 2
	s_add_u32 s46, s72, 0x80
	s_addc_u32 s47, s73, 0
	s_add_i32 s86, 0, 0x10000
	s_cmp_eq_u32 s78, s44
	s_cselect_b32 s75, s9, s47
	s_cselect_b32 s74, s8, s46
	s_cselect_b32 s47, s71, s85
	s_cselect_b32 s46, s70, s83
	s_add_i32 s44, 0, 0x14000
	v_add_u32_e32 v146, s86, v150
	v_add_u32_e32 v186, s44, v150
	ds_read_b128 v[130:133], v146
	ds_read_b128 v[134:137], v146 offset:1024
	ds_read_b128 v[138:141], v146 offset:2048
	ds_read_b128 v[146:149], v146 offset:3072
	ds_read_b128 v[156:159], v186
	ds_read_b128 v[160:163], v186 offset:1024
	ds_read_b128 v[182:185], v186 offset:2048
	ds_read_b128 v[190:193], v186 offset:3072
	v_lshl_add_u64 v[186:187], s[72:73], 0, v[178:179]
	s_add_i32 m0, s37, 0xc000
	ds_read_b128 v[194:197], v188
	ds_read_b128 v[198:201], v188 offset:1024
	ds_read_b128 v[202:205], v188 offset:2048
	ds_read_b128 v[206:209], v188 offset:3072
	ds_read_b128 v[210:213], v188 offset:4096
	ds_read_b128 v[214:217], v188 offset:5120
	ds_read_b128 v[218:221], v188 offset:6144
	ds_read_b128 v[222:225], v188 offset:7168
	global_load_lds_dwordx4 v[186:187], off
	v_lshl_add_u64 v[186:187], s[72:73], 0, v[180:181]
	s_add_i32 m0, s37, 0xe000
	s_nop 0
	global_load_lds_dwordx4 v[186:187], off
	s_waitcnt vmcnt(8)
	s_waitcnt lgkmcnt(0)
	s_barrier
	s_waitcnt lgkmcnt(0)
	v_mfma_f32_16x16x32_bf16 v[142:145], v[130:133], v[194:197], v[142:145]
	v_mfma_f32_16x16x32_bf16 v[126:129], v[138:141], v[194:197], v[126:129]
	v_mfma_f32_16x16x32_bf16 v[114:117], v[130:133], v[202:205], v[114:117]
	v_mfma_f32_16x16x32_bf16 v[110:113], v[138:141], v[202:205], v[110:113]
	v_mfma_f32_16x16x32_bf16 v[98:101], v[130:133], v[210:213], v[98:101]
	v_mfma_f32_16x16x32_bf16 v[94:97], v[138:141], v[210:213], v[94:97]
	v_mfma_f32_16x16x32_bf16 v[82:85], v[130:133], v[218:221], v[82:85]
	v_mfma_f32_16x16x32_bf16 v[78:81], v[138:141], v[218:221], v[78:81]
	v_mfma_f32_16x16x32_bf16 v[142:145], v[134:137], v[198:201], v[142:145]
	v_mfma_f32_16x16x32_bf16 v[126:129], v[146:149], v[198:201], v[126:129]
	v_mfma_f32_16x16x32_bf16 v[114:117], v[134:137], v[206:209], v[114:117]
	v_mfma_f32_16x16x32_bf16 v[110:113], v[146:149], v[206:209], v[110:113]
	v_mfma_f32_16x16x32_bf16 v[98:101], v[134:137], v[214:217], v[98:101]
	v_mfma_f32_16x16x32_bf16 v[94:97], v[146:149], v[214:217], v[94:97]
	v_mfma_f32_16x16x32_bf16 v[82:85], v[134:137], v[222:225], v[82:85]
	v_mfma_f32_16x16x32_bf16 v[78:81], v[146:149], v[222:225], v[78:81]
	v_mfma_f32_16x16x32_bf16 v[122:125], v[156:159], v[194:197], v[122:125]
	v_mfma_f32_16x16x32_bf16 v[118:121], v[182:185], v[194:197], v[118:121]
	v_mfma_f32_16x16x32_bf16 v[106:109], v[156:159], v[202:205], v[106:109]
	v_mfma_f32_16x16x32_bf16 v[102:105], v[182:185], v[202:205], v[102:105]
	v_mfma_f32_16x16x32_bf16 v[90:93], v[156:159], v[210:213], v[90:93]
	v_mfma_f32_16x16x32_bf16 v[86:89], v[182:185], v[210:213], v[86:89]
	v_mfma_f32_16x16x32_bf16 v[74:77], v[156:159], v[218:221], v[74:77]
	v_mfma_f32_16x16x32_bf16 v[70:73], v[182:185], v[218:221], v[70:73]
	v_mfma_f32_16x16x32_bf16 v[122:125], v[160:163], v[198:201], v[122:125]
	v_mfma_f32_16x16x32_bf16 v[118:121], v[190:193], v[198:201], v[118:121]
	v_mfma_f32_16x16x32_bf16 v[106:109], v[160:163], v[206:209], v[106:109]
	v_mfma_f32_16x16x32_bf16 v[102:105], v[190:193], v[206:209], v[102:105]
	v_mfma_f32_16x16x32_bf16 v[90:93], v[160:163], v[214:217], v[90:93]
	v_mfma_f32_16x16x32_bf16 v[86:89], v[190:193], v[214:217], v[86:89]
	v_mfma_f32_16x16x32_bf16 v[74:77], v[160:163], v[222:225], v[74:77]
	v_mfma_f32_16x16x32_bf16 v[70:73], v[190:193], v[222:225], v[70:73]
	s_barrier
	s_add_i32 s86, s86, s3
	v_lshl_add_u64 v[186:187], s[46:47], 0, v[174:175]
	s_mov_b32 m0, s86
	ds_read_b128 v[194:197], v188 offset:16384
	ds_read_b128 v[198:201], v188 offset:17408
	ds_read_b128 v[202:205], v188 offset:18432
	ds_read_b128 v[206:209], v188 offset:19456
	ds_read_b128 v[210:213], v188 offset:20480
	ds_read_b128 v[214:217], v188 offset:21504
	ds_read_b128 v[218:221], v188 offset:22528
	ds_read_b128 v[222:225], v188 offset:23552
	global_load_lds_dwordx4 v[186:187], off
	s_add_i32 m0, s86, 0x2000
	v_lshl_add_u64 v[226:227], s[46:47], 0, v[170:171]
	s_add_u32 s46, s46, s20
	s_addc_u32 s47, s47, 0
	s_add_i32 s44, s44, s3
	global_load_lds_dwordx4 v[226:227], off
	v_lshl_add_u64 v[228:229], s[46:47], 0, v[174:175]
	s_mov_b32 m0, s44
	v_lshl_add_u64 v[230:231], s[46:47], 0, v[170:171]
	global_load_lds_dwordx4 v[228:229], off
	s_add_i32 m0, s44, 0x2000
	v_lshl_add_u64 v[232:233], s[74:75], 0, v[176:177]
	global_load_lds_dwordx4 v[230:231], off
	s_mov_b32 m0, s37
	v_lshl_add_u64 v[234:235], s[74:75], 0, v[172:173]
	global_load_lds_dwordx4 v[232:233], off
	s_mov_b32 m0, s38
	s_nop 0
	global_load_lds_dwordx4 v[234:235], off
	s_waitcnt vmcnt(8)
	s_waitcnt lgkmcnt(0)
	s_barrier
	s_waitcnt lgkmcnt(0)
	v_mfma_f32_16x16x32_bf16 v[66:69], v[130:133], v[194:197], v[66:69]
	v_mfma_f32_16x16x32_bf16 v[62:65], v[138:141], v[194:197], v[62:65]
	v_mfma_f32_16x16x32_bf16 v[50:53], v[130:133], v[202:205], v[50:53]
	v_mfma_f32_16x16x32_bf16 v[46:49], v[138:141], v[202:205], v[46:49]
	v_mfma_f32_16x16x32_bf16 v[34:37], v[130:133], v[210:213], v[34:37]
	v_mfma_f32_16x16x32_bf16 v[30:33], v[138:141], v[210:213], v[30:33]
	v_mfma_f32_16x16x32_bf16 v[18:21], v[130:133], v[218:221], v[18:21]
	v_mfma_f32_16x16x32_bf16 v[10:13], v[138:141], v[218:221], v[10:13]
	v_mfma_f32_16x16x32_bf16 v[66:69], v[134:137], v[198:201], v[66:69]
	v_mfma_f32_16x16x32_bf16 v[62:65], v[146:149], v[198:201], v[62:65]
	v_mfma_f32_16x16x32_bf16 v[50:53], v[134:137], v[206:209], v[50:53]
	v_mfma_f32_16x16x32_bf16 v[46:49], v[146:149], v[206:209], v[46:49]
	v_mfma_f32_16x16x32_bf16 v[34:37], v[134:137], v[214:217], v[34:37]
	v_mfma_f32_16x16x32_bf16 v[30:33], v[146:149], v[214:217], v[30:33]
	v_mfma_f32_16x16x32_bf16 v[18:21], v[134:137], v[222:225], v[18:21]
	v_mfma_f32_16x16x32_bf16 v[10:13], v[146:149], v[222:225], v[10:13]
	v_mfma_f32_16x16x32_bf16 v[58:61], v[156:159], v[194:197], v[58:61]
	v_mfma_f32_16x16x32_bf16 v[54:57], v[182:185], v[194:197], v[54:57]
	v_mfma_f32_16x16x32_bf16 v[42:45], v[156:159], v[202:205], v[42:45]
	v_mfma_f32_16x16x32_bf16 v[38:41], v[182:185], v[202:205], v[38:41]
	v_mfma_f32_16x16x32_bf16 v[26:29], v[156:159], v[210:213], v[26:29]
	v_mfma_f32_16x16x32_bf16 v[22:25], v[182:185], v[210:213], v[22:25]
	v_mfma_f32_16x16x32_bf16 v[6:9], v[156:159], v[218:221], v[6:9]
	v_mfma_f32_16x16x32_bf16 v[0:3], v[182:185], v[218:221], v[0:3]
	v_mfma_f32_16x16x32_bf16 v[58:61], v[160:163], v[198:201], v[58:61]
	v_mfma_f32_16x16x32_bf16 v[54:57], v[190:193], v[198:201], v[54:57]
	v_mfma_f32_16x16x32_bf16 v[42:45], v[160:163], v[206:209], v[42:45]
	v_mfma_f32_16x16x32_bf16 v[38:41], v[190:193], v[206:209], v[38:41]
	v_mfma_f32_16x16x32_bf16 v[26:29], v[160:163], v[214:217], v[26:29]
	v_mfma_f32_16x16x32_bf16 v[22:25], v[190:193], v[214:217], v[22:25]
	v_mfma_f32_16x16x32_bf16 v[6:9], v[160:163], v[222:225], v[6:9]
	v_mfma_f32_16x16x32_bf16 v[0:3], v[190:193], v[222:225], v[0:3]
	s_barrier
	s_add_i32 s44, 0, 0x18000
	s_add_i32 s86, 0, 0x1c000
	v_add_u32_e32 v146, s44, v150
	v_add_u32_e32 v189, s86, v150
	ds_read_b128 v[130:133], v146
	ds_read_b128 v[134:137], v146 offset:1024
	ds_read_b128 v[138:141], v146 offset:2048
	ds_read_b128 v[146:149], v146 offset:3072
	ds_read_b128 v[156:159], v189
	ds_read_b128 v[160:163], v189 offset:1024
	ds_read_b128 v[182:185], v189 offset:2048
	ds_read_b128 v[190:193], v189 offset:3072
	s_add_u32 s46, s74, s20
	s_addc_u32 s47, s75, 0
	s_mov_b32 m0, s39
	v_lshl_add_u64 v[242:243], s[46:47], 0, v[176:177]
	ds_read_b128 v[194:197], v188 offset:32768
	ds_read_b128 v[198:201], v188 offset:33792
	ds_read_b128 v[202:205], v188 offset:34816
	ds_read_b128 v[206:209], v188 offset:35840
	ds_read_b128 v[210:213], v188 offset:36864
	ds_read_b128 v[214:217], v188 offset:37888
	ds_read_b128 v[218:221], v188 offset:38912
	ds_read_b128 v[222:225], v188 offset:39936
	global_load_lds_dwordx4 v[242:243], off
	v_lshl_add_u64 v[242:243], s[46:47], 0, v[172:173]
	s_mov_b32 m0, s40
	s_nop 0
	global_load_lds_dwordx4 v[242:243], off
	s_waitcnt vmcnt(8)
	s_waitcnt lgkmcnt(0)
	s_barrier
	s_waitcnt lgkmcnt(0)
	v_mfma_f32_16x16x32_bf16 v[142:145], v[130:133], v[194:197], v[142:145]
	v_mfma_f32_16x16x32_bf16 v[126:129], v[138:141], v[194:197], v[126:129]
	v_mfma_f32_16x16x32_bf16 v[114:117], v[130:133], v[202:205], v[114:117]
	v_mfma_f32_16x16x32_bf16 v[110:113], v[138:141], v[202:205], v[110:113]
	v_mfma_f32_16x16x32_bf16 v[98:101], v[130:133], v[210:213], v[98:101]
	v_mfma_f32_16x16x32_bf16 v[94:97], v[138:141], v[210:213], v[94:97]
	v_mfma_f32_16x16x32_bf16 v[82:85], v[130:133], v[218:221], v[82:85]
	v_mfma_f32_16x16x32_bf16 v[78:81], v[138:141], v[218:221], v[78:81]
	v_mfma_f32_16x16x32_bf16 v[142:145], v[134:137], v[198:201], v[142:145]
	v_mfma_f32_16x16x32_bf16 v[126:129], v[146:149], v[198:201], v[126:129]
	v_mfma_f32_16x16x32_bf16 v[114:117], v[134:137], v[206:209], v[114:117]
	v_mfma_f32_16x16x32_bf16 v[110:113], v[146:149], v[206:209], v[110:113]
	v_mfma_f32_16x16x32_bf16 v[98:101], v[134:137], v[214:217], v[98:101]
	v_mfma_f32_16x16x32_bf16 v[94:97], v[146:149], v[214:217], v[94:97]
	v_mfma_f32_16x16x32_bf16 v[82:85], v[134:137], v[222:225], v[82:85]
	v_mfma_f32_16x16x32_bf16 v[78:81], v[146:149], v[222:225], v[78:81]
	v_mfma_f32_16x16x32_bf16 v[122:125], v[156:159], v[194:197], v[122:125]
	v_mfma_f32_16x16x32_bf16 v[118:121], v[182:185], v[194:197], v[118:121]
	v_mfma_f32_16x16x32_bf16 v[106:109], v[156:159], v[202:205], v[106:109]
	v_mfma_f32_16x16x32_bf16 v[102:105], v[182:185], v[202:205], v[102:105]
	v_mfma_f32_16x16x32_bf16 v[90:93], v[156:159], v[210:213], v[90:93]
	v_mfma_f32_16x16x32_bf16 v[86:89], v[182:185], v[210:213], v[86:89]
	v_mfma_f32_16x16x32_bf16 v[74:77], v[156:159], v[218:221], v[74:77]
	v_mfma_f32_16x16x32_bf16 v[70:73], v[182:185], v[218:221], v[70:73]
	v_mfma_f32_16x16x32_bf16 v[122:125], v[160:163], v[198:201], v[122:125]
	v_mfma_f32_16x16x32_bf16 v[118:121], v[190:193], v[198:201], v[118:121]
	v_mfma_f32_16x16x32_bf16 v[106:109], v[160:163], v[206:209], v[106:109]
	v_mfma_f32_16x16x32_bf16 v[102:105], v[190:193], v[206:209], v[102:105]
	v_mfma_f32_16x16x32_bf16 v[90:93], v[160:163], v[214:217], v[90:93]
	v_mfma_f32_16x16x32_bf16 v[86:89], v[190:193], v[214:217], v[86:89]
	v_mfma_f32_16x16x32_bf16 v[74:77], v[160:163], v[222:225], v[74:77]
	v_mfma_f32_16x16x32_bf16 v[70:73], v[190:193], v[222:225], v[70:73]
	s_barrier
	s_add_i32 s44, s44, s3
	v_lshl_add_u64 v[186:187], v[186:187], 0, s[30:31]
	s_mov_b32 m0, s44
	ds_read_b128 v[194:197], v188 offset:49152
	ds_read_b128 v[198:201], v188 offset:50176
	ds_read_b128 v[202:205], v188 offset:51200
	ds_read_b128 v[206:209], v188 offset:52224
	ds_read_b128 v[210:213], v188 offset:53248
	ds_read_b128 v[214:217], v188 offset:54272
	ds_read_b128 v[218:221], v188 offset:55296
	ds_read_b128 v[222:225], v188 offset:56320
	global_load_lds_dwordx4 v[186:187], off
	v_lshl_add_u64 v[186:187], v[226:227], 0, s[30:31]
	s_add_i32 m0, s44, 0x2000
	s_add_i32 s44, s86, s3
	global_load_lds_dwordx4 v[186:187], off
	v_lshl_add_u64 v[186:187], v[228:229], 0, s[30:31]
	s_mov_b32 m0, s44
	s_nop 0
	global_load_lds_dwordx4 v[186:187], off
	v_lshl_add_u64 v[186:187], v[230:231], 0, s[30:31]
	s_add_i32 m0, s44, 0x2000
	s_nop 0
	global_load_lds_dwordx4 v[186:187], off
	v_lshl_add_u64 v[186:187], v[232:233], 0, s[30:31]
	s_mov_b32 m0, s76
	s_nop 0
	global_load_lds_dwordx4 v[186:187], off
	v_lshl_add_u64 v[186:187], v[234:235], 0, s[30:31]
	s_mov_b32 m0, s77
	s_nop 0
	global_load_lds_dwordx4 v[186:187], off
	s_waitcnt vmcnt(8)
	s_waitcnt lgkmcnt(0)
	s_barrier
	s_waitcnt lgkmcnt(0)
	v_mfma_f32_16x16x32_bf16 v[66:69], v[130:133], v[194:197], v[66:69]
	v_mfma_f32_16x16x32_bf16 v[62:65], v[138:141], v[194:197], v[62:65]
	v_mfma_f32_16x16x32_bf16 v[50:53], v[130:133], v[202:205], v[50:53]
	v_mfma_f32_16x16x32_bf16 v[46:49], v[138:141], v[202:205], v[46:49]
	v_mfma_f32_16x16x32_bf16 v[34:37], v[130:133], v[210:213], v[34:37]
	v_mfma_f32_16x16x32_bf16 v[30:33], v[138:141], v[210:213], v[30:33]
	v_mfma_f32_16x16x32_bf16 v[18:21], v[130:133], v[218:221], v[18:21]
	v_mfma_f32_16x16x32_bf16 v[10:13], v[138:141], v[218:221], v[10:13]
	v_mfma_f32_16x16x32_bf16 v[66:69], v[134:137], v[198:201], v[66:69]
	v_mfma_f32_16x16x32_bf16 v[62:65], v[146:149], v[198:201], v[62:65]
	v_mfma_f32_16x16x32_bf16 v[50:53], v[134:137], v[206:209], v[50:53]
	v_mfma_f32_16x16x32_bf16 v[46:49], v[146:149], v[206:209], v[46:49]
	v_mfma_f32_16x16x32_bf16 v[34:37], v[134:137], v[214:217], v[34:37]
	v_mfma_f32_16x16x32_bf16 v[30:33], v[146:149], v[214:217], v[30:33]
	v_mfma_f32_16x16x32_bf16 v[18:21], v[134:137], v[222:225], v[18:21]
	v_mfma_f32_16x16x32_bf16 v[10:13], v[146:149], v[222:225], v[10:13]
	v_mfma_f32_16x16x32_bf16 v[58:61], v[156:159], v[194:197], v[58:61]
	v_mfma_f32_16x16x32_bf16 v[54:57], v[182:185], v[194:197], v[54:57]
	v_mfma_f32_16x16x32_bf16 v[42:45], v[156:159], v[202:205], v[42:45]
	v_mfma_f32_16x16x32_bf16 v[38:41], v[182:185], v[202:205], v[38:41]
	v_mfma_f32_16x16x32_bf16 v[26:29], v[156:159], v[210:213], v[26:29]
	v_mfma_f32_16x16x32_bf16 v[22:25], v[182:185], v[210:213], v[22:25]
	v_mfma_f32_16x16x32_bf16 v[6:9], v[156:159], v[218:221], v[6:9]
	v_mfma_f32_16x16x32_bf16 v[0:3], v[182:185], v[218:221], v[0:3]
	v_mfma_f32_16x16x32_bf16 v[58:61], v[160:163], v[198:201], v[58:61]
	v_mfma_f32_16x16x32_bf16 v[54:57], v[190:193], v[198:201], v[54:57]
	v_mfma_f32_16x16x32_bf16 v[42:45], v[160:163], v[206:209], v[42:45]
	v_mfma_f32_16x16x32_bf16 v[38:41], v[190:193], v[206:209], v[38:41]
	v_mfma_f32_16x16x32_bf16 v[26:29], v[160:163], v[214:217], v[26:29]
	v_mfma_f32_16x16x32_bf16 v[22:25], v[190:193], v[214:217], v[22:25]
	v_mfma_f32_16x16x32_bf16 v[6:9], v[160:163], v[222:225], v[6:9]
	v_mfma_f32_16x16x32_bf16 v[0:3], v[190:193], v[222:225], v[0:3]
	s_barrier
	s_add_u32 s72, s72, 0x100
	s_addc_u32 s73, s73, 0
	s_add_u32 s83, s83, 0x100
	s_addc_u32 s85, s85, 0
	s_cmp_ge_u32 s45, s65
	s_mov_b32 s44, s45
	s_cbranch_scc0 .LBB0_189
	s_and_b64 vcc, exec, s[68:69]
	s_cbranch_vccz .LBB0_192
	s_barrier

.LBB0_195:
	s_waitcnt vmcnt(0)
	v_readlane_b32 s72, v247, 5
	v_readlane_b32 s68, v247, 7
	v_readlane_b32 s79, v247, 4
	v_readlane_b32 s73, v247, 6
	v_readlane_b32 s69, v247, 8
	s_mov_b64 s[70:71], 0x20000000
	s_mov_b32 s74, s24
	s_setprio 0
	s_barrier

.LBB0_233:
	s_mul_i32 s0, s0, s14
	s_add_i32 s84, s84, -2
	s_add_i32 s38, s0, s2
	s_lshl_b32 s36, s14, 3
	s_cmp_lg_u32 s84, 0
	s_cselect_b64 s[66:67], -1, 0
	s_cmp_eq_u32 s84, 0
	s_cselect_b64 s[68:69], -1, 0
	s_and_b64 s[0:1], s[68:69], exec
	s_movk_i32 s0, 0x500
	s_cselect_b32 s37, s0, 0x300
	s_setprio 1
	s_cmp_ge_i32 s38, s37
	s_cbranch_scc1 .LBB0_331
	s_add_u32 s70, s56, 0x1a000000
	s_addc_u32 s71, s57, 0
	s_add_u32 s72, s56, 0xa00000
	s_addc_u32 s73, s57, 0
	s_add_u32 s74, s56, 0xb00000
	s_mul_i32 s0, s43, 0x1100
	s_addc_u32 s75, s57, 0
	s_add_i32 s3, s0, 0
	s_and_b64 s[0:1], s[62:63], exec
	s_cselect_b32 s6, 0x80, 0
	s_cmp_eq_u32 s84, 1
	s_cselect_b64 s[76:77], -1, 0
	s_and_b64 s[0:1], s[62:63], exec
	v_lshrrev_b32_e32 v13, 4, v168
	v_mov_b32_e32 v6, s3
	s_movk_i32 s1, 0x440
	v_and_b32_e32 v12, 15, v241
	s_cselect_b32 s0, 2, 0
	v_mad_u32_u24 v8, v13, s1, v6
	s_movk_i32 s1, 0x110
	s_and_b32 s39, s38, 1
	v_mad_u32_u24 v9, v12, s1, v6
	s_lshl_b32 s1, s39, 6
	s_or_b32 s64, s1, s6
	s_or_b32 s65, s39, 2
	s_or_b32 s40, s39, 4
	s_mul_i32 s1, s39, 0x3000000
	s_add_u32 s1, s56, s1
	s_waitcnt lgkmcnt(0)
	s_load_dwordx4 s[8:11], s[58:59], 0x70
	s_addc_u32 s3, s57, 0
	s_add_u32 s78, s1, 0x20000000
	s_addc_u32 s79, s3, 0
	v_lshlrev_b32_e32 v142, 3, v13
	s_cmp_eq_u32 s39, 0
	v_lshlrev_b32_e32 v0, 2, v13
	v_lshlrev_b32_e32 v1, 6, v12
	v_and_b32_e32 v2, 8, v142
	v_lshlrev_b32_e32 v3, 2, v12
	v_and_b32_e32 v5, 48, v241
	s_cselect_b64 s[6:7], -1, 0
	s_or_b32 s0, s0, s39
	v_and_b32_e32 v6, 48, v168
	v_mov_b32_e32 v7, v4
	v_mov_b64_e32 v[252:253], 0x840
	v_cmp_gt_u32_e64 s[4:5], 32, v168
	v_bfe_u32 v143, v241, 2, 2
	v_and_b32_e32 v153, 3, v241
	s_waitcnt lgkmcnt(0)
	v_lshl_add_u64 v[144:145], s[8:9], 0, v[6:7]
	v_lshl_add_u64 v[146:147], s[10:11], 0, v[6:7]
	v_bitop3_b32 v242, v241, 3, v241 bitop3:0x3f
	s_lshl_b32 s41, s0, 1
	v_lshlrev_b32_e32 v243, 2, v1
	v_lshlrev_b32_e32 v148, 1, v2
	v_lshlrev_b32_e32 v170, 2, v0
	v_add_u32_e32 v244, v8, v3
	v_add_u32_e32 v245, v9, v5
	s_branch .LBB0_236

.Lsc_loop:
	global_load_dwordx2 v[106:107], v[130:131], off
	v_lshl_add_u64 v[130:131], v[130:131], 0, s[86:87]
	global_load_dwordx2 v[108:109], v[130:131], off
	v_lshl_add_u64 v[130:131], v[130:131], 0, s[86:87]
	global_load_dwordx2 v[110:111], v[130:131], off
	v_lshl_add_u64 v[130:131], v[130:131], 0, s[86:87]
	global_load_dwordx2 v[112:113], v[130:131], off
	v_lshl_add_u64 v[130:131], v[130:131], 0, s[86:87]
	v_mfma_f32_16x16x16_bf16 v[50:53], v[84:85], v[114:115], v[212:215]
	v_fmac_f32_e32 v18, v232, v228
	v_fmac_f32_e32 v22, v220, v224
	v_fmac_f32_e32 v26, v233, v229
	v_fmac_f32_e32 v30, v221, v225
	v_mfma_f32_16x16x16_bf16 v[54:57], v[84:85], v[116:117], v[212:215]
	v_fmac_f32_e32 v34, v234, v230
	v_fmac_f32_e32 v38, v222, v226
	v_fmac_f32_e32 v42, v235, v231
	v_fmac_f32_e32 v46, v223, v227
	v_mfma_f32_16x16x16_bf16 v[58:61], v[84:85], v[118:119], v[212:215]
	v_fma_f32 v224, v216, v224, v18
	v_fma_f32 v228, v216, v228, v22
	v_fma_f32 v225, v217, v225, v26
	v_fma_f32 v229, v217, v229, v30
	v_mfma_f32_16x16x16_bf16 v[62:65], v[84:85], v[120:121], v[212:215]
	v_fma_f32 v226, v218, v226, v34
	v_fma_f32 v230, v218, v230, v38
	v_fma_f32 v227, v219, v227, v42
	v_fma_f32 v231, v219, v231, v46
	s_waitcnt lgkmcnt(0)
	v_mfma_f32_16x16x32_bf16 v[204:207], v[172:175], v[188:191], v[212:215]
	v_cvt_pk_bf16_f32 v136, v224, v228
	v_cvt_pk_bf16_f32 v137, v225, v229
	v_mfma_f32_16x16x32_bf16 v[208:211], v[176:179], v[192:195], v[212:215]
	v_cvt_pk_bf16_f32 v138, v226, v230
	v_cvt_pk_bf16_f32 v139, v227, v231
	ds_write2_b32 v134, v136, v137 offset0:0 offset1:16
	ds_write2_b32 v134, v138, v139 offset0:32 offset1:48
	v_mfma_f32_16x16x16_bf16 v[66:69], v[84:85], v[122:123], v[212:215]
	v_fmac_f32_e32 v19, v232, v228
	v_fmac_f32_e32 v23, v220, v224
	v_fmac_f32_e32 v27, v233, v229
	v_fmac_f32_e32 v31, v221, v225
	v_mfma_f32_16x16x16_bf16 v[70:73], v[84:85], v[124:125], v[212:215]
	v_fmac_f32_e32 v35, v234, v230
	v_fmac_f32_e32 v39, v222, v226
	v_fmac_f32_e32 v43, v235, v231
	v_fmac_f32_e32 v47, v223, v227
	v_mfma_f32_16x16x16_bf16 v[74:77], v[84:85], v[126:127], v[212:215]
	v_fma_f32 v224, v216, v224, v19
	v_fma_f32 v228, v216, v228, v23
	v_fma_f32 v225, v217, v225, v27
	v_fma_f32 v229, v217, v229, v31
	v_mfma_f32_16x16x16_bf16 v[78:81], v[84:85], v[128:129], v[212:215]
	v_fma_f32 v226, v218, v226, v35
	v_fma_f32 v230, v218, v230, v39
	v_fma_f32 v227, v219, v227, v43
	v_fma_f32 v231, v219, v231, v47
	v_mfma_f32_16x16x32_bf16 v[204:207], v[180:183], v[196:199], v[204:207]
	v_cvt_pk_bf16_f32 v136, v224, v228
	v_cvt_pk_bf16_f32 v137, v225, v229
	v_mfma_f32_16x16x32_bf16 v[208:211], v[184:187], v[200:203], v[208:211]
	v_cvt_pk_bf16_f32 v138, v226, v230
	v_cvt_pk_bf16_f32 v139, v227, v231
	ds_write2_b32 v134, v136, v137 offset0:68 offset1:84
	ds_write2_b32 v134, v138, v139 offset0:100 offset1:116
	v_fmac_f32_e32 v20, v232, v228
	v_fmac_f32_e32 v24, v220, v224
	v_fmac_f32_e32 v28, v233, v229
	v_fmac_f32_e32 v32, v221, v225
	v_fmac_f32_e32 v36, v234, v230
	v_fmac_f32_e32 v40, v222, v226
	v_fmac_f32_e32 v44, v235, v231
	v_fmac_f32_e32 v48, v223, v227
	v_fma_f32 v224, v216, v224, v20
	v_fma_f32 v228, v216, v228, v24
	v_fma_f32 v225, v217, v225, v28
	v_fma_f32 v229, v217, v229, v32
	v_fma_f32 v226, v218, v226, v36
	v_fma_f32 v230, v218, v230, v40
	v_fma_f32 v227, v219, v227, v44
	v_fma_f32 v231, v219, v231, v48
	v_cvt_pk_bf16_f32 v136, v224, v228
	v_cvt_pk_bf16_f32 v137, v225, v229
	v_cvt_pk_bf16_f32 v138, v226, v230
	v_cvt_pk_bf16_f32 v139, v227, v231
	ds_write2_b32 v134, v136, v137 offset0:136 offset1:152
	ds_write2_b32 v134, v138, v139 offset0:168 offset1:184
	v_fmac_f32_e32 v21, v232, v228
	v_fmac_f32_e32 v25, v220, v224
	v_fmac_f32_e32 v29, v233, v229
	v_fmac_f32_e32 v33, v221, v225
	v_fmac_f32_e32 v37, v234, v230
	v_fmac_f32_e32 v41, v222, v226
	v_fmac_f32_e32 v45, v235, v231
	v_fmac_f32_e32 v49, v223, v227
	v_fma_f32 v224, v216, v224, v21
	v_fma_f32 v228, v216, v228, v25
	v_fma_f32 v225, v217, v225, v29
	v_fma_f32 v229, v217, v229, v33
	v_fma_f32 v226, v218, v226, v37
	v_fma_f32 v230, v218, v230, v41
	v_fma_f32 v227, v219, v227, v45
	v_fma_f32 v231, v219, v231, v49
	v_cvt_pk_bf16_f32 v136, v224, v228
	v_cvt_pk_bf16_f32 v137, v225, v229
	v_cvt_pk_bf16_f32 v138, v226, v230
	v_cvt_pk_bf16_f32 v139, v227, v231
	ds_write2_b32 v134, v136, v137 offset0:204 offset1:220
	ds_write2_b32 v134, v138, v139 offset0:236 offset1:252
	s_cmp_eq_u32 s15, 0
	s_cbranch_scc1 .Lsc_skip_first
	v_add_f32_e32 v204, v204, v208
	v_add_f32_e32 v205, v205, v209
	v_add_f32_e32 v206, v206, v210
	v_add_f32_e32 v207, v207, v211
	global_store_dwordx4 v[132:133], v[204:207], off sc1
	v_lshl_add_u64 v[132:133], v[132:133], 0, s[88:89]
.Lsc_skip_first:
	s_waitcnt lgkmcnt(0)
	ds_read_b128 v[188:191], v135 offset:0
	ds_read_b128 v[192:195], v135 offset:64
	ds_read_b128 v[196:199], v135 offset:128
	ds_read_b128 v[200:203], v135 offset:192
	v_mfma_f32_16x16x16_bf16 v[18:21], v[86:87], v[114:115], v[212:215]
	v_fmac_f32_e32 v50, v232, v228
	v_fmac_f32_e32 v54, v220, v224
	v_fmac_f32_e32 v58, v233, v229
	v_fmac_f32_e32 v62, v221, v225
	v_mfma_f32_16x16x16_bf16 v[22:25], v[86:87], v[116:117], v[212:215]
	v_fmac_f32_e32 v66, v234, v230
	v_fmac_f32_e32 v70, v222, v226
	v_fmac_f32_e32 v74, v235, v231
	v_fmac_f32_e32 v78, v223, v227
	v_mfma_f32_16x16x16_bf16 v[26:29], v[86:87], v[118:119], v[212:215]
	v_fma_f32 v224, v216, v224, v50
	v_fma_f32 v228, v216, v228, v54
	v_fma_f32 v225, v217, v225, v58
	v_fma_f32 v229, v217, v229, v62
	v_mfma_f32_16x16x16_bf16 v[30:33], v[86:87], v[120:121], v[212:215]
	v_fma_f32 v226, v218, v226, v66
	v_fma_f32 v230, v218, v230, v70
	v_fma_f32 v227, v219, v227, v74
	v_fma_f32 v231, v219, v231, v78
	s_waitcnt lgkmcnt(0)
	v_mfma_f32_16x16x32_bf16 v[204:207], v[172:175], v[188:191], v[212:215]
	v_cvt_pk_bf16_f32 v136, v224, v228
	v_cvt_pk_bf16_f32 v137, v225, v229
	v_mfma_f32_16x16x32_bf16 v[208:211], v[176:179], v[192:195], v[212:215]
	v_cvt_pk_bf16_f32 v138, v226, v230
	v_cvt_pk_bf16_f32 v139, v227, v231
	ds_write2_b32 v134, v136, v137 offset0:0 offset1:16
	ds_write2_b32 v134, v138, v139 offset0:32 offset1:48
	v_mfma_f32_16x16x16_bf16 v[34:37], v[86:87], v[122:123], v[212:215]
	v_fmac_f32_e32 v51, v232, v228
	v_fmac_f32_e32 v55, v220, v224
	v_fmac_f32_e32 v59, v233, v229
	v_fmac_f32_e32 v63, v221, v225
	v_mfma_f32_16x16x16_bf16 v[38:41], v[86:87], v[124:125], v[212:215]
	v_fmac_f32_e32 v67, v234, v230
	v_fmac_f32_e32 v71, v222, v226
	v_fmac_f32_e32 v75, v235, v231
	v_fmac_f32_e32 v79, v223, v227
	v_mfma_f32_16x16x16_bf16 v[42:45], v[86:87], v[126:127], v[212:215]
	v_fma_f32 v224, v216, v224, v51
	v_fma_f32 v228, v216, v228, v55
	v_fma_f32 v225, v217, v225, v59
	v_fma_f32 v229, v217, v229, v63
	v_mfma_f32_16x16x16_bf16 v[46:49], v[86:87], v[128:129], v[212:215]
	v_fma_f32 v226, v218, v226, v67
	v_fma_f32 v230, v218, v230, v71
	v_fma_f32 v227, v219, v227, v75
	v_fma_f32 v231, v219, v231, v79
	v_mfma_f32_16x16x32_bf16 v[204:207], v[180:183], v[196:199], v[204:207]
	v_cvt_pk_bf16_f32 v136, v224, v228
	v_cvt_pk_bf16_f32 v137, v225, v229
	v_mfma_f32_16x16x32_bf16 v[208:211], v[184:187], v[200:203], v[208:211]
	v_cvt_pk_bf16_f32 v138, v226, v230
	v_cvt_pk_bf16_f32 v139, v227, v231
	ds_write2_b32 v134, v136, v137 offset0:68 offset1:84
	ds_write2_b32 v134, v138, v139 offset0:100 offset1:116
	v_fmac_f32_e32 v52, v232, v228
	v_fmac_f32_e32 v56, v220, v224
	v_fmac_f32_e32 v60, v233, v229
	v_fmac_f32_e32 v64, v221, v225
	v_fmac_f32_e32 v68, v234, v230
	v_fmac_f32_e32 v72, v222, v226
	v_fmac_f32_e32 v76, v235, v231
	v_fmac_f32_e32 v80, v223, v227
	v_fma_f32 v224, v216, v224, v52
	v_fma_f32 v228, v216, v228, v56
	v_fma_f32 v225, v217, v225, v60
	v_fma_f32 v229, v217, v229, v64
	v_fma_f32 v226, v218, v226, v68
	v_fma_f32 v230, v218, v230, v72
	v_fma_f32 v227, v219, v227, v76
	v_fma_f32 v231, v219, v231, v80
	v_cvt_pk_bf16_f32 v136, v224, v228
	v_cvt_pk_bf16_f32 v137, v225, v229
	v_cvt_pk_bf16_f32 v138, v226, v230
	v_cvt_pk_bf16_f32 v139, v227, v231
	ds_write2_b32 v134, v136, v137 offset0:136 offset1:152
	ds_write2_b32 v134, v138, v139 offset0:168 offset1:184
	v_fmac_f32_e32 v53, v232, v228
	v_fmac_f32_e32 v57, v220, v224
	v_fmac_f32_e32 v61, v233, v229
	v_fmac_f32_e32 v65, v221, v225
	v_fmac_f32_e32 v69, v234, v230
	v_fmac_f32_e32 v73, v222, v226
	v_fmac_f32_e32 v77, v235, v231
	v_fmac_f32_e32 v81, v223, v227
	v_fma_f32 v224, v216, v224, v53
	v_fma_f32 v228, v216, v228, v57
	v_fma_f32 v225, v217, v225, v61
	v_fma_f32 v229, v217, v229, v65
	v_fma_f32 v226, v218, v226, v69
	v_fma_f32 v230, v218, v230, v73
	v_fma_f32 v227, v219, v227, v77
	v_fma_f32 v231, v219, v231, v81
	v_cvt_pk_bf16_f32 v136, v224, v228
	v_cvt_pk_bf16_f32 v137, v225, v229
	v_cvt_pk_bf16_f32 v138, v226, v230
	v_cvt_pk_bf16_f32 v139, v227, v231
	ds_write2_b32 v134, v136, v137 offset0:204 offset1:220
	ds_write2_b32 v134, v138, v139 offset0:236 offset1:252
	v_add_f32_e32 v204, v204, v208
	v_add_f32_e32 v205, v205, v209
	v_add_f32_e32 v206, v206, v210
	v_add_f32_e32 v207, v207, v211
	global_store_dwordx4 v[132:133], v[204:207], off sc1
	v_lshl_add_u64 v[132:133], v[132:133], 0, s[88:89]
	s_waitcnt lgkmcnt(0)
	ds_read_b128 v[188:191], v135 offset:0
	ds_read_b128 v[192:195], v135 offset:64
	ds_read_b128 v[196:199], v135 offset:128
	ds_read_b128 v[200:203], v135 offset:192
	v_mfma_f32_16x16x16_bf16 v[50:53], v[88:89], v[114:115], v[212:215]
	v_fmac_f32_e32 v18, v232, v228
	v_fmac_f32_e32 v22, v220, v224
	v_fmac_f32_e32 v26, v233, v229
	v_fmac_f32_e32 v30, v221, v225
	v_mfma_f32_16x16x16_bf16 v[54:57], v[88:89], v[116:117], v[212:215]
	v_fmac_f32_e32 v34, v234, v230
	v_fmac_f32_e32 v38, v222, v226
	v_fmac_f32_e32 v42, v235, v231
	v_fmac_f32_e32 v46, v223, v227
	v_mfma_f32_16x16x16_bf16 v[58:61], v[88:89], v[118:119], v[212:215]
	v_fma_f32 v224, v216, v224, v18
	v_fma_f32 v228, v216, v228, v22
	v_fma_f32 v225, v217, v225, v26
	v_fma_f32 v229, v217, v229, v30
	v_mfma_f32_16x16x16_bf16 v[62:65], v[88:89], v[120:121], v[212:215]
	v_fma_f32 v226, v218, v226, v34
	v_fma_f32 v230, v218, v230, v38
	v_fma_f32 v227, v219, v227, v42
	v_fma_f32 v231, v219, v231, v46
	s_waitcnt lgkmcnt(0)
	v_mfma_f32_16x16x32_bf16 v[204:207], v[172:175], v[188:191], v[212:215]
	v_cvt_pk_bf16_f32 v136, v224, v228
	v_cvt_pk_bf16_f32 v137, v225, v229
	v_mfma_f32_16x16x32_bf16 v[208:211], v[176:179], v[192:195], v[212:215]
	v_cvt_pk_bf16_f32 v138, v226, v230
	v_cvt_pk_bf16_f32 v139, v227, v231
	ds_write2_b32 v134, v136, v137 offset0:0 offset1:16
	ds_write2_b32 v134, v138, v139 offset0:32 offset1:48
	v_mfma_f32_16x16x16_bf16 v[66:69], v[88:89], v[122:123], v[212:215]
	v_fmac_f32_e32 v19, v232, v228
	v_fmac_f32_e32 v23, v220, v224
	v_fmac_f32_e32 v27, v233, v229
	v_fmac_f32_e32 v31, v221, v225
	v_mfma_f32_16x16x16_bf16 v[70:73], v[88:89], v[124:125], v[212:215]
	v_fmac_f32_e32 v35, v234, v230
	v_fmac_f32_e32 v39, v222, v226
	v_fmac_f32_e32 v43, v235, v231
	v_fmac_f32_e32 v47, v223, v227
	v_mfma_f32_16x16x16_bf16 v[74:77], v[88:89], v[126:127], v[212:215]
	v_fma_f32 v224, v216, v224, v19
	v_fma_f32 v228, v216, v228, v23
	v_fma_f32 v225, v217, v225, v27
	v_fma_f32 v229, v217, v229, v31
	v_mfma_f32_16x16x16_bf16 v[78:81], v[88:89], v[128:129], v[212:215]
	v_fma_f32 v226, v218, v226, v35
	v_fma_f32 v230, v218, v230, v39
	v_fma_f32 v227, v219, v227, v43
	v_fma_f32 v231, v219, v231, v47
	v_mfma_f32_16x16x32_bf16 v[204:207], v[180:183], v[196:199], v[204:207]
	v_cvt_pk_bf16_f32 v136, v224, v228
	v_cvt_pk_bf16_f32 v137, v225, v229
	v_mfma_f32_16x16x32_bf16 v[208:211], v[184:187], v[200:203], v[208:211]
	v_cvt_pk_bf16_f32 v138, v226, v230
	v_cvt_pk_bf16_f32 v139, v227, v231
	ds_write2_b32 v134, v136, v137 offset0:68 offset1:84
	ds_write2_b32 v134, v138, v139 offset0:100 offset1:116
	v_fmac_f32_e32 v20, v232, v228
	v_fmac_f32_e32 v24, v220, v224
	v_fmac_f32_e32 v28, v233, v229
	v_fmac_f32_e32 v32, v221, v225
	v_fmac_f32_e32 v36, v234, v230
	v_fmac_f32_e32 v40, v222, v226
	v_fmac_f32_e32 v44, v235, v231
	v_fmac_f32_e32 v48, v223, v227
	v_fma_f32 v224, v216, v224, v20
	v_fma_f32 v228, v216, v228, v24
	v_fma_f32 v225, v217, v225, v28
	v_fma_f32 v229, v217, v229, v32
	v_fma_f32 v226, v218, v226, v36
	v_fma_f32 v230, v218, v230, v40
	v_fma_f32 v227, v219, v227, v44
	v_fma_f32 v231, v219, v231, v48
	v_cvt_pk_bf16_f32 v136, v224, v228
	v_cvt_pk_bf16_f32 v137, v225, v229
	v_cvt_pk_bf16_f32 v138, v226, v230
	v_cvt_pk_bf16_f32 v139, v227, v231
	ds_write2_b32 v134, v136, v137 offset0:136 offset1:152
	ds_write2_b32 v134, v138, v139 offset0:168 offset1:184
	v_fmac_f32_e32 v21, v232, v228
	v_fmac_f32_e32 v25, v220, v224
	v_fmac_f32_e32 v29, v233, v229
	v_fmac_f32_e32 v33, v221, v225
	v_fmac_f32_e32 v37, v234, v230
	v_fmac_f32_e32 v41, v222, v226
	v_fmac_f32_e32 v45, v235, v231
	v_fmac_f32_e32 v49, v223, v227
	v_fma_f32 v224, v216, v224, v21
	v_fma_f32 v228, v216, v228, v25
	v_fma_f32 v225, v217, v225, v29
	v_fma_f32 v229, v217, v229, v33
	v_fma_f32 v226, v218, v226, v37
	v_fma_f32 v230, v218, v230, v41
	v_fma_f32 v227, v219, v227, v45
	v_fma_f32 v231, v219, v231, v49
	v_cvt_pk_bf16_f32 v136, v224, v228
	v_cvt_pk_bf16_f32 v137, v225, v229
	v_cvt_pk_bf16_f32 v138, v226, v230
	v_cvt_pk_bf16_f32 v139, v227, v231
	ds_write2_b32 v134, v136, v137 offset0:204 offset1:220
	ds_write2_b32 v134, v138, v139 offset0:236 offset1:252
	v_add_f32_e32 v204, v204, v208
	v_add_f32_e32 v205, v205, v209
	v_add_f32_e32 v206, v206, v210
	v_add_f32_e32 v207, v207, v211
	global_store_dwordx4 v[132:133], v[204:207], off sc1
	v_lshl_add_u64 v[132:133], v[132:133], 0, s[88:89]
	s_waitcnt lgkmcnt(0)
	ds_read_b128 v[188:191], v135 offset:0
	ds_read_b128 v[192:195], v135 offset:64
	ds_read_b128 v[196:199], v135 offset:128
	ds_read_b128 v[200:203], v135 offset:192
	s_waitcnt vmcnt(14)
	v_mfma_f32_16x16x16_bf16 v[18:21], v[90:91], v[114:115], v[212:215]
	v_fmac_f32_e32 v50, v232, v228
	v_fmac_f32_e32 v54, v220, v224
	v_fmac_f32_e32 v58, v233, v229
	v_fmac_f32_e32 v62, v221, v225
	v_mfma_f32_16x16x16_bf16 v[22:25], v[90:91], v[116:117], v[212:215]
	v_fmac_f32_e32 v66, v234, v230
	v_fmac_f32_e32 v70, v222, v226
	v_fmac_f32_e32 v74, v235, v231
	v_fmac_f32_e32 v78, v223, v227
	v_mfma_f32_16x16x16_bf16 v[26:29], v[90:91], v[118:119], v[212:215]
	v_fma_f32 v224, v216, v224, v50
	v_fma_f32 v228, v216, v228, v54
	v_fma_f32 v225, v217, v225, v58
	v_fma_f32 v229, v217, v229, v62
	v_mfma_f32_16x16x16_bf16 v[30:33], v[90:91], v[120:121], v[212:215]
	v_fma_f32 v226, v218, v226, v66
	v_fma_f32 v230, v218, v230, v70
	v_fma_f32 v227, v219, v227, v74
	v_fma_f32 v231, v219, v231, v78
	s_waitcnt lgkmcnt(0)
	v_mfma_f32_16x16x32_bf16 v[204:207], v[172:175], v[188:191], v[212:215]
	v_cvt_pk_bf16_f32 v136, v224, v228
	v_cvt_pk_bf16_f32 v137, v225, v229
	v_mfma_f32_16x16x32_bf16 v[208:211], v[176:179], v[192:195], v[212:215]
	v_cvt_pk_bf16_f32 v138, v226, v230
	v_cvt_pk_bf16_f32 v139, v227, v231
	ds_write2_b32 v134, v136, v137 offset0:0 offset1:16
	ds_write2_b32 v134, v138, v139 offset0:32 offset1:48
	v_mfma_f32_16x16x16_bf16 v[34:37], v[90:91], v[122:123], v[212:215]
	v_fmac_f32_e32 v51, v232, v228
	v_fmac_f32_e32 v55, v220, v224
	v_fmac_f32_e32 v59, v233, v229
	v_fmac_f32_e32 v63, v221, v225
	v_mfma_f32_16x16x16_bf16 v[38:41], v[90:91], v[124:125], v[212:215]
	v_fmac_f32_e32 v67, v234, v230
	v_fmac_f32_e32 v71, v222, v226
	v_fmac_f32_e32 v75, v235, v231
	v_fmac_f32_e32 v79, v223, v227
	v_mfma_f32_16x16x16_bf16 v[42:45], v[90:91], v[126:127], v[212:215]
	v_fma_f32 v224, v216, v224, v51
	v_fma_f32 v228, v216, v228, v55
	v_fma_f32 v225, v217, v225, v59
	v_fma_f32 v229, v217, v229, v63
	v_mfma_f32_16x16x16_bf16 v[46:49], v[90:91], v[128:129], v[212:215]
	v_fma_f32 v226, v218, v226, v67
	v_fma_f32 v230, v218, v230, v71
	v_fma_f32 v227, v219, v227, v75
	v_fma_f32 v231, v219, v231, v79
	v_mfma_f32_16x16x32_bf16 v[204:207], v[180:183], v[196:199], v[204:207]
	v_cvt_pk_bf16_f32 v136, v224, v228
	v_cvt_pk_bf16_f32 v137, v225, v229
	v_mfma_f32_16x16x32_bf16 v[208:211], v[184:187], v[200:203], v[208:211]
	v_cvt_pk_bf16_f32 v138, v226, v230
	v_cvt_pk_bf16_f32 v139, v227, v231
	ds_write2_b32 v134, v136, v137 offset0:68 offset1:84
	ds_write2_b32 v134, v138, v139 offset0:100 offset1:116
	v_fmac_f32_e32 v52, v232, v228
	v_fmac_f32_e32 v56, v220, v224
	v_fmac_f32_e32 v60, v233, v229
	v_fmac_f32_e32 v64, v221, v225
	v_fmac_f32_e32 v68, v234, v230
	v_fmac_f32_e32 v72, v222, v226
	v_fmac_f32_e32 v76, v235, v231
	v_fmac_f32_e32 v80, v223, v227
	v_fma_f32 v224, v216, v224, v52
	v_fma_f32 v228, v216, v228, v56
	v_fma_f32 v225, v217, v225, v60
	v_fma_f32 v229, v217, v229, v64
	v_fma_f32 v226, v218, v226, v68
	v_fma_f32 v230, v218, v230, v72
	v_fma_f32 v227, v219, v227, v76
	v_fma_f32 v231, v219, v231, v80
	v_cvt_pk_bf16_f32 v136, v224, v228
	v_cvt_pk_bf16_f32 v137, v225, v229
	v_cvt_pk_bf16_f32 v138, v226, v230
	v_cvt_pk_bf16_f32 v139, v227, v231
	ds_write2_b32 v134, v136, v137 offset0:136 offset1:152
	ds_write2_b32 v134, v138, v139 offset0:168 offset1:184
	v_fmac_f32_e32 v53, v232, v228
	v_fmac_f32_e32 v57, v220, v224
	v_fmac_f32_e32 v61, v233, v229
	v_fmac_f32_e32 v65, v221, v225
	v_fmac_f32_e32 v69, v234, v230
	v_fmac_f32_e32 v73, v222, v226
	v_fmac_f32_e32 v77, v235, v231
	v_fmac_f32_e32 v81, v223, v227
	v_fma_f32 v224, v216, v224, v53
	v_fma_f32 v228, v216, v228, v57
	v_fma_f32 v225, v217, v225, v61
	v_fma_f32 v229, v217, v229, v65
	v_fma_f32 v226, v218, v226, v69
	v_fma_f32 v230, v218, v230, v73
	v_fma_f32 v227, v219, v227, v77
	v_fma_f32 v231, v219, v231, v81
	v_cvt_pk_bf16_f32 v136, v224, v228
	v_cvt_pk_bf16_f32 v137, v225, v229
	v_cvt_pk_bf16_f32 v138, v226, v230
	v_cvt_pk_bf16_f32 v139, v227, v231
	ds_write2_b32 v134, v136, v137 offset0:204 offset1:220
	ds_write2_b32 v134, v138, v139 offset0:236 offset1:252
	v_add_f32_e32 v204, v204, v208
	v_add_f32_e32 v205, v205, v209
	v_add_f32_e32 v206, v206, v210
	v_add_f32_e32 v207, v207, v211
	global_store_dwordx4 v[132:133], v[204:207], off sc1
	v_lshl_add_u64 v[132:133], v[132:133], 0, s[88:89]
	s_waitcnt lgkmcnt(0)
	ds_read_b128 v[188:191], v135 offset:0
	ds_read_b128 v[192:195], v135 offset:64
	ds_read_b128 v[196:199], v135 offset:128
	ds_read_b128 v[200:203], v135 offset:192
	global_load_dwordx2 v[82:83], v[130:131], off
	v_lshl_add_u64 v[130:131], v[130:131], 0, s[86:87]
	global_load_dwordx2 v[84:85], v[130:131], off
	v_lshl_add_u64 v[130:131], v[130:131], 0, s[86:87]
	global_load_dwordx2 v[86:87], v[130:131], off
	v_lshl_add_u64 v[130:131], v[130:131], 0, s[86:87]
	global_load_dwordx2 v[88:89], v[130:131], off
	v_lshl_add_u64 v[130:131], v[130:131], 0, s[86:87]
	v_mfma_f32_16x16x16_bf16 v[50:53], v[92:93], v[114:115], v[212:215]
	v_fmac_f32_e32 v18, v232, v228
	v_fmac_f32_e32 v22, v220, v224
	v_fmac_f32_e32 v26, v233, v229
	v_fmac_f32_e32 v30, v221, v225
	v_mfma_f32_16x16x16_bf16 v[54:57], v[92:93], v[116:117], v[212:215]
	v_fmac_f32_e32 v34, v234, v230
	v_fmac_f32_e32 v38, v222, v226
	v_fmac_f32_e32 v42, v235, v231
	v_fmac_f32_e32 v46, v223, v227
	v_mfma_f32_16x16x16_bf16 v[58:61], v[92:93], v[118:119], v[212:215]
	v_fma_f32 v224, v216, v224, v18
	v_fma_f32 v228, v216, v228, v22
	v_fma_f32 v225, v217, v225, v26
	v_fma_f32 v229, v217, v229, v30
	v_mfma_f32_16x16x16_bf16 v[62:65], v[92:93], v[120:121], v[212:215]
	v_fma_f32 v226, v218, v226, v34
	v_fma_f32 v230, v218, v230, v38
	v_fma_f32 v227, v219, v227, v42
	v_fma_f32 v231, v219, v231, v46
	s_waitcnt lgkmcnt(0)
	v_mfma_f32_16x16x32_bf16 v[204:207], v[172:175], v[188:191], v[212:215]
	v_cvt_pk_bf16_f32 v136, v224, v228
	v_cvt_pk_bf16_f32 v137, v225, v229
	v_mfma_f32_16x16x32_bf16 v[208:211], v[176:179], v[192:195], v[212:215]
	v_cvt_pk_bf16_f32 v138, v226, v230
	v_cvt_pk_bf16_f32 v139, v227, v231
	ds_write2_b32 v134, v136, v137 offset0:0 offset1:16
	ds_write2_b32 v134, v138, v139 offset0:32 offset1:48
	v_mfma_f32_16x16x16_bf16 v[66:69], v[92:93], v[122:123], v[212:215]
	v_fmac_f32_e32 v19, v232, v228
	v_fmac_f32_e32 v23, v220, v224
	v_fmac_f32_e32 v27, v233, v229
	v_fmac_f32_e32 v31, v221, v225
	v_mfma_f32_16x16x16_bf16 v[70:73], v[92:93], v[124:125], v[212:215]
	v_fmac_f32_e32 v35, v234, v230
	v_fmac_f32_e32 v39, v222, v226
	v_fmac_f32_e32 v43, v235, v231
	v_fmac_f32_e32 v47, v223, v227
	v_mfma_f32_16x16x16_bf16 v[74:77], v[92:93], v[126:127], v[212:215]
	v_fma_f32 v224, v216, v224, v19
	v_fma_f32 v228, v216, v228, v23
	v_fma_f32 v225, v217, v225, v27
	v_fma_f32 v229, v217, v229, v31
	v_mfma_f32_16x16x16_bf16 v[78:81], v[92:93], v[128:129], v[212:215]
	v_fma_f32 v226, v218, v226, v35
	v_fma_f32 v230, v218, v230, v39
	v_fma_f32 v227, v219, v227, v43
	v_fma_f32 v231, v219, v231, v47
	v_mfma_f32_16x16x32_bf16 v[204:207], v[180:183], v[196:199], v[204:207]
	v_cvt_pk_bf16_f32 v136, v224, v228
	v_cvt_pk_bf16_f32 v137, v225, v229
	v_mfma_f32_16x16x32_bf16 v[208:211], v[184:187], v[200:203], v[208:211]
	v_cvt_pk_bf16_f32 v138, v226, v230
	v_cvt_pk_bf16_f32 v139, v227, v231
	ds_write2_b32 v134, v136, v137 offset0:68 offset1:84
	ds_write2_b32 v134, v138, v139 offset0:100 offset1:116
	v_fmac_f32_e32 v20, v232, v228
	v_fmac_f32_e32 v24, v220, v224
	v_fmac_f32_e32 v28, v233, v229
	v_fmac_f32_e32 v32, v221, v225
	v_fmac_f32_e32 v36, v234, v230
	v_fmac_f32_e32 v40, v222, v226
	v_fmac_f32_e32 v44, v235, v231
	v_fmac_f32_e32 v48, v223, v227
	v_fma_f32 v224, v216, v224, v20
	v_fma_f32 v228, v216, v228, v24
	v_fma_f32 v225, v217, v225, v28
	v_fma_f32 v229, v217, v229, v32
	v_fma_f32 v226, v218, v226, v36
	v_fma_f32 v230, v218, v230, v40
	v_fma_f32 v227, v219, v227, v44
	v_fma_f32 v231, v219, v231, v48
	v_cvt_pk_bf16_f32 v136, v224, v228
	v_cvt_pk_bf16_f32 v137, v225, v229
	v_cvt_pk_bf16_f32 v138, v226, v230
	v_cvt_pk_bf16_f32 v139, v227, v231
	ds_write2_b32 v134, v136, v137 offset0:136 offset1:152
	ds_write2_b32 v134, v138, v139 offset0:168 offset1:184
	v_fmac_f32_e32 v21, v232, v228
	v_fmac_f32_e32 v25, v220, v224
	v_fmac_f32_e32 v29, v233, v229
	v_fmac_f32_e32 v33, v221, v225
	v_fmac_f32_e32 v37, v234, v230
	v_fmac_f32_e32 v41, v222, v226
	v_fmac_f32_e32 v45, v235, v231
	v_fmac_f32_e32 v49, v223, v227
	v_fma_f32 v224, v216, v224, v21
	v_fma_f32 v228, v216, v228, v25
	v_fma_f32 v225, v217, v225, v29
	v_fma_f32 v229, v217, v229, v33
	v_fma_f32 v226, v218, v226, v37
	v_fma_f32 v230, v218, v230, v41
	v_fma_f32 v227, v219, v227, v45
	v_fma_f32 v231, v219, v231, v49
	v_cvt_pk_bf16_f32 v136, v224, v228
	v_cvt_pk_bf16_f32 v137, v225, v229
	v_cvt_pk_bf16_f32 v138, v226, v230
	v_cvt_pk_bf16_f32 v139, v227, v231
	ds_write2_b32 v134, v136, v137 offset0:204 offset1:220
	ds_write2_b32 v134, v138, v139 offset0:236 offset1:252
	v_add_f32_e32 v204, v204, v208
	v_add_f32_e32 v205, v205, v209
	v_add_f32_e32 v206, v206, v210
	v_add_f32_e32 v207, v207, v211
	global_store_dwordx4 v[132:133], v[204:207], off sc1
	v_lshl_add_u64 v[132:133], v[132:133], 0, s[88:89]
	s_waitcnt lgkmcnt(0)
	ds_read_b128 v[188:191], v135 offset:0
	ds_read_b128 v[192:195], v135 offset:64
	ds_read_b128 v[196:199], v135 offset:128
	ds_read_b128 v[200:203], v135 offset:192
	v_mfma_f32_16x16x16_bf16 v[18:21], v[94:95], v[114:115], v[212:215]
	v_fmac_f32_e32 v50, v232, v228
	v_fmac_f32_e32 v54, v220, v224
	v_fmac_f32_e32 v58, v233, v229
	v_fmac_f32_e32 v62, v221, v225
	v_mfma_f32_16x16x16_bf16 v[22:25], v[94:95], v[116:117], v[212:215]
	v_fmac_f32_e32 v66, v234, v230
	v_fmac_f32_e32 v70, v222, v226
	v_fmac_f32_e32 v74, v235, v231
	v_fmac_f32_e32 v78, v223, v227
	v_mfma_f32_16x16x16_bf16 v[26:29], v[94:95], v[118:119], v[212:215]
	v_fma_f32 v224, v216, v224, v50
	v_fma_f32 v228, v216, v228, v54
	v_fma_f32 v225, v217, v225, v58
	v_fma_f32 v229, v217, v229, v62
	v_mfma_f32_16x16x16_bf16 v[30:33], v[94:95], v[120:121], v[212:215]
	v_fma_f32 v226, v218, v226, v66
	v_fma_f32 v230, v218, v230, v70
	v_fma_f32 v227, v219, v227, v74
	v_fma_f32 v231, v219, v231, v78
	s_waitcnt lgkmcnt(0)
	v_mfma_f32_16x16x32_bf16 v[204:207], v[172:175], v[188:191], v[212:215]
	v_cvt_pk_bf16_f32 v136, v224, v228
	v_cvt_pk_bf16_f32 v137, v225, v229
	v_mfma_f32_16x16x32_bf16 v[208:211], v[176:179], v[192:195], v[212:215]
	v_cvt_pk_bf16_f32 v138, v226, v230
	v_cvt_pk_bf16_f32 v139, v227, v231
	ds_write2_b32 v134, v136, v137 offset0:0 offset1:16
	ds_write2_b32 v134, v138, v139 offset0:32 offset1:48
	v_mfma_f32_16x16x16_bf16 v[34:37], v[94:95], v[122:123], v[212:215]
	v_fmac_f32_e32 v51, v232, v228
	v_fmac_f32_e32 v55, v220, v224
	v_fmac_f32_e32 v59, v233, v229
	v_fmac_f32_e32 v63, v221, v225
	v_mfma_f32_16x16x16_bf16 v[38:41], v[94:95], v[124:125], v[212:215]
	v_fmac_f32_e32 v67, v234, v230
	v_fmac_f32_e32 v71, v222, v226
	v_fmac_f32_e32 v75, v235, v231
	v_fmac_f32_e32 v79, v223, v227
	v_mfma_f32_16x16x16_bf16 v[42:45], v[94:95], v[126:127], v[212:215]
	v_fma_f32 v224, v216, v224, v51
	v_fma_f32 v228, v216, v228, v55
	v_fma_f32 v225, v217, v225, v59
	v_fma_f32 v229, v217, v229, v63
	v_mfma_f32_16x16x16_bf16 v[46:49], v[94:95], v[128:129], v[212:215]
	v_fma_f32 v226, v218, v226, v67
	v_fma_f32 v230, v218, v230, v71
	v_fma_f32 v227, v219, v227, v75
	v_fma_f32 v231, v219, v231, v79
	v_mfma_f32_16x16x32_bf16 v[204:207], v[180:183], v[196:199], v[204:207]
	v_cvt_pk_bf16_f32 v136, v224, v228
	v_cvt_pk_bf16_f32 v137, v225, v229
	v_mfma_f32_16x16x32_bf16 v[208:211], v[184:187], v[200:203], v[208:211]
	v_cvt_pk_bf16_f32 v138, v226, v230
	v_cvt_pk_bf16_f32 v139, v227, v231
	ds_write2_b32 v134, v136, v137 offset0:68 offset1:84
	ds_write2_b32 v134, v138, v139 offset0:100 offset1:116
	v_fmac_f32_e32 v52, v232, v228
	v_fmac_f32_e32 v56, v220, v224
	v_fmac_f32_e32 v60, v233, v229
	v_fmac_f32_e32 v64, v221, v225
	v_fmac_f32_e32 v68, v234, v230
	v_fmac_f32_e32 v72, v222, v226
	v_fmac_f32_e32 v76, v235, v231
	v_fmac_f32_e32 v80, v223, v227
	v_fma_f32 v224, v216, v224, v52
	v_fma_f32 v228, v216, v228, v56
	v_fma_f32 v225, v217, v225, v60
	v_fma_f32 v229, v217, v229, v64
	v_fma_f32 v226, v218, v226, v68
	v_fma_f32 v230, v218, v230, v72
	v_fma_f32 v227, v219, v227, v76
	v_fma_f32 v231, v219, v231, v80
	v_cvt_pk_bf16_f32 v136, v224, v228
	v_cvt_pk_bf16_f32 v137, v225, v229
	v_cvt_pk_bf16_f32 v138, v226, v230
	v_cvt_pk_bf16_f32 v139, v227, v231
	ds_write2_b32 v134, v136, v137 offset0:136 offset1:152
	ds_write2_b32 v134, v138, v139 offset0:168 offset1:184
	v_fmac_f32_e32 v53, v232, v228
	v_fmac_f32_e32 v57, v220, v224
	v_fmac_f32_e32 v61, v233, v229
	v_fmac_f32_e32 v65, v221, v225
	v_fmac_f32_e32 v69, v234, v230
	v_fmac_f32_e32 v73, v222, v226
	v_fmac_f32_e32 v77, v235, v231
	v_fmac_f32_e32 v81, v223, v227
	v_fma_f32 v224, v216, v224, v53
	v_fma_f32 v228, v216, v228, v57
	v_fma_f32 v225, v217, v225, v61
	v_fma_f32 v229, v217, v229, v65
	v_fma_f32 v226, v218, v226, v69
	v_fma_f32 v230, v218, v230, v73
	v_fma_f32 v227, v219, v227, v77
	v_fma_f32 v231, v219, v231, v81
	v_cvt_pk_bf16_f32 v136, v224, v228
	v_cvt_pk_bf16_f32 v137, v225, v229
	v_cvt_pk_bf16_f32 v138, v226, v230
	v_cvt_pk_bf16_f32 v139, v227, v231
	ds_write2_b32 v134, v136, v137 offset0:204 offset1:220
	ds_write2_b32 v134, v138, v139 offset0:236 offset1:252
	v_add_f32_e32 v204, v204, v208
	v_add_f32_e32 v205, v205, v209
	v_add_f32_e32 v206, v206, v210
	v_add_f32_e32 v207, v207, v211
	global_store_dwordx4 v[132:133], v[204:207], off sc1
	v_lshl_add_u64 v[132:133], v[132:133], 0, s[88:89]
	s_waitcnt lgkmcnt(0)
	ds_read_b128 v[188:191], v135 offset:0
	ds_read_b128 v[192:195], v135 offset:64
	ds_read_b128 v[196:199], v135 offset:128
	ds_read_b128 v[200:203], v135 offset:192
	v_mfma_f32_16x16x16_bf16 v[50:53], v[96:97], v[114:115], v[212:215]
	v_fmac_f32_e32 v18, v232, v228
	v_fmac_f32_e32 v22, v220, v224
	v_fmac_f32_e32 v26, v233, v229
	v_fmac_f32_e32 v30, v221, v225
	v_mfma_f32_16x16x16_bf16 v[54:57], v[96:97], v[116:117], v[212:215]
	v_fmac_f32_e32 v34, v234, v230
	v_fmac_f32_e32 v38, v222, v226
	v_fmac_f32_e32 v42, v235, v231
	v_fmac_f32_e32 v46, v223, v227
	v_mfma_f32_16x16x16_bf16 v[58:61], v[96:97], v[118:119], v[212:215]
	v_fma_f32 v224, v216, v224, v18
	v_fma_f32 v228, v216, v228, v22
	v_fma_f32 v225, v217, v225, v26
	v_fma_f32 v229, v217, v229, v30
	v_mfma_f32_16x16x16_bf16 v[62:65], v[96:97], v[120:121], v[212:215]
	v_fma_f32 v226, v218, v226, v34
	v_fma_f32 v230, v218, v230, v38
	v_fma_f32 v227, v219, v227, v42
	v_fma_f32 v231, v219, v231, v46
	s_waitcnt lgkmcnt(0)
	v_mfma_f32_16x16x32_bf16 v[204:207], v[172:175], v[188:191], v[212:215]
	v_cvt_pk_bf16_f32 v136, v224, v228
	v_cvt_pk_bf16_f32 v137, v225, v229
	v_mfma_f32_16x16x32_bf16 v[208:211], v[176:179], v[192:195], v[212:215]
	v_cvt_pk_bf16_f32 v138, v226, v230
	v_cvt_pk_bf16_f32 v139, v227, v231
	ds_write2_b32 v134, v136, v137 offset0:0 offset1:16
	ds_write2_b32 v134, v138, v139 offset0:32 offset1:48
	v_mfma_f32_16x16x16_bf16 v[66:69], v[96:97], v[122:123], v[212:215]
	v_fmac_f32_e32 v19, v232, v228
	v_fmac_f32_e32 v23, v220, v224
	v_fmac_f32_e32 v27, v233, v229
	v_fmac_f32_e32 v31, v221, v225
	v_mfma_f32_16x16x16_bf16 v[70:73], v[96:97], v[124:125], v[212:215]
	v_fmac_f32_e32 v35, v234, v230
	v_fmac_f32_e32 v39, v222, v226
	v_fmac_f32_e32 v43, v235, v231
	v_fmac_f32_e32 v47, v223, v227
	v_mfma_f32_16x16x16_bf16 v[74:77], v[96:97], v[126:127], v[212:215]
	v_fma_f32 v224, v216, v224, v19
	v_fma_f32 v228, v216, v228, v23
	v_fma_f32 v225, v217, v225, v27
	v_fma_f32 v229, v217, v229, v31
	v_mfma_f32_16x16x16_bf16 v[78:81], v[96:97], v[128:129], v[212:215]
	v_fma_f32 v226, v218, v226, v35
	v_fma_f32 v230, v218, v230, v39
	v_fma_f32 v227, v219, v227, v43
	v_fma_f32 v231, v219, v231, v47
	v_mfma_f32_16x16x32_bf16 v[204:207], v[180:183], v[196:199], v[204:207]
	v_cvt_pk_bf16_f32 v136, v224, v228
	v_cvt_pk_bf16_f32 v137, v225, v229
	v_mfma_f32_16x16x32_bf16 v[208:211], v[184:187], v[200:203], v[208:211]
	v_cvt_pk_bf16_f32 v138, v226, v230
	v_cvt_pk_bf16_f32 v139, v227, v231
	ds_write2_b32 v134, v136, v137 offset0:68 offset1:84
	ds_write2_b32 v134, v138, v139 offset0:100 offset1:116
	v_fmac_f32_e32 v20, v232, v228
	v_fmac_f32_e32 v24, v220, v224
	v_fmac_f32_e32 v28, v233, v229
	v_fmac_f32_e32 v32, v221, v225
	v_fmac_f32_e32 v36, v234, v230
	v_fmac_f32_e32 v40, v222, v226
	v_fmac_f32_e32 v44, v235, v231
	v_fmac_f32_e32 v48, v223, v227
	v_fma_f32 v224, v216, v224, v20
	v_fma_f32 v228, v216, v228, v24
	v_fma_f32 v225, v217, v225, v28
	v_fma_f32 v229, v217, v229, v32
	v_fma_f32 v226, v218, v226, v36
	v_fma_f32 v230, v218, v230, v40
	v_fma_f32 v227, v219, v227, v44
	v_fma_f32 v231, v219, v231, v48
	v_cvt_pk_bf16_f32 v136, v224, v228
	v_cvt_pk_bf16_f32 v137, v225, v229
	v_cvt_pk_bf16_f32 v138, v226, v230
	v_cvt_pk_bf16_f32 v139, v227, v231
	ds_write2_b32 v134, v136, v137 offset0:136 offset1:152
	ds_write2_b32 v134, v138, v139 offset0:168 offset1:184
	v_fmac_f32_e32 v21, v232, v228
	v_fmac_f32_e32 v25, v220, v224
	v_fmac_f32_e32 v29, v233, v229
	v_fmac_f32_e32 v33, v221, v225
	v_fmac_f32_e32 v37, v234, v230
	v_fmac_f32_e32 v41, v222, v226
	v_fmac_f32_e32 v45, v235, v231
	v_fmac_f32_e32 v49, v223, v227
	v_fma_f32 v224, v216, v224, v21
	v_fma_f32 v228, v216, v228, v25
	v_fma_f32 v225, v217, v225, v29
	v_fma_f32 v229, v217, v229, v33
	v_fma_f32 v226, v218, v226, v37
	v_fma_f32 v230, v218, v230, v41
	v_fma_f32 v227, v219, v227, v45
	v_fma_f32 v231, v219, v231, v49
	v_cvt_pk_bf16_f32 v136, v224, v228
	v_cvt_pk_bf16_f32 v137, v225, v229
	v_cvt_pk_bf16_f32 v138, v226, v230
	v_cvt_pk_bf16_f32 v139, v227, v231
	ds_write2_b32 v134, v136, v137 offset0:204 offset1:220
	ds_write2_b32 v134, v138, v139 offset0:236 offset1:252
	v_add_f32_e32 v204, v204, v208
	v_add_f32_e32 v205, v205, v209
	v_add_f32_e32 v206, v206, v210
	v_add_f32_e32 v207, v207, v211
	global_store_dwordx4 v[132:133], v[204:207], off sc1
	v_lshl_add_u64 v[132:133], v[132:133], 0, s[88:89]
	s_waitcnt lgkmcnt(0)
	ds_read_b128 v[188:191], v135 offset:0
	ds_read_b128 v[192:195], v135 offset:64
	ds_read_b128 v[196:199], v135 offset:128
	ds_read_b128 v[200:203], v135 offset:192
	s_waitcnt vmcnt(14)
	v_mfma_f32_16x16x16_bf16 v[18:21], v[98:99], v[114:115], v[212:215]
	v_fmac_f32_e32 v50, v232, v228
	v_fmac_f32_e32 v54, v220, v224
	v_fmac_f32_e32 v58, v233, v229
	v_fmac_f32_e32 v62, v221, v225
	v_mfma_f32_16x16x16_bf16 v[22:25], v[98:99], v[116:117], v[212:215]
	v_fmac_f32_e32 v66, v234, v230
	v_fmac_f32_e32 v70, v222, v226
	v_fmac_f32_e32 v74, v235, v231
	v_fmac_f32_e32 v78, v223, v227
	v_mfma_f32_16x16x16_bf16 v[26:29], v[98:99], v[118:119], v[212:215]
	v_fma_f32 v224, v216, v224, v50
	v_fma_f32 v228, v216, v228, v54
	v_fma_f32 v225, v217, v225, v58
	v_fma_f32 v229, v217, v229, v62
	v_mfma_f32_16x16x16_bf16 v[30:33], v[98:99], v[120:121], v[212:215]
	v_fma_f32 v226, v218, v226, v66
	v_fma_f32 v230, v218, v230, v70
	v_fma_f32 v227, v219, v227, v74
	v_fma_f32 v231, v219, v231, v78
	s_waitcnt lgkmcnt(0)
	v_mfma_f32_16x16x32_bf16 v[204:207], v[172:175], v[188:191], v[212:215]
	v_cvt_pk_bf16_f32 v136, v224, v228
	v_cvt_pk_bf16_f32 v137, v225, v229
	v_mfma_f32_16x16x32_bf16 v[208:211], v[176:179], v[192:195], v[212:215]
	v_cvt_pk_bf16_f32 v138, v226, v230
	v_cvt_pk_bf16_f32 v139, v227, v231
	ds_write2_b32 v134, v136, v137 offset0:0 offset1:16
	ds_write2_b32 v134, v138, v139 offset0:32 offset1:48
	v_mfma_f32_16x16x16_bf16 v[34:37], v[98:99], v[122:123], v[212:215]
	v_fmac_f32_e32 v51, v232, v228
	v_fmac_f32_e32 v55, v220, v224
	v_fmac_f32_e32 v59, v233, v229
	v_fmac_f32_e32 v63, v221, v225
	v_mfma_f32_16x16x16_bf16 v[38:41], v[98:99], v[124:125], v[212:215]
	v_fmac_f32_e32 v67, v234, v230
	v_fmac_f32_e32 v71, v222, v226
	v_fmac_f32_e32 v75, v235, v231
	v_fmac_f32_e32 v79, v223, v227
	v_mfma_f32_16x16x16_bf16 v[42:45], v[98:99], v[126:127], v[212:215]
	v_fma_f32 v224, v216, v224, v51
	v_fma_f32 v228, v216, v228, v55
	v_fma_f32 v225, v217, v225, v59
	v_fma_f32 v229, v217, v229, v63
	v_mfma_f32_16x16x16_bf16 v[46:49], v[98:99], v[128:129], v[212:215]
	v_fma_f32 v226, v218, v226, v67
	v_fma_f32 v230, v218, v230, v71
	v_fma_f32 v227, v219, v227, v75
	v_fma_f32 v231, v219, v231, v79
	v_mfma_f32_16x16x32_bf16 v[204:207], v[180:183], v[196:199], v[204:207]
	v_cvt_pk_bf16_f32 v136, v224, v228
	v_cvt_pk_bf16_f32 v137, v225, v229
	v_mfma_f32_16x16x32_bf16 v[208:211], v[184:187], v[200:203], v[208:211]
	v_cvt_pk_bf16_f32 v138, v226, v230
	v_cvt_pk_bf16_f32 v139, v227, v231
	ds_write2_b32 v134, v136, v137 offset0:68 offset1:84
	ds_write2_b32 v134, v138, v139 offset0:100 offset1:116
	v_fmac_f32_e32 v52, v232, v228
	v_fmac_f32_e32 v56, v220, v224
	v_fmac_f32_e32 v60, v233, v229
	v_fmac_f32_e32 v64, v221, v225
	v_fmac_f32_e32 v68, v234, v230
	v_fmac_f32_e32 v72, v222, v226
	v_fmac_f32_e32 v76, v235, v231
	v_fmac_f32_e32 v80, v223, v227
	v_fma_f32 v224, v216, v224, v52
	v_fma_f32 v228, v216, v228, v56
	v_fma_f32 v225, v217, v225, v60
	v_fma_f32 v229, v217, v229, v64
	v_fma_f32 v226, v218, v226, v68
	v_fma_f32 v230, v218, v230, v72
	v_fma_f32 v227, v219, v227, v76
	v_fma_f32 v231, v219, v231, v80
	v_cvt_pk_bf16_f32 v136, v224, v228
	v_cvt_pk_bf16_f32 v137, v225, v229
	v_cvt_pk_bf16_f32 v138, v226, v230
	v_cvt_pk_bf16_f32 v139, v227, v231
	ds_write2_b32 v134, v136, v137 offset0:136 offset1:152
	ds_write2_b32 v134, v138, v139 offset0:168 offset1:184
	v_fmac_f32_e32 v53, v232, v228
	v_fmac_f32_e32 v57, v220, v224
	v_fmac_f32_e32 v61, v233, v229
	v_fmac_f32_e32 v65, v221, v225
	v_fmac_f32_e32 v69, v234, v230
	v_fmac_f32_e32 v73, v222, v226
	v_fmac_f32_e32 v77, v235, v231
	v_fmac_f32_e32 v81, v223, v227
	v_fma_f32 v224, v216, v224, v53
	v_fma_f32 v228, v216, v228, v57
	v_fma_f32 v225, v217, v225, v61
	v_fma_f32 v229, v217, v229, v65
	v_fma_f32 v226, v218, v226, v69
	v_fma_f32 v230, v218, v230, v73
	v_fma_f32 v227, v219, v227, v77
	v_fma_f32 v231, v219, v231, v81
	v_cvt_pk_bf16_f32 v136, v224, v228
	v_cvt_pk_bf16_f32 v137, v225, v229
	v_cvt_pk_bf16_f32 v138, v226, v230
	v_cvt_pk_bf16_f32 v139, v227, v231
	ds_write2_b32 v134, v136, v137 offset0:204 offset1:220
	ds_write2_b32 v134, v138, v139 offset0:236 offset1:252
	v_add_f32_e32 v204, v204, v208
	v_add_f32_e32 v205, v205, v209
	v_add_f32_e32 v206, v206, v210
	v_add_f32_e32 v207, v207, v211
	global_store_dwordx4 v[132:133], v[204:207], off sc1
	v_lshl_add_u64 v[132:133], v[132:133], 0, s[88:89]
	s_waitcnt lgkmcnt(0)
	ds_read_b128 v[188:191], v135 offset:0
	ds_read_b128 v[192:195], v135 offset:64
	ds_read_b128 v[196:199], v135 offset:128
	ds_read_b128 v[200:203], v135 offset:192
	global_load_dwordx2 v[90:91], v[130:131], off
	v_lshl_add_u64 v[130:131], v[130:131], 0, s[86:87]
	global_load_dwordx2 v[92:93], v[130:131], off
	v_lshl_add_u64 v[130:131], v[130:131], 0, s[86:87]
	global_load_dwordx2 v[94:95], v[130:131], off
	v_lshl_add_u64 v[130:131], v[130:131], 0, s[86:87]
	global_load_dwordx2 v[96:97], v[130:131], off
	v_lshl_add_u64 v[130:131], v[130:131], 0, s[86:87]
	v_mfma_f32_16x16x16_bf16 v[50:53], v[100:101], v[114:115], v[212:215]
	v_fmac_f32_e32 v18, v232, v228
	v_fmac_f32_e32 v22, v220, v224
	v_fmac_f32_e32 v26, v233, v229
	v_fmac_f32_e32 v30, v221, v225
	v_mfma_f32_16x16x16_bf16 v[54:57], v[100:101], v[116:117], v[212:215]
	v_fmac_f32_e32 v34, v234, v230
	v_fmac_f32_e32 v38, v222, v226
	v_fmac_f32_e32 v42, v235, v231
	v_fmac_f32_e32 v46, v223, v227
	v_mfma_f32_16x16x16_bf16 v[58:61], v[100:101], v[118:119], v[212:215]
	v_fma_f32 v224, v216, v224, v18
	v_fma_f32 v228, v216, v228, v22
	v_fma_f32 v225, v217, v225, v26
	v_fma_f32 v229, v217, v229, v30
	v_mfma_f32_16x16x16_bf16 v[62:65], v[100:101], v[120:121], v[212:215]
	v_fma_f32 v226, v218, v226, v34
	v_fma_f32 v230, v218, v230, v38
	v_fma_f32 v227, v219, v227, v42
	v_fma_f32 v231, v219, v231, v46
	s_waitcnt lgkmcnt(0)
	v_mfma_f32_16x16x32_bf16 v[204:207], v[172:175], v[188:191], v[212:215]
	v_cvt_pk_bf16_f32 v136, v224, v228
	v_cvt_pk_bf16_f32 v137, v225, v229
	v_mfma_f32_16x16x32_bf16 v[208:211], v[176:179], v[192:195], v[212:215]
	v_cvt_pk_bf16_f32 v138, v226, v230
	v_cvt_pk_bf16_f32 v139, v227, v231
	ds_write2_b32 v134, v136, v137 offset0:0 offset1:16
	ds_write2_b32 v134, v138, v139 offset0:32 offset1:48
	v_mfma_f32_16x16x16_bf16 v[66:69], v[100:101], v[122:123], v[212:215]
	v_fmac_f32_e32 v19, v232, v228
	v_fmac_f32_e32 v23, v220, v224
	v_fmac_f32_e32 v27, v233, v229
	v_fmac_f32_e32 v31, v221, v225
	v_mfma_f32_16x16x16_bf16 v[70:73], v[100:101], v[124:125], v[212:215]
	v_fmac_f32_e32 v35, v234, v230
	v_fmac_f32_e32 v39, v222, v226
	v_fmac_f32_e32 v43, v235, v231
	v_fmac_f32_e32 v47, v223, v227
	v_mfma_f32_16x16x16_bf16 v[74:77], v[100:101], v[126:127], v[212:215]
	v_fma_f32 v224, v216, v224, v19
	v_fma_f32 v228, v216, v228, v23
	v_fma_f32 v225, v217, v225, v27
	v_fma_f32 v229, v217, v229, v31
	v_mfma_f32_16x16x16_bf16 v[78:81], v[100:101], v[128:129], v[212:215]
	v_fma_f32 v226, v218, v226, v35
	v_fma_f32 v230, v218, v230, v39
	v_fma_f32 v227, v219, v227, v43
	v_fma_f32 v231, v219, v231, v47
	v_mfma_f32_16x16x32_bf16 v[204:207], v[180:183], v[196:199], v[204:207]
	v_cvt_pk_bf16_f32 v136, v224, v228
	v_cvt_pk_bf16_f32 v137, v225, v229
	v_mfma_f32_16x16x32_bf16 v[208:211], v[184:187], v[200:203], v[208:211]
	v_cvt_pk_bf16_f32 v138, v226, v230
	v_cvt_pk_bf16_f32 v139, v227, v231
	ds_write2_b32 v134, v136, v137 offset0:68 offset1:84
	ds_write2_b32 v134, v138, v139 offset0:100 offset1:116
	v_fmac_f32_e32 v20, v232, v228
	v_fmac_f32_e32 v24, v220, v224
	v_fmac_f32_e32 v28, v233, v229
	v_fmac_f32_e32 v32, v221, v225
	v_fmac_f32_e32 v36, v234, v230
	v_fmac_f32_e32 v40, v222, v226
	v_fmac_f32_e32 v44, v235, v231
	v_fmac_f32_e32 v48, v223, v227
	v_fma_f32 v224, v216, v224, v20
	v_fma_f32 v228, v216, v228, v24
	v_fma_f32 v225, v217, v225, v28
	v_fma_f32 v229, v217, v229, v32
	v_fma_f32 v226, v218, v226, v36
	v_fma_f32 v230, v218, v230, v40
	v_fma_f32 v227, v219, v227, v44
	v_fma_f32 v231, v219, v231, v48
	v_cvt_pk_bf16_f32 v136, v224, v228
	v_cvt_pk_bf16_f32 v137, v225, v229
	v_cvt_pk_bf16_f32 v138, v226, v230
	v_cvt_pk_bf16_f32 v139, v227, v231
	ds_write2_b32 v134, v136, v137 offset0:136 offset1:152
	ds_write2_b32 v134, v138, v139 offset0:168 offset1:184
	v_fmac_f32_e32 v21, v232, v228
	v_fmac_f32_e32 v25, v220, v224
	v_fmac_f32_e32 v29, v233, v229
	v_fmac_f32_e32 v33, v221, v225
	v_fmac_f32_e32 v37, v234, v230
	v_fmac_f32_e32 v41, v222, v226
	v_fmac_f32_e32 v45, v235, v231
	v_fmac_f32_e32 v49, v223, v227
	v_fma_f32 v224, v216, v224, v21
	v_fma_f32 v228, v216, v228, v25
	v_fma_f32 v225, v217, v225, v29
	v_fma_f32 v229, v217, v229, v33
	v_fma_f32 v226, v218, v226, v37
	v_fma_f32 v230, v218, v230, v41
	v_fma_f32 v227, v219, v227, v45
	v_fma_f32 v231, v219, v231, v49
	v_cvt_pk_bf16_f32 v136, v224, v228
	v_cvt_pk_bf16_f32 v137, v225, v229
	v_cvt_pk_bf16_f32 v138, v226, v230
	v_cvt_pk_bf16_f32 v139, v227, v231
	ds_write2_b32 v134, v136, v137 offset0:204 offset1:220
	ds_write2_b32 v134, v138, v139 offset0:236 offset1:252
	v_add_f32_e32 v204, v204, v208
	v_add_f32_e32 v205, v205, v209
	v_add_f32_e32 v206, v206, v210
	v_add_f32_e32 v207, v207, v211
	global_store_dwordx4 v[132:133], v[204:207], off sc1
	v_lshl_add_u64 v[132:133], v[132:133], 0, s[88:89]
	s_waitcnt lgkmcnt(0)
	ds_read_b128 v[188:191], v135 offset:0
	ds_read_b128 v[192:195], v135 offset:64
	ds_read_b128 v[196:199], v135 offset:128
	ds_read_b128 v[200:203], v135 offset:192
	v_mfma_f32_16x16x16_bf16 v[18:21], v[102:103], v[114:115], v[212:215]
	v_fmac_f32_e32 v50, v232, v228
	v_fmac_f32_e32 v54, v220, v224
	v_fmac_f32_e32 v58, v233, v229
	v_fmac_f32_e32 v62, v221, v225
	v_mfma_f32_16x16x16_bf16 v[22:25], v[102:103], v[116:117], v[212:215]
	v_fmac_f32_e32 v66, v234, v230
	v_fmac_f32_e32 v70, v222, v226
	v_fmac_f32_e32 v74, v235, v231
	v_fmac_f32_e32 v78, v223, v227
	v_mfma_f32_16x16x16_bf16 v[26:29], v[102:103], v[118:119], v[212:215]
	v_fma_f32 v224, v216, v224, v50
	v_fma_f32 v228, v216, v228, v54
	v_fma_f32 v225, v217, v225, v58
	v_fma_f32 v229, v217, v229, v62
	v_mfma_f32_16x16x16_bf16 v[30:33], v[102:103], v[120:121], v[212:215]
	v_fma_f32 v226, v218, v226, v66
	v_fma_f32 v230, v218, v230, v70
	v_fma_f32 v227, v219, v227, v74
	v_fma_f32 v231, v219, v231, v78
	s_waitcnt lgkmcnt(0)
	v_mfma_f32_16x16x32_bf16 v[204:207], v[172:175], v[188:191], v[212:215]
	v_cvt_pk_bf16_f32 v136, v224, v228
	v_cvt_pk_bf16_f32 v137, v225, v229
	v_mfma_f32_16x16x32_bf16 v[208:211], v[176:179], v[192:195], v[212:215]
	v_cvt_pk_bf16_f32 v138, v226, v230
	v_cvt_pk_bf16_f32 v139, v227, v231
	ds_write2_b32 v134, v136, v137 offset0:0 offset1:16
	ds_write2_b32 v134, v138, v139 offset0:32 offset1:48
	v_mfma_f32_16x16x16_bf16 v[34:37], v[102:103], v[122:123], v[212:215]
	v_fmac_f32_e32 v51, v232, v228
	v_fmac_f32_e32 v55, v220, v224
	v_fmac_f32_e32 v59, v233, v229
	v_fmac_f32_e32 v63, v221, v225
	v_mfma_f32_16x16x16_bf16 v[38:41], v[102:103], v[124:125], v[212:215]
	v_fmac_f32_e32 v67, v234, v230
	v_fmac_f32_e32 v71, v222, v226
	v_fmac_f32_e32 v75, v235, v231
	v_fmac_f32_e32 v79, v223, v227
	v_mfma_f32_16x16x16_bf16 v[42:45], v[102:103], v[126:127], v[212:215]
	v_fma_f32 v224, v216, v224, v51
	v_fma_f32 v228, v216, v228, v55
	v_fma_f32 v225, v217, v225, v59
	v_fma_f32 v229, v217, v229, v63
	v_mfma_f32_16x16x16_bf16 v[46:49], v[102:103], v[128:129], v[212:215]
	v_fma_f32 v226, v218, v226, v67
	v_fma_f32 v230, v218, v230, v71
	v_fma_f32 v227, v219, v227, v75
	v_fma_f32 v231, v219, v231, v79
	v_mfma_f32_16x16x32_bf16 v[204:207], v[180:183], v[196:199], v[204:207]
	v_cvt_pk_bf16_f32 v136, v224, v228
	v_cvt_pk_bf16_f32 v137, v225, v229
	v_mfma_f32_16x16x32_bf16 v[208:211], v[184:187], v[200:203], v[208:211]
	v_cvt_pk_bf16_f32 v138, v226, v230
	v_cvt_pk_bf16_f32 v139, v227, v231
	ds_write2_b32 v134, v136, v137 offset0:68 offset1:84
	ds_write2_b32 v134, v138, v139 offset0:100 offset1:116
	v_fmac_f32_e32 v52, v232, v228
	v_fmac_f32_e32 v56, v220, v224
	v_fmac_f32_e32 v60, v233, v229
	v_fmac_f32_e32 v64, v221, v225
	v_fmac_f32_e32 v68, v234, v230
	v_fmac_f32_e32 v72, v222, v226
	v_fmac_f32_e32 v76, v235, v231
	v_fmac_f32_e32 v80, v223, v227
	v_fma_f32 v224, v216, v224, v52
	v_fma_f32 v228, v216, v228, v56
	v_fma_f32 v225, v217, v225, v60
	v_fma_f32 v229, v217, v229, v64
	v_fma_f32 v226, v218, v226, v68
	v_fma_f32 v230, v218, v230, v72
	v_fma_f32 v227, v219, v227, v76
	v_fma_f32 v231, v219, v231, v80
	v_cvt_pk_bf16_f32 v136, v224, v228
	v_cvt_pk_bf16_f32 v137, v225, v229
	v_cvt_pk_bf16_f32 v138, v226, v230
	v_cvt_pk_bf16_f32 v139, v227, v231
	ds_write2_b32 v134, v136, v137 offset0:136 offset1:152
	ds_write2_b32 v134, v138, v139 offset0:168 offset1:184
	v_fmac_f32_e32 v53, v232, v228
	v_fmac_f32_e32 v57, v220, v224
	v_fmac_f32_e32 v61, v233, v229
	v_fmac_f32_e32 v65, v221, v225
	v_fmac_f32_e32 v69, v234, v230
	v_fmac_f32_e32 v73, v222, v226
	v_fmac_f32_e32 v77, v235, v231
	v_fmac_f32_e32 v81, v223, v227
	v_fma_f32 v224, v216, v224, v53
	v_fma_f32 v228, v216, v228, v57
	v_fma_f32 v225, v217, v225, v61
	v_fma_f32 v229, v217, v229, v65
	v_fma_f32 v226, v218, v226, v69
	v_fma_f32 v230, v218, v230, v73
	v_fma_f32 v227, v219, v227, v77
	v_fma_f32 v231, v219, v231, v81
	v_cvt_pk_bf16_f32 v136, v224, v228
	v_cvt_pk_bf16_f32 v137, v225, v229
	v_cvt_pk_bf16_f32 v138, v226, v230
	v_cvt_pk_bf16_f32 v139, v227, v231
	ds_write2_b32 v134, v136, v137 offset0:204 offset1:220
	ds_write2_b32 v134, v138, v139 offset0:236 offset1:252
	v_add_f32_e32 v204, v204, v208
	v_add_f32_e32 v205, v205, v209
	v_add_f32_e32 v206, v206, v210
	v_add_f32_e32 v207, v207, v211
	global_store_dwordx4 v[132:133], v[204:207], off sc1
	v_lshl_add_u64 v[132:133], v[132:133], 0, s[88:89]
	s_waitcnt lgkmcnt(0)
	ds_read_b128 v[188:191], v135 offset:0
	ds_read_b128 v[192:195], v135 offset:64
	ds_read_b128 v[196:199], v135 offset:128
	ds_read_b128 v[200:203], v135 offset:192
	v_mfma_f32_16x16x16_bf16 v[50:53], v[104:105], v[114:115], v[212:215]
	v_fmac_f32_e32 v18, v232, v228
	v_fmac_f32_e32 v22, v220, v224
	v_fmac_f32_e32 v26, v233, v229
	v_fmac_f32_e32 v30, v221, v225
	v_mfma_f32_16x16x16_bf16 v[54:57], v[104:105], v[116:117], v[212:215]
	v_fmac_f32_e32 v34, v234, v230
	v_fmac_f32_e32 v38, v222, v226
	v_fmac_f32_e32 v42, v235, v231
	v_fmac_f32_e32 v46, v223, v227
	v_mfma_f32_16x16x16_bf16 v[58:61], v[104:105], v[118:119], v[212:215]
	v_fma_f32 v224, v216, v224, v18
	v_fma_f32 v228, v216, v228, v22
	v_fma_f32 v225, v217, v225, v26
	v_fma_f32 v229, v217, v229, v30
	v_mfma_f32_16x16x16_bf16 v[62:65], v[104:105], v[120:121], v[212:215]
	v_fma_f32 v226, v218, v226, v34
	v_fma_f32 v230, v218, v230, v38
	v_fma_f32 v227, v219, v227, v42
	v_fma_f32 v231, v219, v231, v46
	s_waitcnt lgkmcnt(0)
	v_mfma_f32_16x16x32_bf16 v[204:207], v[172:175], v[188:191], v[212:215]
	v_cvt_pk_bf16_f32 v136, v224, v228
	v_cvt_pk_bf16_f32 v137, v225, v229
	v_mfma_f32_16x16x32_bf16 v[208:211], v[176:179], v[192:195], v[212:215]
	v_cvt_pk_bf16_f32 v138, v226, v230
	v_cvt_pk_bf16_f32 v139, v227, v231
	ds_write2_b32 v134, v136, v137 offset0:0 offset1:16
	ds_write2_b32 v134, v138, v139 offset0:32 offset1:48
	v_mfma_f32_16x16x16_bf16 v[66:69], v[104:105], v[122:123], v[212:215]
	v_fmac_f32_e32 v19, v232, v228
	v_fmac_f32_e32 v23, v220, v224
	v_fmac_f32_e32 v27, v233, v229
	v_fmac_f32_e32 v31, v221, v225
	v_mfma_f32_16x16x16_bf16 v[70:73], v[104:105], v[124:125], v[212:215]
	v_fmac_f32_e32 v35, v234, v230
	v_fmac_f32_e32 v39, v222, v226
	v_fmac_f32_e32 v43, v235, v231
	v_fmac_f32_e32 v47, v223, v227
	v_mfma_f32_16x16x16_bf16 v[74:77], v[104:105], v[126:127], v[212:215]
	v_fma_f32 v224, v216, v224, v19
	v_fma_f32 v228, v216, v228, v23
	v_fma_f32 v225, v217, v225, v27
	v_fma_f32 v229, v217, v229, v31
	v_mfma_f32_16x16x16_bf16 v[78:81], v[104:105], v[128:129], v[212:215]
	v_fma_f32 v226, v218, v226, v35
	v_fma_f32 v230, v218, v230, v39
	v_fma_f32 v227, v219, v227, v43
	v_fma_f32 v231, v219, v231, v47
	v_mfma_f32_16x16x32_bf16 v[204:207], v[180:183], v[196:199], v[204:207]
	v_cvt_pk_bf16_f32 v136, v224, v228
	v_cvt_pk_bf16_f32 v137, v225, v229
	v_mfma_f32_16x16x32_bf16 v[208:211], v[184:187], v[200:203], v[208:211]
	v_cvt_pk_bf16_f32 v138, v226, v230
	v_cvt_pk_bf16_f32 v139, v227, v231
	ds_write2_b32 v134, v136, v137 offset0:68 offset1:84
	ds_write2_b32 v134, v138, v139 offset0:100 offset1:116
	v_fmac_f32_e32 v20, v232, v228
	v_fmac_f32_e32 v24, v220, v224
	v_fmac_f32_e32 v28, v233, v229
	v_fmac_f32_e32 v32, v221, v225
	v_fmac_f32_e32 v36, v234, v230
	v_fmac_f32_e32 v40, v222, v226
	v_fmac_f32_e32 v44, v235, v231
	v_fmac_f32_e32 v48, v223, v227
	v_fma_f32 v224, v216, v224, v20
	v_fma_f32 v228, v216, v228, v24
	v_fma_f32 v225, v217, v225, v28
	v_fma_f32 v229, v217, v229, v32
	v_fma_f32 v226, v218, v226, v36
	v_fma_f32 v230, v218, v230, v40
	v_fma_f32 v227, v219, v227, v44
	v_fma_f32 v231, v219, v231, v48
	v_cvt_pk_bf16_f32 v136, v224, v228
	v_cvt_pk_bf16_f32 v137, v225, v229
	v_cvt_pk_bf16_f32 v138, v226, v230
	v_cvt_pk_bf16_f32 v139, v227, v231
	ds_write2_b32 v134, v136, v137 offset0:136 offset1:152
	ds_write2_b32 v134, v138, v139 offset0:168 offset1:184
	v_fmac_f32_e32 v21, v232, v228
	v_fmac_f32_e32 v25, v220, v224
	v_fmac_f32_e32 v29, v233, v229
	v_fmac_f32_e32 v33, v221, v225
	v_fmac_f32_e32 v37, v234, v230
	v_fmac_f32_e32 v41, v222, v226
	v_fmac_f32_e32 v45, v235, v231
	v_fmac_f32_e32 v49, v223, v227
	v_fma_f32 v224, v216, v224, v21
	v_fma_f32 v228, v216, v228, v25
	v_fma_f32 v225, v217, v225, v29
	v_fma_f32 v229, v217, v229, v33
	v_fma_f32 v226, v218, v226, v37
	v_fma_f32 v230, v218, v230, v41
	v_fma_f32 v227, v219, v227, v45
	v_fma_f32 v231, v219, v231, v49
	v_cvt_pk_bf16_f32 v136, v224, v228
	v_cvt_pk_bf16_f32 v137, v225, v229
	v_cvt_pk_bf16_f32 v138, v226, v230
	v_cvt_pk_bf16_f32 v139, v227, v231
	ds_write2_b32 v134, v136, v137 offset0:204 offset1:220
	ds_write2_b32 v134, v138, v139 offset0:236 offset1:252
	v_add_f32_e32 v204, v204, v208
	v_add_f32_e32 v205, v205, v209
	v_add_f32_e32 v206, v206, v210
	v_add_f32_e32 v207, v207, v211
	global_store_dwordx4 v[132:133], v[204:207], off sc1
	v_lshl_add_u64 v[132:133], v[132:133], 0, s[88:89]
	s_waitcnt lgkmcnt(0)
	ds_read_b128 v[188:191], v135 offset:0
	ds_read_b128 v[192:195], v135 offset:64
	ds_read_b128 v[196:199], v135 offset:128
	ds_read_b128 v[200:203], v135 offset:192
	s_waitcnt vmcnt(14)
	v_mfma_f32_16x16x16_bf16 v[18:21], v[106:107], v[114:115], v[212:215]
	v_fmac_f32_e32 v50, v232, v228
	v_fmac_f32_e32 v54, v220, v224
	v_fmac_f32_e32 v58, v233, v229
	v_fmac_f32_e32 v62, v221, v225
	v_mfma_f32_16x16x16_bf16 v[22:25], v[106:107], v[116:117], v[212:215]
	v_fmac_f32_e32 v66, v234, v230
	v_fmac_f32_e32 v70, v222, v226
	v_fmac_f32_e32 v74, v235, v231
	v_fmac_f32_e32 v78, v223, v227
	v_mfma_f32_16x16x16_bf16 v[26:29], v[106:107], v[118:119], v[212:215]
	v_fma_f32 v224, v216, v224, v50
	v_fma_f32 v228, v216, v228, v54
	v_fma_f32 v225, v217, v225, v58
	v_fma_f32 v229, v217, v229, v62
	v_mfma_f32_16x16x16_bf16 v[30:33], v[106:107], v[120:121], v[212:215]
	v_fma_f32 v226, v218, v226, v66
	v_fma_f32 v230, v218, v230, v70
	v_fma_f32 v227, v219, v227, v74
	v_fma_f32 v231, v219, v231, v78
	s_waitcnt lgkmcnt(0)
	v_mfma_f32_16x16x32_bf16 v[204:207], v[172:175], v[188:191], v[212:215]
	v_cvt_pk_bf16_f32 v136, v224, v228
	v_cvt_pk_bf16_f32 v137, v225, v229
	v_mfma_f32_16x16x32_bf16 v[208:211], v[176:179], v[192:195], v[212:215]
	v_cvt_pk_bf16_f32 v138, v226, v230
	v_cvt_pk_bf16_f32 v139, v227, v231
	ds_write2_b32 v134, v136, v137 offset0:0 offset1:16
	ds_write2_b32 v134, v138, v139 offset0:32 offset1:48
	v_mfma_f32_16x16x16_bf16 v[34:37], v[106:107], v[122:123], v[212:215]
	v_fmac_f32_e32 v51, v232, v228
	v_fmac_f32_e32 v55, v220, v224
	v_fmac_f32_e32 v59, v233, v229
	v_fmac_f32_e32 v63, v221, v225
	v_mfma_f32_16x16x16_bf16 v[38:41], v[106:107], v[124:125], v[212:215]
	v_fmac_f32_e32 v67, v234, v230
	v_fmac_f32_e32 v71, v222, v226
	v_fmac_f32_e32 v75, v235, v231
	v_fmac_f32_e32 v79, v223, v227
	v_mfma_f32_16x16x16_bf16 v[42:45], v[106:107], v[126:127], v[212:215]
	v_fma_f32 v224, v216, v224, v51
	v_fma_f32 v228, v216, v228, v55
	v_fma_f32 v225, v217, v225, v59
	v_fma_f32 v229, v217, v229, v63
	v_mfma_f32_16x16x16_bf16 v[46:49], v[106:107], v[128:129], v[212:215]
	v_fma_f32 v226, v218, v226, v67
	v_fma_f32 v230, v218, v230, v71
	v_fma_f32 v227, v219, v227, v75
	v_fma_f32 v231, v219, v231, v79
	v_mfma_f32_16x16x32_bf16 v[204:207], v[180:183], v[196:199], v[204:207]
	v_cvt_pk_bf16_f32 v136, v224, v228
	v_cvt_pk_bf16_f32 v137, v225, v229
	v_mfma_f32_16x16x32_bf16 v[208:211], v[184:187], v[200:203], v[208:211]
	v_cvt_pk_bf16_f32 v138, v226, v230
	v_cvt_pk_bf16_f32 v139, v227, v231
	ds_write2_b32 v134, v136, v137 offset0:68 offset1:84
	ds_write2_b32 v134, v138, v139 offset0:100 offset1:116
	v_fmac_f32_e32 v52, v232, v228
	v_fmac_f32_e32 v56, v220, v224
	v_fmac_f32_e32 v60, v233, v229
	v_fmac_f32_e32 v64, v221, v225
	v_fmac_f32_e32 v68, v234, v230
	v_fmac_f32_e32 v72, v222, v226
	v_fmac_f32_e32 v76, v235, v231
	v_fmac_f32_e32 v80, v223, v227
	v_fma_f32 v224, v216, v224, v52
	v_fma_f32 v228, v216, v228, v56
	v_fma_f32 v225, v217, v225, v60
	v_fma_f32 v229, v217, v229, v64
	v_fma_f32 v226, v218, v226, v68
	v_fma_f32 v230, v218, v230, v72
	v_fma_f32 v227, v219, v227, v76
	v_fma_f32 v231, v219, v231, v80
	v_cvt_pk_bf16_f32 v136, v224, v228
	v_cvt_pk_bf16_f32 v137, v225, v229
	v_cvt_pk_bf16_f32 v138, v226, v230
	v_cvt_pk_bf16_f32 v139, v227, v231
	ds_write2_b32 v134, v136, v137 offset0:136 offset1:152
	ds_write2_b32 v134, v138, v139 offset0:168 offset1:184
	v_fmac_f32_e32 v53, v232, v228
	v_fmac_f32_e32 v57, v220, v224
	v_fmac_f32_e32 v61, v233, v229
	v_fmac_f32_e32 v65, v221, v225
	v_fmac_f32_e32 v69, v234, v230
	v_fmac_f32_e32 v73, v222, v226
	v_fmac_f32_e32 v77, v235, v231
	v_fmac_f32_e32 v81, v223, v227
	v_fma_f32 v224, v216, v224, v53
	v_fma_f32 v228, v216, v228, v57
	v_fma_f32 v225, v217, v225, v61
	v_fma_f32 v229, v217, v229, v65
	v_fma_f32 v226, v218, v226, v69
	v_fma_f32 v230, v218, v230, v73
	v_fma_f32 v227, v219, v227, v77
	v_fma_f32 v231, v219, v231, v81
	v_cvt_pk_bf16_f32 v136, v224, v228
	v_cvt_pk_bf16_f32 v137, v225, v229
	v_cvt_pk_bf16_f32 v138, v226, v230
	v_cvt_pk_bf16_f32 v139, v227, v231
	ds_write2_b32 v134, v136, v137 offset0:204 offset1:220
	ds_write2_b32 v134, v138, v139 offset0:236 offset1:252
	v_add_f32_e32 v204, v204, v208
	v_add_f32_e32 v205, v205, v209
	v_add_f32_e32 v206, v206, v210
	v_add_f32_e32 v207, v207, v211
	global_store_dwordx4 v[132:133], v[204:207], off sc1
	v_lshl_add_u64 v[132:133], v[132:133], 0, s[88:89]
	s_waitcnt lgkmcnt(0)
	ds_read_b128 v[188:191], v135 offset:0
	ds_read_b128 v[192:195], v135 offset:64
	ds_read_b128 v[196:199], v135 offset:128
	ds_read_b128 v[200:203], v135 offset:192
	global_load_dwordx2 v[98:99], v[130:131], off
	v_lshl_add_u64 v[130:131], v[130:131], 0, s[86:87]
	global_load_dwordx2 v[100:101], v[130:131], off
	v_lshl_add_u64 v[130:131], v[130:131], 0, s[86:87]
	global_load_dwordx2 v[102:103], v[130:131], off
	v_lshl_add_u64 v[130:131], v[130:131], 0, s[86:87]
	global_load_dwordx2 v[104:105], v[130:131], off
	v_lshl_add_u64 v[130:131], v[130:131], 0, s[86:87]
	v_mfma_f32_16x16x16_bf16 v[50:53], v[108:109], v[114:115], v[212:215]
	v_fmac_f32_e32 v18, v232, v228
	v_fmac_f32_e32 v22, v220, v224
	v_fmac_f32_e32 v26, v233, v229
	v_fmac_f32_e32 v30, v221, v225
	v_mfma_f32_16x16x16_bf16 v[54:57], v[108:109], v[116:117], v[212:215]
	v_fmac_f32_e32 v34, v234, v230
	v_fmac_f32_e32 v38, v222, v226
	v_fmac_f32_e32 v42, v235, v231
	v_fmac_f32_e32 v46, v223, v227
	v_mfma_f32_16x16x16_bf16 v[58:61], v[108:109], v[118:119], v[212:215]
	v_fma_f32 v224, v216, v224, v18
	v_fma_f32 v228, v216, v228, v22
	v_fma_f32 v225, v217, v225, v26
	v_fma_f32 v229, v217, v229, v30
	v_mfma_f32_16x16x16_bf16 v[62:65], v[108:109], v[120:121], v[212:215]
	v_fma_f32 v226, v218, v226, v34
	v_fma_f32 v230, v218, v230, v38
	v_fma_f32 v227, v219, v227, v42
	v_fma_f32 v231, v219, v231, v46
	s_waitcnt lgkmcnt(0)
	v_mfma_f32_16x16x32_bf16 v[204:207], v[172:175], v[188:191], v[212:215]
	v_cvt_pk_bf16_f32 v136, v224, v228
	v_cvt_pk_bf16_f32 v137, v225, v229
	v_mfma_f32_16x16x32_bf16 v[208:211], v[176:179], v[192:195], v[212:215]
	v_cvt_pk_bf16_f32 v138, v226, v230
	v_cvt_pk_bf16_f32 v139, v227, v231
	ds_write2_b32 v134, v136, v137 offset0:0 offset1:16
	ds_write2_b32 v134, v138, v139 offset0:32 offset1:48
	v_mfma_f32_16x16x16_bf16 v[66:69], v[108:109], v[122:123], v[212:215]
	v_fmac_f32_e32 v19, v232, v228
	v_fmac_f32_e32 v23, v220, v224
	v_fmac_f32_e32 v27, v233, v229
	v_fmac_f32_e32 v31, v221, v225
	v_mfma_f32_16x16x16_bf16 v[70:73], v[108:109], v[124:125], v[212:215]
	v_fmac_f32_e32 v35, v234, v230
	v_fmac_f32_e32 v39, v222, v226
	v_fmac_f32_e32 v43, v235, v231
	v_fmac_f32_e32 v47, v223, v227
	v_mfma_f32_16x16x16_bf16 v[74:77], v[108:109], v[126:127], v[212:215]
	v_fma_f32 v224, v216, v224, v19
	v_fma_f32 v228, v216, v228, v23
	v_fma_f32 v225, v217, v225, v27
	v_fma_f32 v229, v217, v229, v31
	v_mfma_f32_16x16x16_bf16 v[78:81], v[108:109], v[128:129], v[212:215]
	v_fma_f32 v226, v218, v226, v35
	v_fma_f32 v230, v218, v230, v39
	v_fma_f32 v227, v219, v227, v43
	v_fma_f32 v231, v219, v231, v47
	v_mfma_f32_16x16x32_bf16 v[204:207], v[180:183], v[196:199], v[204:207]
	v_cvt_pk_bf16_f32 v136, v224, v228
	v_cvt_pk_bf16_f32 v137, v225, v229
	v_mfma_f32_16x16x32_bf16 v[208:211], v[184:187], v[200:203], v[208:211]
	v_cvt_pk_bf16_f32 v138, v226, v230
	v_cvt_pk_bf16_f32 v139, v227, v231
	ds_write2_b32 v134, v136, v137 offset0:68 offset1:84
	ds_write2_b32 v134, v138, v139 offset0:100 offset1:116
	v_fmac_f32_e32 v20, v232, v228
	v_fmac_f32_e32 v24, v220, v224
	v_fmac_f32_e32 v28, v233, v229
	v_fmac_f32_e32 v32, v221, v225
	v_fmac_f32_e32 v36, v234, v230
	v_fmac_f32_e32 v40, v222, v226
	v_fmac_f32_e32 v44, v235, v231
	v_fmac_f32_e32 v48, v223, v227
	v_fma_f32 v224, v216, v224, v20
	v_fma_f32 v228, v216, v228, v24
	v_fma_f32 v225, v217, v225, v28
	v_fma_f32 v229, v217, v229, v32
	v_fma_f32 v226, v218, v226, v36
	v_fma_f32 v230, v218, v230, v40
	v_fma_f32 v227, v219, v227, v44
	v_fma_f32 v231, v219, v231, v48
	v_cvt_pk_bf16_f32 v136, v224, v228
	v_cvt_pk_bf16_f32 v137, v225, v229
	v_cvt_pk_bf16_f32 v138, v226, v230
	v_cvt_pk_bf16_f32 v139, v227, v231
	ds_write2_b32 v134, v136, v137 offset0:136 offset1:152
	ds_write2_b32 v134, v138, v139 offset0:168 offset1:184
	v_fmac_f32_e32 v21, v232, v228
	v_fmac_f32_e32 v25, v220, v224
	v_fmac_f32_e32 v29, v233, v229
	v_fmac_f32_e32 v33, v221, v225
	v_fmac_f32_e32 v37, v234, v230
	v_fmac_f32_e32 v41, v222, v226
	v_fmac_f32_e32 v45, v235, v231
	v_fmac_f32_e32 v49, v223, v227
	v_fma_f32 v224, v216, v224, v21
	v_fma_f32 v228, v216, v228, v25
	v_fma_f32 v225, v217, v225, v29
	v_fma_f32 v229, v217, v229, v33
	v_fma_f32 v226, v218, v226, v37
	v_fma_f32 v230, v218, v230, v41
	v_fma_f32 v227, v219, v227, v45
	v_fma_f32 v231, v219, v231, v49
	v_cvt_pk_bf16_f32 v136, v224, v228
	v_cvt_pk_bf16_f32 v137, v225, v229
	v_cvt_pk_bf16_f32 v138, v226, v230
	v_cvt_pk_bf16_f32 v139, v227, v231
	ds_write2_b32 v134, v136, v137 offset0:204 offset1:220
	ds_write2_b32 v134, v138, v139 offset0:236 offset1:252
	v_add_f32_e32 v204, v204, v208
	v_add_f32_e32 v205, v205, v209
	v_add_f32_e32 v206, v206, v210
	v_add_f32_e32 v207, v207, v211
	global_store_dwordx4 v[132:133], v[204:207], off sc1
	v_lshl_add_u64 v[132:133], v[132:133], 0, s[88:89]
	s_waitcnt lgkmcnt(0)
	ds_read_b128 v[188:191], v135 offset:0
	ds_read_b128 v[192:195], v135 offset:64
	ds_read_b128 v[196:199], v135 offset:128
	ds_read_b128 v[200:203], v135 offset:192
	v_mfma_f32_16x16x16_bf16 v[18:21], v[110:111], v[114:115], v[212:215]
	v_fmac_f32_e32 v50, v232, v228
	v_fmac_f32_e32 v54, v220, v224
	v_fmac_f32_e32 v58, v233, v229
	v_fmac_f32_e32 v62, v221, v225
	v_mfma_f32_16x16x16_bf16 v[22:25], v[110:111], v[116:117], v[212:215]
	v_fmac_f32_e32 v66, v234, v230
	v_fmac_f32_e32 v70, v222, v226
	v_fmac_f32_e32 v74, v235, v231
	v_fmac_f32_e32 v78, v223, v227
	v_mfma_f32_16x16x16_bf16 v[26:29], v[110:111], v[118:119], v[212:215]
	v_fma_f32 v224, v216, v224, v50
	v_fma_f32 v228, v216, v228, v54
	v_fma_f32 v225, v217, v225, v58
	v_fma_f32 v229, v217, v229, v62
	v_mfma_f32_16x16x16_bf16 v[30:33], v[110:111], v[120:121], v[212:215]
	v_fma_f32 v226, v218, v226, v66
	v_fma_f32 v230, v218, v230, v70
	v_fma_f32 v227, v219, v227, v74
	v_fma_f32 v231, v219, v231, v78
	s_waitcnt lgkmcnt(0)
	v_mfma_f32_16x16x32_bf16 v[204:207], v[172:175], v[188:191], v[212:215]
	v_cvt_pk_bf16_f32 v136, v224, v228
	v_cvt_pk_bf16_f32 v137, v225, v229
	v_mfma_f32_16x16x32_bf16 v[208:211], v[176:179], v[192:195], v[212:215]
	v_cvt_pk_bf16_f32 v138, v226, v230
	v_cvt_pk_bf16_f32 v139, v227, v231
	ds_write2_b32 v134, v136, v137 offset0:0 offset1:16
	ds_write2_b32 v134, v138, v139 offset0:32 offset1:48
	v_mfma_f32_16x16x16_bf16 v[34:37], v[110:111], v[122:123], v[212:215]
	v_fmac_f32_e32 v51, v232, v228
	v_fmac_f32_e32 v55, v220, v224
	v_fmac_f32_e32 v59, v233, v229
	v_fmac_f32_e32 v63, v221, v225
	v_mfma_f32_16x16x16_bf16 v[38:41], v[110:111], v[124:125], v[212:215]
	v_fmac_f32_e32 v67, v234, v230
	v_fmac_f32_e32 v71, v222, v226
	v_fmac_f32_e32 v75, v235, v231
	v_fmac_f32_e32 v79, v223, v227
	v_mfma_f32_16x16x16_bf16 v[42:45], v[110:111], v[126:127], v[212:215]
	v_fma_f32 v224, v216, v224, v51
	v_fma_f32 v228, v216, v228, v55
	v_fma_f32 v225, v217, v225, v59
	v_fma_f32 v229, v217, v229, v63
	v_mfma_f32_16x16x16_bf16 v[46:49], v[110:111], v[128:129], v[212:215]
	v_fma_f32 v226, v218, v226, v67
	v_fma_f32 v230, v218, v230, v71
	v_fma_f32 v227, v219, v227, v75
	v_fma_f32 v231, v219, v231, v79
	v_mfma_f32_16x16x32_bf16 v[204:207], v[180:183], v[196:199], v[204:207]
	v_cvt_pk_bf16_f32 v136, v224, v228
	v_cvt_pk_bf16_f32 v137, v225, v229
	v_mfma_f32_16x16x32_bf16 v[208:211], v[184:187], v[200:203], v[208:211]
	v_cvt_pk_bf16_f32 v138, v226, v230
	v_cvt_pk_bf16_f32 v139, v227, v231
	ds_write2_b32 v134, v136, v137 offset0:68 offset1:84
	ds_write2_b32 v134, v138, v139 offset0:100 offset1:116
	v_fmac_f32_e32 v52, v232, v228
	v_fmac_f32_e32 v56, v220, v224
	v_fmac_f32_e32 v60, v233, v229
	v_fmac_f32_e32 v64, v221, v225
	v_fmac_f32_e32 v68, v234, v230
	v_fmac_f32_e32 v72, v222, v226
	v_fmac_f32_e32 v76, v235, v231
	v_fmac_f32_e32 v80, v223, v227
	v_fma_f32 v224, v216, v224, v52
	v_fma_f32 v228, v216, v228, v56
	v_fma_f32 v225, v217, v225, v60
	v_fma_f32 v229, v217, v229, v64
	v_fma_f32 v226, v218, v226, v68
	v_fma_f32 v230, v218, v230, v72
	v_fma_f32 v227, v219, v227, v76
	v_fma_f32 v231, v219, v231, v80
	v_cvt_pk_bf16_f32 v136, v224, v228
	v_cvt_pk_bf16_f32 v137, v225, v229
	v_cvt_pk_bf16_f32 v138, v226, v230
	v_cvt_pk_bf16_f32 v139, v227, v231
	ds_write2_b32 v134, v136, v137 offset0:136 offset1:152
	ds_write2_b32 v134, v138, v139 offset0:168 offset1:184
	v_fmac_f32_e32 v53, v232, v228
	v_fmac_f32_e32 v57, v220, v224
	v_fmac_f32_e32 v61, v233, v229
	v_fmac_f32_e32 v65, v221, v225
	v_fmac_f32_e32 v69, v234, v230
	v_fmac_f32_e32 v73, v222, v226
	v_fmac_f32_e32 v77, v235, v231
	v_fmac_f32_e32 v81, v223, v227
	v_fma_f32 v224, v216, v224, v53
	v_fma_f32 v228, v216, v228, v57
	v_fma_f32 v225, v217, v225, v61
	v_fma_f32 v229, v217, v229, v65
	v_fma_f32 v226, v218, v226, v69
	v_fma_f32 v230, v218, v230, v73
	v_fma_f32 v227, v219, v227, v77
	v_fma_f32 v231, v219, v231, v81
	v_cvt_pk_bf16_f32 v136, v224, v228
	v_cvt_pk_bf16_f32 v137, v225, v229
	v_cvt_pk_bf16_f32 v138, v226, v230
	v_cvt_pk_bf16_f32 v139, v227, v231
	ds_write2_b32 v134, v136, v137 offset0:204 offset1:220
	ds_write2_b32 v134, v138, v139 offset0:236 offset1:252
	v_add_f32_e32 v204, v204, v208
	v_add_f32_e32 v205, v205, v209
	v_add_f32_e32 v206, v206, v210
	v_add_f32_e32 v207, v207, v211
	global_store_dwordx4 v[132:133], v[204:207], off sc1
	v_lshl_add_u64 v[132:133], v[132:133], 0, s[88:89]
	s_waitcnt lgkmcnt(0)
	ds_read_b128 v[188:191], v135 offset:0
	ds_read_b128 v[192:195], v135 offset:64
	ds_read_b128 v[196:199], v135 offset:128
	ds_read_b128 v[200:203], v135 offset:192
	v_mfma_f32_16x16x16_bf16 v[50:53], v[112:113], v[114:115], v[212:215]
	v_fmac_f32_e32 v18, v232, v228
	v_fmac_f32_e32 v22, v220, v224
	v_fmac_f32_e32 v26, v233, v229
	v_fmac_f32_e32 v30, v221, v225
	v_mfma_f32_16x16x16_bf16 v[54:57], v[112:113], v[116:117], v[212:215]
	v_fmac_f32_e32 v34, v234, v230
	v_fmac_f32_e32 v38, v222, v226
	v_fmac_f32_e32 v42, v235, v231
	v_fmac_f32_e32 v46, v223, v227
	v_mfma_f32_16x16x16_bf16 v[58:61], v[112:113], v[118:119], v[212:215]
	v_fma_f32 v224, v216, v224, v18
	v_fma_f32 v228, v216, v228, v22
	v_fma_f32 v225, v217, v225, v26
	v_fma_f32 v229, v217, v229, v30
	v_mfma_f32_16x16x16_bf16 v[62:65], v[112:113], v[120:121], v[212:215]
	v_fma_f32 v226, v218, v226, v34
	v_fma_f32 v230, v218, v230, v38
	v_fma_f32 v227, v219, v227, v42
	v_fma_f32 v231, v219, v231, v46
	s_waitcnt lgkmcnt(0)
	v_mfma_f32_16x16x32_bf16 v[204:207], v[172:175], v[188:191], v[212:215]
	v_cvt_pk_bf16_f32 v136, v224, v228
	v_cvt_pk_bf16_f32 v137, v225, v229
	v_mfma_f32_16x16x32_bf16 v[208:211], v[176:179], v[192:195], v[212:215]
	v_cvt_pk_bf16_f32 v138, v226, v230
	v_cvt_pk_bf16_f32 v139, v227, v231
	ds_write2_b32 v134, v136, v137 offset0:0 offset1:16
	ds_write2_b32 v134, v138, v139 offset0:32 offset1:48
	v_mfma_f32_16x16x16_bf16 v[66:69], v[112:113], v[122:123], v[212:215]
	v_fmac_f32_e32 v19, v232, v228
	v_fmac_f32_e32 v23, v220, v224
	v_fmac_f32_e32 v27, v233, v229
	v_fmac_f32_e32 v31, v221, v225
	v_mfma_f32_16x16x16_bf16 v[70:73], v[112:113], v[124:125], v[212:215]
	v_fmac_f32_e32 v35, v234, v230
	v_fmac_f32_e32 v39, v222, v226
	v_fmac_f32_e32 v43, v235, v231
	v_fmac_f32_e32 v47, v223, v227
	v_mfma_f32_16x16x16_bf16 v[74:77], v[112:113], v[126:127], v[212:215]
	v_fma_f32 v224, v216, v224, v19
	v_fma_f32 v228, v216, v228, v23
	v_fma_f32 v225, v217, v225, v27
	v_fma_f32 v229, v217, v229, v31
	v_mfma_f32_16x16x16_bf16 v[78:81], v[112:113], v[128:129], v[212:215]
	v_fma_f32 v226, v218, v226, v35
	v_fma_f32 v230, v218, v230, v39
	v_fma_f32 v227, v219, v227, v43
	v_fma_f32 v231, v219, v231, v47
	v_mfma_f32_16x16x32_bf16 v[204:207], v[180:183], v[196:199], v[204:207]
	v_cvt_pk_bf16_f32 v136, v224, v228
	v_cvt_pk_bf16_f32 v137, v225, v229
	v_mfma_f32_16x16x32_bf16 v[208:211], v[184:187], v[200:203], v[208:211]
	v_cvt_pk_bf16_f32 v138, v226, v230
	v_cvt_pk_bf16_f32 v139, v227, v231
	ds_write2_b32 v134, v136, v137 offset0:68 offset1:84
	ds_write2_b32 v134, v138, v139 offset0:100 offset1:116
	v_fmac_f32_e32 v20, v232, v228
	v_fmac_f32_e32 v24, v220, v224
	v_fmac_f32_e32 v28, v233, v229
	v_fmac_f32_e32 v32, v221, v225
	v_fmac_f32_e32 v36, v234, v230
	v_fmac_f32_e32 v40, v222, v226
	v_fmac_f32_e32 v44, v235, v231
	v_fmac_f32_e32 v48, v223, v227
	v_fma_f32 v224, v216, v224, v20
	v_fma_f32 v228, v216, v228, v24
	v_fma_f32 v225, v217, v225, v28
	v_fma_f32 v229, v217, v229, v32
	v_fma_f32 v226, v218, v226, v36
	v_fma_f32 v230, v218, v230, v40
	v_fma_f32 v227, v219, v227, v44
	v_fma_f32 v231, v219, v231, v48
	v_cvt_pk_bf16_f32 v136, v224, v228
	v_cvt_pk_bf16_f32 v137, v225, v229
	v_cvt_pk_bf16_f32 v138, v226, v230
	v_cvt_pk_bf16_f32 v139, v227, v231
	ds_write2_b32 v134, v136, v137 offset0:136 offset1:152
	ds_write2_b32 v134, v138, v139 offset0:168 offset1:184
	v_fmac_f32_e32 v21, v232, v228
	v_fmac_f32_e32 v25, v220, v224
	v_fmac_f32_e32 v29, v233, v229
	v_fmac_f32_e32 v33, v221, v225
	v_fmac_f32_e32 v37, v234, v230
	v_fmac_f32_e32 v41, v222, v226
	v_fmac_f32_e32 v45, v235, v231
	v_fmac_f32_e32 v49, v223, v227
	v_fma_f32 v224, v216, v224, v21
	v_fma_f32 v228, v216, v228, v25
	v_fma_f32 v225, v217, v225, v29
	v_fma_f32 v229, v217, v229, v33
	v_fma_f32 v226, v218, v226, v37
	v_fma_f32 v230, v218, v230, v41
	v_fma_f32 v227, v219, v227, v45
	v_fma_f32 v231, v219, v231, v49
	v_cvt_pk_bf16_f32 v136, v224, v228
	v_cvt_pk_bf16_f32 v137, v225, v229
	v_cvt_pk_bf16_f32 v138, v226, v230
	v_cvt_pk_bf16_f32 v139, v227, v231
	ds_write2_b32 v134, v136, v137 offset0:204 offset1:220
	ds_write2_b32 v134, v138, v139 offset0:236 offset1:252
	v_add_f32_e32 v204, v204, v208
	v_add_f32_e32 v205, v205, v209
	v_add_f32_e32 v206, v206, v210
	v_add_f32_e32 v207, v207, v211
	global_store_dwordx4 v[132:133], v[204:207], off sc1
	v_lshl_add_u64 v[132:133], v[132:133], 0, s[88:89]
	s_waitcnt lgkmcnt(0)
	ds_read_b128 v[188:191], v135 offset:0
	ds_read_b128 v[192:195], v135 offset:64
	ds_read_b128 v[196:199], v135 offset:128
	ds_read_b128 v[200:203], v135 offset:192
	s_waitcnt vmcnt(14)
	v_mfma_f32_16x16x16_bf16 v[18:21], v[82:83], v[114:115], v[212:215]
	v_fmac_f32_e32 v50, v232, v228
	v_fmac_f32_e32 v54, v220, v224
	v_fmac_f32_e32 v58, v233, v229
	v_fmac_f32_e32 v62, v221, v225
	v_mfma_f32_16x16x16_bf16 v[22:25], v[82:83], v[116:117], v[212:215]
	v_fmac_f32_e32 v66, v234, v230
	v_fmac_f32_e32 v70, v222, v226
	v_fmac_f32_e32 v74, v235, v231
	v_fmac_f32_e32 v78, v223, v227
	v_mfma_f32_16x16x16_bf16 v[26:29], v[82:83], v[118:119], v[212:215]
	v_fma_f32 v224, v216, v224, v50
	v_fma_f32 v228, v216, v228, v54
	v_fma_f32 v225, v217, v225, v58
	v_fma_f32 v229, v217, v229, v62
	v_mfma_f32_16x16x16_bf16 v[30:33], v[82:83], v[120:121], v[212:215]
	v_fma_f32 v226, v218, v226, v66
	v_fma_f32 v230, v218, v230, v70
	v_fma_f32 v227, v219, v227, v74
	v_fma_f32 v231, v219, v231, v78
	s_waitcnt lgkmcnt(0)
	v_mfma_f32_16x16x32_bf16 v[204:207], v[172:175], v[188:191], v[212:215]
	v_cvt_pk_bf16_f32 v136, v224, v228
	v_cvt_pk_bf16_f32 v137, v225, v229
	v_mfma_f32_16x16x32_bf16 v[208:211], v[176:179], v[192:195], v[212:215]
	v_cvt_pk_bf16_f32 v138, v226, v230
	v_cvt_pk_bf16_f32 v139, v227, v231
	ds_write2_b32 v134, v136, v137 offset0:0 offset1:16
	ds_write2_b32 v134, v138, v139 offset0:32 offset1:48
	v_mfma_f32_16x16x16_bf16 v[34:37], v[82:83], v[122:123], v[212:215]
	v_fmac_f32_e32 v51, v232, v228
	v_fmac_f32_e32 v55, v220, v224
	v_fmac_f32_e32 v59, v233, v229
	v_fmac_f32_e32 v63, v221, v225
	v_mfma_f32_16x16x16_bf16 v[38:41], v[82:83], v[124:125], v[212:215]
	v_fmac_f32_e32 v67, v234, v230
	v_fmac_f32_e32 v71, v222, v226
	v_fmac_f32_e32 v75, v235, v231
	v_fmac_f32_e32 v79, v223, v227
	v_mfma_f32_16x16x16_bf16 v[42:45], v[82:83], v[126:127], v[212:215]
	v_fma_f32 v224, v216, v224, v51
	v_fma_f32 v228, v216, v228, v55
	v_fma_f32 v225, v217, v225, v59
	v_fma_f32 v229, v217, v229, v63
	v_mfma_f32_16x16x16_bf16 v[46:49], v[82:83], v[128:129], v[212:215]
	v_fma_f32 v226, v218, v226, v67
	v_fma_f32 v230, v218, v230, v71
	v_fma_f32 v227, v219, v227, v75
	v_fma_f32 v231, v219, v231, v79
	v_mfma_f32_16x16x32_bf16 v[204:207], v[180:183], v[196:199], v[204:207]
	v_cvt_pk_bf16_f32 v136, v224, v228
	v_cvt_pk_bf16_f32 v137, v225, v229
	v_mfma_f32_16x16x32_bf16 v[208:211], v[184:187], v[200:203], v[208:211]
	v_cvt_pk_bf16_f32 v138, v226, v230
	v_cvt_pk_bf16_f32 v139, v227, v231
	ds_write2_b32 v134, v136, v137 offset0:68 offset1:84
	ds_write2_b32 v134, v138, v139 offset0:100 offset1:116
	v_fmac_f32_e32 v52, v232, v228
	v_fmac_f32_e32 v56, v220, v224
	v_fmac_f32_e32 v60, v233, v229
	v_fmac_f32_e32 v64, v221, v225
	v_fmac_f32_e32 v68, v234, v230
	v_fmac_f32_e32 v72, v222, v226
	v_fmac_f32_e32 v76, v235, v231
	v_fmac_f32_e32 v80, v223, v227
	v_fma_f32 v224, v216, v224, v52
	v_fma_f32 v228, v216, v228, v56
	v_fma_f32 v225, v217, v225, v60
	v_fma_f32 v229, v217, v229, v64
	v_fma_f32 v226, v218, v226, v68
	v_fma_f32 v230, v218, v230, v72
	v_fma_f32 v227, v219, v227, v76
	v_fma_f32 v231, v219, v231, v80
	v_cvt_pk_bf16_f32 v136, v224, v228
	v_cvt_pk_bf16_f32 v137, v225, v229
	v_cvt_pk_bf16_f32 v138, v226, v230
	v_cvt_pk_bf16_f32 v139, v227, v231
	ds_write2_b32 v134, v136, v137 offset0:136 offset1:152
	ds_write2_b32 v134, v138, v139 offset0:168 offset1:184
	v_fmac_f32_e32 v53, v232, v228
	v_fmac_f32_e32 v57, v220, v224
	v_fmac_f32_e32 v61, v233, v229
	v_fmac_f32_e32 v65, v221, v225
	v_fmac_f32_e32 v69, v234, v230
	v_fmac_f32_e32 v73, v222, v226
	v_fmac_f32_e32 v77, v235, v231
	v_fmac_f32_e32 v81, v223, v227
	v_fma_f32 v224, v216, v224, v53
	v_fma_f32 v228, v216, v228, v57
	v_fma_f32 v225, v217, v225, v61
	v_fma_f32 v229, v217, v229, v65
	v_fma_f32 v226, v218, v226, v69
	v_fma_f32 v230, v218, v230, v73
	v_fma_f32 v227, v219, v227, v77
	v_fma_f32 v231, v219, v231, v81
	v_cvt_pk_bf16_f32 v136, v224, v228
	v_cvt_pk_bf16_f32 v137, v225, v229
	v_cvt_pk_bf16_f32 v138, v226, v230
	v_cvt_pk_bf16_f32 v139, v227, v231
	ds_write2_b32 v134, v136, v137 offset0:204 offset1:220
	ds_write2_b32 v134, v138, v139 offset0:236 offset1:252
	v_add_f32_e32 v204, v204, v208
	v_add_f32_e32 v205, v205, v209
	v_add_f32_e32 v206, v206, v210
	v_add_f32_e32 v207, v207, v211
	global_store_dwordx4 v[132:133], v[204:207], off sc1
	v_lshl_add_u64 v[132:133], v[132:133], 0, s[88:89]
	s_waitcnt lgkmcnt(0)
	ds_read_b128 v[188:191], v135 offset:0
	ds_read_b128 v[192:195], v135 offset:64
	ds_read_b128 v[196:199], v135 offset:128
	ds_read_b128 v[200:203], v135 offset:192
	s_add_i32 s15, s15, 1
	s_cmp_lt_u32 s15, 4
	s_cbranch_scc1 .Lsc_loop
	s_waitcnt lgkmcnt(0)
	v_mfma_f32_16x16x32_bf16 v[204:207], v[172:175], v[188:191], v[212:215]
	v_mfma_f32_16x16x32_bf16 v[208:211], v[176:179], v[192:195], v[212:215]
	v_mfma_f32_16x16x32_bf16 v[204:207], v[180:183], v[196:199], v[204:207]
	v_mfma_f32_16x16x32_bf16 v[208:211], v[184:187], v[200:203], v[208:211]
	s_nop 7
	s_nop 1
	v_add_f32_e32 v204, v204, v208
	v_add_f32_e32 v205, v205, v209
	v_add_f32_e32 v206, v206, v210
	v_add_f32_e32 v207, v207, v211
	global_store_dwordx4 v[132:133], v[204:207], off sc1
	s_branch .Lsc_final
